# scalar diet of the K-loop load segments: s_nop pads replaced by a moved ds_read (29 sites), M0 formed directly from the wave LDS base in modes 0 and 3 (16 SALU/iteration removed)
# speedup vs baseline: 1.0075x; 1.0075x over previous
; #define PG8_STAGE(bufoff, gbase, voff) do { _Pragma("unroll") for (int _i = 0; _i < 2; ++_i) \
;         __builtin_amdgcn_global_load_lds((const unsigned*)((const char*)(gbase) + (voff)[_i]), (LAS unsigned*)(lds + (bufoff) + ldsw + _i * 8192), 16, 0, 0); } while (0)
; #define PG8_LDA(dst, b, h) do { _Pragma("unroll") for (int m = 0; m < 4; ++m) _Pragma("unroll") for (int k = 0; k < 2; ++k) dst[m][k] = *(const LAS bf16x8*)(lds + PG8_SA(b, h) + aoff + m * 2048 + k * 1024); } while (0)
; #define PG8_LDB(dst, b, h) do { _Pragma("unroll") for (int n = 0; n < 2; ++n) _Pragma("unroll") for (int k = 0; k < 2; ++k) dst[n][k] = *(const LAS bf16x8*)(lds + PG8_SB(b, h) + boff + n * 2048 + k * 1024); } while (0)
; #define PG8_MMA(ai, bj, At, Bt) do { __builtin_amdgcn_s_setprio(1); _Pragma("unroll") for (int m = 0; m < 4; ++m) _Pragma("unroll") for (int n = 0; n < 2; ++n) _Pragma("unroll") for (int k = 0; k < 2; ++k) \
;         acc[ai][bj][m][n] = __builtin_amdgcn_mfma_f32_16x16x32_bf16(Bt[n][k], At[m][k], acc[ai][bj][m][n], 0, 0, 0); __builtin_amdgcn_s_setprio(0); } while (0)
; #define PG8_WAIT_V(n) asm volatile("s_waitcnt vmcnt(" #n ")" ::: "memory")
; #define PG8_WAIT_L(n) asm volatile("s_waitcnt lgkmcnt(" #n ")" ::: "memory")
; #define PG8_BAR __builtin_amdgcn_s_barrier()
; #define PG8_SCHED __builtin_amdgcn_sched_barrier(0)
; template <int MODE, class EpiT, class Sched>
; __device__ __forceinline__ void gemm_phase(LAS unsigned char* lds, const Gemm g, const Sched& S, const EpiT& E) {
;     ...
;             PG8_LDB(B0, 0, 0); PG8_SCHED; PG8_LDA(At, 0, 0); PG8_STAGE(PG8_SA(1, 1), a1 + hstep, voffA);
;             PG8_WAIT_L(8); PG8_BAR; PG8_WAIT_L(0); PG8_MMA(0, 0, At, B0); PG8_BAR; PG8_SCHED;
;             PG8_LDB(B1, 0, 1); PG8_STAGE(PG8_SB(0, 0), b2, voffB);
;             PG8_BAR; PG8_WAIT_L(0); PG8_MMA(0, 1, At, B1); PG8_BAR;
;             PG8_LDA(At, 0, 1); PG8_STAGE(PG8_SA(0, 0), a2, voffA);
;             PG8_BAR; PG8_WAIT_L(0); PG8_MMA(1, 0, At, B0); PG8_BAR; PG8_SCHED;
;             PG8_STAGE(PG8_SB(0, 1), b2 + hstep, voffB);
;             PG8_WAIT_V(6); PG8_BAR; PG8_MMA(1, 1, At, B1); PG8_BAR;
.LBB0_115:
	s_add_i32 s58, s52, 2
	s_add_u32 s59, s44, 0x80
	s_addc_u32 s53, s45, 0
	s_add_u32 s100, s44, s78
	s_addc_u32 s101, s45, 0
	s_add_i32 s91, 0, 0x10000
	ds_read_b128 v[70:73], v249
	ds_read_b128 v[74:77], v249 offset:1024
	ds_read_b128 v[82:85], v249 offset:2048
	ds_read_b128 v[86:89], v249 offset:3072
	s_cmp_eq_u32 s57, s52
	s_cselect_b32 s52, s4, s59
	s_cselect_b32 s53, s5, s53
	s_cselect_b32 s75, s47, vcc_hi
	s_cselect_b32 s74, s46, vcc_lo
	s_add_i32 m0, s20, 0xc000
	ds_read_b128 v[138:141], v194
	ds_read_b128 v[142:145], v194 offset:1024
	ds_read_b128 v[146:149], v194 offset:2048
	ds_read_b128 v[154:157], v194 offset:3072
	ds_read_b128 v[162:165], v194 offset:4096
	ds_read_b128 v[166:169], v194 offset:5120
	ds_read_b128 v[170:173], v194 offset:6144
	global_load_lds_dwordx4 v0, s[100:101]
	s_add_i32 m0, s20, 0xe000
	ds_read_b128 v[184:187], v194 offset:7168
	global_load_lds_dwordx4 v174, s[100:101]
	s_waitcnt lgkmcnt(8)
	s_barrier
	s_waitcnt lgkmcnt(0)
	v_mfma_f32_16x16x32_bf16 v[158:161], v[70:73], v[138:141], v[158:161]
	v_mfma_f32_16x16x32_bf16 v[150:153], v[82:85], v[138:141], v[150:153]
	v_mfma_f32_16x16x32_bf16 v[126:129], v[70:73], v[146:149], v[126:129]
	v_mfma_f32_16x16x32_bf16 v[122:125], v[82:85], v[146:149], v[122:125]
	v_mfma_f32_16x16x32_bf16 v[110:113], v[70:73], v[162:165], v[110:113]
	v_mfma_f32_16x16x32_bf16 v[106:109], v[82:85], v[162:165], v[106:109]
	v_mfma_f32_16x16x32_bf16 v[94:97], v[70:73], v[170:173], v[94:97]
	v_mfma_f32_16x16x32_bf16 v[90:93], v[82:85], v[170:173], v[90:93]
	v_mfma_f32_16x16x32_bf16 v[158:161], v[74:77], v[142:145], v[158:161]
	v_mfma_f32_16x16x32_bf16 v[150:153], v[86:89], v[142:145], v[150:153]
	v_mfma_f32_16x16x32_bf16 v[126:129], v[74:77], v[154:157], v[126:129]
	v_mfma_f32_16x16x32_bf16 v[122:125], v[86:89], v[154:157], v[122:125]
	v_mfma_f32_16x16x32_bf16 v[110:113], v[74:77], v[166:169], v[110:113]
	v_mfma_f32_16x16x32_bf16 v[106:109], v[86:89], v[166:169], v[106:109]
	v_mfma_f32_16x16x32_bf16 v[94:97], v[74:77], v[184:187], v[94:97]
	v_mfma_f32_16x16x32_bf16 v[90:93], v[86:89], v[184:187], v[90:93]
	s_barrier
	s_add_i32 s59, 0, 0x14000
	s_add_i32 s91, s91, s9
	s_add_u32 s98, s74, 0x80
	s_addc_u32 s99, s75, 0
	s_mov_b32 m0, s91
	ds_read_b128 v[188:191], v249 offset:16384
	ds_read_b128 v[196:199], v249 offset:17408
	ds_read_b128 v[220:223], v249 offset:18432
	global_load_lds_dwordx4 v0, s[74:75]
	s_add_i32 m0, s91, 0x2000
	ds_read_b128 v[224:227], v249 offset:19456
	global_load_lds_dwordx4 v174, s[74:75]
	s_barrier
	s_waitcnt lgkmcnt(0)
	v_mfma_f32_16x16x32_bf16 v[134:137], v[188:191], v[138:141], v[134:137]
	v_mfma_f32_16x16x32_bf16 v[130:133], v[220:223], v[138:141], v[130:133]
	v_mfma_f32_16x16x32_bf16 v[118:121], v[188:191], v[146:149], v[118:121]
	v_mfma_f32_16x16x32_bf16 v[114:117], v[220:223], v[146:149], v[114:117]
	v_mfma_f32_16x16x32_bf16 v[102:105], v[188:191], v[162:165], v[102:105]
	v_mfma_f32_16x16x32_bf16 v[98:101], v[220:223], v[162:165], v[98:101]
	v_mfma_f32_16x16x32_bf16 v[78:81], v[188:191], v[170:173], v[78:81]
	v_mfma_f32_16x16x32_bf16 v[66:69], v[220:223], v[170:173], v[66:69]
	v_mfma_f32_16x16x32_bf16 v[134:137], v[196:199], v[142:145], v[134:137]
	v_mfma_f32_16x16x32_bf16 v[130:133], v[224:227], v[142:145], v[130:133]
	v_mfma_f32_16x16x32_bf16 v[118:121], v[196:199], v[154:157], v[118:121]
	v_mfma_f32_16x16x32_bf16 v[114:117], v[224:227], v[154:157], v[114:117]
	v_mfma_f32_16x16x32_bf16 v[102:105], v[196:199], v[166:169], v[102:105]
	v_mfma_f32_16x16x32_bf16 v[98:101], v[224:227], v[166:169], v[98:101]
	v_mfma_f32_16x16x32_bf16 v[78:81], v[196:199], v[184:187], v[78:81]
	v_mfma_f32_16x16x32_bf16 v[66:69], v[224:227], v[184:187], v[66:69]
	s_barrier
	s_mov_b32 m0, s20
	s_add_u32 s100, s52, 0x80
	s_addc_u32 s101, s53, 0
	ds_read_b128 v[138:141], v194 offset:16384
	ds_read_b128 v[142:145], v194 offset:17408
	ds_read_b128 v[146:149], v194 offset:18432
	ds_read_b128 v[154:157], v194 offset:19456
	ds_read_b128 v[162:165], v194 offset:20480
	ds_read_b128 v[166:169], v194 offset:21504
	ds_read_b128 v[170:173], v194 offset:22528
	global_load_lds_dwordx4 v0, s[52:53]
	s_mov_b32 m0, s21
	ds_read_b128 v[184:187], v194 offset:23552
	global_load_lds_dwordx4 v174, s[52:53]
	s_barrier
	s_waitcnt lgkmcnt(0)
	v_mfma_f32_16x16x32_bf16 v[62:65], v[70:73], v[138:141], v[62:65]
	v_mfma_f32_16x16x32_bf16 v[58:61], v[82:85], v[138:141], v[58:61]
	v_mfma_f32_16x16x32_bf16 v[46:49], v[70:73], v[146:149], v[46:49]
	v_mfma_f32_16x16x32_bf16 v[42:45], v[82:85], v[146:149], v[42:45]
	v_mfma_f32_16x16x32_bf16 v[30:33], v[70:73], v[162:165], v[30:33]
	v_mfma_f32_16x16x32_bf16 v[26:29], v[82:85], v[162:165], v[26:29]
	v_mfma_f32_16x16x32_bf16 v[14:17], v[70:73], v[170:173], v[14:17]
	v_mfma_f32_16x16x32_bf16 v[10:13], v[82:85], v[170:173], v[10:13]
	v_mfma_f32_16x16x32_bf16 v[62:65], v[74:77], v[142:145], v[62:65]
	v_mfma_f32_16x16x32_bf16 v[58:61], v[86:89], v[142:145], v[58:61]
	v_mfma_f32_16x16x32_bf16 v[46:49], v[74:77], v[154:157], v[46:49]
	v_mfma_f32_16x16x32_bf16 v[42:45], v[86:89], v[154:157], v[42:45]
	v_mfma_f32_16x16x32_bf16 v[30:33], v[74:77], v[166:169], v[30:33]
	v_mfma_f32_16x16x32_bf16 v[26:29], v[86:89], v[166:169], v[26:29]
	v_mfma_f32_16x16x32_bf16 v[14:17], v[74:77], v[184:187], v[14:17]
	v_mfma_f32_16x16x32_bf16 v[10:13], v[86:89], v[184:187], v[10:13]
	s_barrier
	s_add_u32 s74, s74, s78
	s_addc_u32 s75, s75, 0
	s_add_i32 s59, s59, s9
	s_mov_b32 m0, s59
	s_nop 0
	global_load_lds_dwordx4 v0, s[74:75]
	s_add_i32 m0, s59, 0x2000
	s_nop 0
	global_load_lds_dwordx4 v174, s[74:75]
	s_waitcnt vmcnt(6)
	s_barrier
; #define PG8_STAGE(bufoff, gbase, voff) do { _Pragma("unroll") for (int _i = 0; _i < 2; ++_i) \
;         __builtin_amdgcn_global_load_lds((const unsigned*)((const char*)(gbase) + (voff)[_i]), (LAS unsigned*)(lds + (bufoff) + ldsw + _i * 8192), 16, 0, 0); } while (0)
; #define PG8_LDA(dst, b, h) do { _Pragma("unroll") for (int m = 0; m < 4; ++m) _Pragma("unroll") for (int k = 0; k < 2; ++k) dst[m][k] = *(const LAS bf16x8*)(lds + PG8_SA(b, h) + aoff + m * 2048 + k * 1024); } while (0)
; #define PG8_LDB(dst, b, h) do { _Pragma("unroll") for (int n = 0; n < 2; ++n) _Pragma("unroll") for (int k = 0; k < 2; ++k) dst[n][k] = *(const LAS bf16x8*)(lds + PG8_SB(b, h) + boff + n * 2048 + k * 1024); } while (0)
; #define PG8_MMA(ai, bj, At, Bt) do { __builtin_amdgcn_s_setprio(1); _Pragma("unroll") for (int m = 0; m < 4; ++m) _Pragma("unroll") for (int n = 0; n < 2; ++n) _Pragma("unroll") for (int k = 0; k < 2; ++k) \
;         acc[ai][bj][m][n] = __builtin_amdgcn_mfma_f32_16x16x32_bf16(Bt[n][k], At[m][k], acc[ai][bj][m][n], 0, 0, 0); __builtin_amdgcn_s_setprio(0); } while (0)
; #define PG8_WAIT_V(n) asm volatile("s_waitcnt vmcnt(" #n ")" ::: "memory")
; #define PG8_WAIT_L(n) asm volatile("s_waitcnt lgkmcnt(" #n ")" ::: "memory")
; #define PG8_BAR __builtin_amdgcn_s_barrier()
; #define PG8_SCHED __builtin_amdgcn_sched_barrier(0)
; template <int MODE, class EpiT, class Sched>
; __device__ __forceinline__ void gemm_phase(LAS unsigned char* lds, const Gemm g, const Sched& S, const EpiT& E) {
;     ...
;             PG8_WAIT_V(6); PG8_BAR; PG8_MMA(1, 1, At, B1); PG8_BAR;
;             PG8_LDB(B0, 1, 0); PG8_SCHED; PG8_LDA(At, 1, 0); PG8_STAGE(PG8_SA(0, 1), a2 + hstep, voffA);
;             PG8_WAIT_L(8); PG8_BAR; PG8_WAIT_L(0); PG8_MMA(0, 0, At, B0); PG8_BAR; PG8_SCHED;
;             PG8_LDB(B1, 1, 1); PG8_STAGE(PG8_SB(1, 0), b3, voffB);
;             PG8_BAR; PG8_WAIT_L(0); PG8_MMA(0, 1, At, B1); PG8_BAR;
	v_mfma_f32_16x16x32_bf16 v[54:57], v[188:191], v[138:141], v[54:57]
	v_mfma_f32_16x16x32_bf16 v[50:53], v[220:223], v[138:141], v[50:53]
	v_mfma_f32_16x16x32_bf16 v[38:41], v[188:191], v[146:149], v[38:41]
	v_mfma_f32_16x16x32_bf16 v[34:37], v[220:223], v[146:149], v[34:37]
	v_mfma_f32_16x16x32_bf16 v[22:25], v[188:191], v[162:165], v[22:25]
	v_mfma_f32_16x16x32_bf16 v[18:21], v[220:223], v[162:165], v[18:21]
	v_mfma_f32_16x16x32_bf16 v[6:9], v[188:191], v[170:173], v[6:9]
	v_mfma_f32_16x16x32_bf16 v[2:5], v[220:223], v[170:173], v[2:5]
	v_mfma_f32_16x16x32_bf16 v[54:57], v[196:199], v[142:145], v[54:57]
	v_mfma_f32_16x16x32_bf16 v[50:53], v[224:227], v[142:145], v[50:53]
	v_mfma_f32_16x16x32_bf16 v[38:41], v[196:199], v[154:157], v[38:41]
	v_mfma_f32_16x16x32_bf16 v[34:37], v[224:227], v[154:157], v[34:37]
	v_mfma_f32_16x16x32_bf16 v[22:25], v[196:199], v[166:169], v[22:25]
	v_mfma_f32_16x16x32_bf16 v[18:21], v[224:227], v[166:169], v[18:21]
	v_mfma_f32_16x16x32_bf16 v[6:9], v[196:199], v[184:187], v[6:9]
	v_mfma_f32_16x16x32_bf16 v[2:5], v[224:227], v[184:187], v[2:5]
	s_barrier
	s_add_i32 s59, 0, 0x18000
	ds_read_b128 v[70:73], v249 offset:32768
	ds_read_b128 v[74:77], v249 offset:33792
	ds_read_b128 v[82:85], v249 offset:34816
	ds_read_b128 v[86:89], v249 offset:35840
	s_add_u32 s52, s52, s78
	s_addc_u32 s53, s53, 0
	s_mov_b32 m0, s22
	ds_read_b128 v[138:141], v194 offset:32768
	ds_read_b128 v[142:145], v194 offset:33792
	ds_read_b128 v[146:149], v194 offset:34816
	ds_read_b128 v[154:157], v194 offset:35840
	ds_read_b128 v[162:165], v194 offset:36864
	ds_read_b128 v[166:169], v194 offset:37888
	ds_read_b128 v[170:173], v194 offset:38912
	global_load_lds_dwordx4 v0, s[52:53]
	s_mov_b32 m0, s23
	ds_read_b128 v[184:187], v194 offset:39936
	global_load_lds_dwordx4 v174, s[52:53]
	s_waitcnt lgkmcnt(8)
	s_barrier
	s_waitcnt lgkmcnt(0)
	v_mfma_f32_16x16x32_bf16 v[158:161], v[70:73], v[138:141], v[158:161]
	v_mfma_f32_16x16x32_bf16 v[150:153], v[82:85], v[138:141], v[150:153]
	v_mfma_f32_16x16x32_bf16 v[126:129], v[70:73], v[146:149], v[126:129]
	v_mfma_f32_16x16x32_bf16 v[122:125], v[82:85], v[146:149], v[122:125]
	v_mfma_f32_16x16x32_bf16 v[110:113], v[70:73], v[162:165], v[110:113]
	v_mfma_f32_16x16x32_bf16 v[106:109], v[82:85], v[162:165], v[106:109]
	v_mfma_f32_16x16x32_bf16 v[94:97], v[70:73], v[170:173], v[94:97]
	v_mfma_f32_16x16x32_bf16 v[90:93], v[82:85], v[170:173], v[90:93]
	v_mfma_f32_16x16x32_bf16 v[158:161], v[74:77], v[142:145], v[158:161]
	v_mfma_f32_16x16x32_bf16 v[150:153], v[86:89], v[142:145], v[150:153]
	v_mfma_f32_16x16x32_bf16 v[126:129], v[74:77], v[154:157], v[126:129]
	v_mfma_f32_16x16x32_bf16 v[122:125], v[86:89], v[154:157], v[122:125]
	v_mfma_f32_16x16x32_bf16 v[110:113], v[74:77], v[166:169], v[110:113]
	v_mfma_f32_16x16x32_bf16 v[106:109], v[86:89], v[166:169], v[106:109]
	v_mfma_f32_16x16x32_bf16 v[94:97], v[74:77], v[184:187], v[94:97]
	v_mfma_f32_16x16x32_bf16 v[90:93], v[86:89], v[184:187], v[90:93]
	s_barrier
	s_add_i32 s52, 0, 0x1c000
	s_add_i32 s53, s59, s9
	s_mov_b32 m0, s53
	ds_read_b128 v[188:191], v249 offset:49152
	ds_read_b128 v[196:199], v249 offset:50176
	ds_read_b128 v[220:223], v249 offset:51200
	global_load_lds_dwordx4 v0, s[98:99]
	s_add_i32 m0, s53, 0x2000
	ds_read_b128 v[224:227], v249 offset:52224
	global_load_lds_dwordx4 v174, s[98:99]
	s_barrier
	s_waitcnt lgkmcnt(0)
	v_mfma_f32_16x16x32_bf16 v[134:137], v[188:191], v[138:141], v[134:137]
	v_mfma_f32_16x16x32_bf16 v[130:133], v[220:223], v[138:141], v[130:133]
	v_mfma_f32_16x16x32_bf16 v[118:121], v[188:191], v[146:149], v[118:121]
	v_mfma_f32_16x16x32_bf16 v[114:117], v[220:223], v[146:149], v[114:117]
	v_mfma_f32_16x16x32_bf16 v[102:105], v[188:191], v[162:165], v[102:105]
	v_mfma_f32_16x16x32_bf16 v[98:101], v[220:223], v[162:165], v[98:101]
	v_mfma_f32_16x16x32_bf16 v[78:81], v[188:191], v[170:173], v[78:81]
	v_mfma_f32_16x16x32_bf16 v[66:69], v[220:223], v[170:173], v[66:69]
	v_mfma_f32_16x16x32_bf16 v[134:137], v[196:199], v[142:145], v[134:137]
	v_mfma_f32_16x16x32_bf16 v[130:133], v[224:227], v[142:145], v[130:133]
	v_mfma_f32_16x16x32_bf16 v[118:121], v[196:199], v[154:157], v[118:121]
	v_mfma_f32_16x16x32_bf16 v[114:117], v[224:227], v[154:157], v[114:117]
	v_mfma_f32_16x16x32_bf16 v[102:105], v[196:199], v[166:169], v[102:105]
	v_mfma_f32_16x16x32_bf16 v[98:101], v[224:227], v[166:169], v[98:101]
	v_mfma_f32_16x16x32_bf16 v[78:81], v[196:199], v[184:187], v[78:81]
	v_mfma_f32_16x16x32_bf16 v[66:69], v[224:227], v[184:187], v[66:69]
	s_barrier
; #define PG8_STAGE(bufoff, gbase, voff) do { _Pragma("unroll") for (int _i = 0; _i < 2; ++_i) \
;         __builtin_amdgcn_global_load_lds((const unsigned*)((const char*)(gbase) + (voff)[_i]), (LAS unsigned*)(lds + (bufoff) + ldsw + _i * 8192), 16, 0, 0); } while (0)
; #define PG8_LDA(dst, b, h) do { _Pragma("unroll") for (int m = 0; m < 4; ++m) _Pragma("unroll") for (int k = 0; k < 2; ++k) dst[m][k] = *(const LAS bf16x8*)(lds + PG8_SA(b, h) + aoff + m * 2048 + k * 1024); } while (0)
; #define PG8_MMA(ai, bj, At, Bt) do { __builtin_amdgcn_s_setprio(1); _Pragma("unroll") for (int m = 0; m < 4; ++m) _Pragma("unroll") for (int n = 0; n < 2; ++n) _Pragma("unroll") for (int k = 0; k < 2; ++k) \
;         acc[ai][bj][m][n] = __builtin_amdgcn_mfma_f32_16x16x32_bf16(Bt[n][k], At[m][k], acc[ai][bj][m][n], 0, 0, 0); __builtin_amdgcn_s_setprio(0); } while (0)
; #define PG8_WAIT_V(n) asm volatile("s_waitcnt vmcnt(" #n ")" ::: "memory")
; #define PG8_WAIT_L(n) asm volatile("s_waitcnt lgkmcnt(" #n ")" ::: "memory")
; #define PG8_BAR __builtin_amdgcn_s_barrier()
; #define PG8_SCHED __builtin_amdgcn_sched_barrier(0)
;     template <int mode> __device__ __forceinline__ void run(const f32x4 (&acc)[2][2][4][2], const Unit& u, int wr, int wc, int fr, int fq, const LAS float* sc) const {
;     ...
;             f32x4 bvv[4];
; #pragma unroll
;             for (int q = 0; q < 4; ++q) bvv[q] = (mode != 4 && bias) ? *(const f32x4*)(bias + col0 + (q >> 1) * HALF + (q & 1) * 4) : (f32x4){0.f, 0.f, 0.f, 0.f};
; template <int MODE, class EpiT, class Sched>
; __device__ __forceinline__ void gemm_phase(LAS unsigned char* lds, const Gemm g, const Sched& S, const EpiT& E) {
;     ...
;             PG8_LDA(At, 1, 1); PG8_STAGE(PG8_SA(1, 0), a3, voffA);
;             PG8_BAR; PG8_WAIT_L(0); PG8_MMA(1, 0, At, B0); PG8_BAR; PG8_SCHED;
;             PG8_STAGE(PG8_SB(1, 1), b3 + hstep, voffB);
;             PG8_WAIT_V(6); PG8_BAR; PG8_MMA(1, 1, At, B1); PG8_BAR;
;         }
	s_mov_b32 m0, s51
	ds_read_b128 v[138:141], v194 offset:49152
	ds_read_b128 v[142:145], v194 offset:50176
	ds_read_b128 v[146:149], v194 offset:51200
	ds_read_b128 v[154:157], v194 offset:52224
	ds_read_b128 v[162:165], v194 offset:53248
	ds_read_b128 v[166:169], v194 offset:54272
	ds_read_b128 v[170:173], v194 offset:55296
	global_load_lds_dwordx4 v0, s[100:101]
	s_mov_b32 m0, s56
	ds_read_b128 v[184:187], v194 offset:56320
	global_load_lds_dwordx4 v174, s[100:101]
	s_barrier
	s_waitcnt lgkmcnt(0)
	v_mfma_f32_16x16x32_bf16 v[62:65], v[70:73], v[138:141], v[62:65]
	v_mfma_f32_16x16x32_bf16 v[58:61], v[82:85], v[138:141], v[58:61]
	v_mfma_f32_16x16x32_bf16 v[46:49], v[70:73], v[146:149], v[46:49]
	v_mfma_f32_16x16x32_bf16 v[42:45], v[82:85], v[146:149], v[42:45]
	v_mfma_f32_16x16x32_bf16 v[30:33], v[70:73], v[162:165], v[30:33]
	v_mfma_f32_16x16x32_bf16 v[26:29], v[82:85], v[162:165], v[26:29]
	v_mfma_f32_16x16x32_bf16 v[14:17], v[70:73], v[170:173], v[14:17]
	v_mfma_f32_16x16x32_bf16 v[10:13], v[82:85], v[170:173], v[10:13]
	v_mfma_f32_16x16x32_bf16 v[62:65], v[74:77], v[142:145], v[62:65]
	v_mfma_f32_16x16x32_bf16 v[58:61], v[86:89], v[142:145], v[58:61]
	v_mfma_f32_16x16x32_bf16 v[46:49], v[74:77], v[154:157], v[46:49]
	v_mfma_f32_16x16x32_bf16 v[42:45], v[86:89], v[154:157], v[42:45]
	v_mfma_f32_16x16x32_bf16 v[30:33], v[74:77], v[166:169], v[30:33]
	v_mfma_f32_16x16x32_bf16 v[26:29], v[86:89], v[166:169], v[26:29]
	v_mfma_f32_16x16x32_bf16 v[14:17], v[74:77], v[184:187], v[14:17]
	v_mfma_f32_16x16x32_bf16 v[10:13], v[86:89], v[184:187], v[10:13]
	s_barrier
	s_add_i32 s52, s52, s9
	s_add_u32 s98, s98, s78
	s_addc_u32 s99, s99, 0
	s_mov_b32 m0, s52
	s_nop 0
	global_load_lds_dwordx4 v0, s[98:99]
	s_add_i32 m0, s52, 0x2000
	s_nop 0
	global_load_lds_dwordx4 v174, s[98:99]
	s_waitcnt vmcnt(6)
	s_barrier
	v_mfma_f32_16x16x32_bf16 v[54:57], v[188:191], v[138:141], v[54:57]
	v_mfma_f32_16x16x32_bf16 v[50:53], v[220:223], v[138:141], v[50:53]
	v_mfma_f32_16x16x32_bf16 v[38:41], v[188:191], v[146:149], v[38:41]
	v_mfma_f32_16x16x32_bf16 v[34:37], v[220:223], v[146:149], v[34:37]
	v_mfma_f32_16x16x32_bf16 v[22:25], v[188:191], v[162:165], v[22:25]
	v_mfma_f32_16x16x32_bf16 v[18:21], v[220:223], v[162:165], v[18:21]
	v_mfma_f32_16x16x32_bf16 v[6:9], v[188:191], v[170:173], v[6:9]
	v_mfma_f32_16x16x32_bf16 v[2:5], v[220:223], v[170:173], v[2:5]
	v_mfma_f32_16x16x32_bf16 v[54:57], v[196:199], v[142:145], v[54:57]
	v_mfma_f32_16x16x32_bf16 v[50:53], v[224:227], v[142:145], v[50:53]
	v_mfma_f32_16x16x32_bf16 v[38:41], v[196:199], v[154:157], v[38:41]
	v_mfma_f32_16x16x32_bf16 v[34:37], v[224:227], v[154:157], v[34:37]
	v_mfma_f32_16x16x32_bf16 v[22:25], v[196:199], v[166:169], v[22:25]
	v_mfma_f32_16x16x32_bf16 v[18:21], v[224:227], v[166:169], v[18:21]
	v_mfma_f32_16x16x32_bf16 v[6:9], v[196:199], v[184:187], v[6:9]
	v_mfma_f32_16x16x32_bf16 v[2:5], v[224:227], v[184:187], v[2:5]
	s_barrier
	s_add_u32 s44, s44, 0x100
	s_addc_u32 s45, s45, 0
	s_add_u32 vcc_lo, vcc_lo, 0x100
	s_addc_u32 vcc_hi, vcc_hi, 0
	s_cmp_ge_u32 s58, s50
	s_mov_b32 s52, s58
	s_cbranch_scc0 .LBB0_115
	v_lshl_or_b32 v184, s24, 8, v193
	v_ashrrev_i32_e32 v185, 31, v184
	v_mov_b32_e32 v74, 0
	v_cndmask_b32_e64 v70, 0, 1, s[68:69]
	v_lshl_add_u64 v[138:139], v[184:185], 2, s[12:13]
	v_cmp_ne_u32_e64 s[44:45], 1, v70
	s_andn2_b64 vcc, exec, s[68:69]
	v_mov_b32_e32 v86, 0
	v_mov_b32_e32 v87, v74
	v_mov_b32_e32 v186, 0
	v_mov_b32_e32 v187, v74
	s_cbranch_vccnz .LBB0_118
	global_load_dwordx4 v[86:89], v[138:139], off
	s_waitcnt vmcnt(0)
	v_mov_b32_e32 v186, v88
	v_mov_b32_e32 v187, v89

; #define PG8_STAGE(bufoff, gbase, voff) do { _Pragma("unroll") for (int _i = 0; _i < 2; ++_i) \
;         __builtin_amdgcn_global_load_lds((const unsigned*)((const char*)(gbase) + (voff)[_i]), (LAS unsigned*)(lds + (bufoff) + ldsw + _i * 8192), 16, 0, 0); } while (0)
; #define PG8_LDA(dst, b, h) do { _Pragma("unroll") for (int m = 0; m < 4; ++m) _Pragma("unroll") for (int k = 0; k < 2; ++k) dst[m][k] = *(const LAS bf16x8*)(lds + PG8_SA(b, h) + aoff + m * 2048 + k * 1024); } while (0)
; #define PG8_LDB(dst, b, h) do { _Pragma("unroll") for (int n = 0; n < 2; ++n) _Pragma("unroll") for (int k = 0; k < 2; ++k) dst[n][k] = *(const LAS bf16x8*)(lds + PG8_SB(b, h) + boff + n * 2048 + k * 1024); } while (0)
; #define PG8_MMA(ai, bj, At, Bt) do { __builtin_amdgcn_s_setprio(1); _Pragma("unroll") for (int m = 0; m < 4; ++m) _Pragma("unroll") for (int n = 0; n < 2; ++n) _Pragma("unroll") for (int k = 0; k < 2; ++k) \
;         acc[ai][bj][m][n] = __builtin_amdgcn_mfma_f32_16x16x32_bf16(Bt[n][k], At[m][k], acc[ai][bj][m][n], 0, 0, 0); __builtin_amdgcn_s_setprio(0); } while (0)
; #define PG8_WAIT_V(n) asm volatile("s_waitcnt vmcnt(" #n ")" ::: "memory")
; #define PG8_WAIT_L(n) asm volatile("s_waitcnt lgkmcnt(" #n ")" ::: "memory")
; #define PG8_BAR __builtin_amdgcn_s_barrier()
; #define PG8_SCHED __builtin_amdgcn_sched_barrier(0)
; template <int MODE, class EpiT, class Sched>
; __device__ __forceinline__ void gemm_phase(LAS unsigned char* lds, const Gemm g, const Sched& S, const EpiT& E) {
;     ...
;             PG8_LDB(B0, 0, 0); PG8_SCHED; PG8_LDA(At, 0, 0); PG8_STAGE(PG8_SA(1, 1), a1 + hstep, voffA);
;             PG8_WAIT_L(8); PG8_BAR; PG8_WAIT_L(0); PG8_MMA(0, 0, At, B0); PG8_BAR; PG8_SCHED;
;             PG8_LDB(B1, 0, 1); PG8_STAGE(PG8_SB(0, 0), b2, voffB);
;             PG8_BAR; PG8_WAIT_L(0); PG8_MMA(0, 1, At, B1); PG8_BAR;
;             PG8_LDA(At, 0, 1); PG8_STAGE(PG8_SA(0, 0), a2, voffA);
;             PG8_BAR; PG8_WAIT_L(0); PG8_MMA(1, 0, At, B0); PG8_BAR; PG8_SCHED;
;             PG8_STAGE(PG8_SB(0, 1), b2 + hstep, voffB);
;             PG8_WAIT_V(6); PG8_BAR; PG8_MMA(1, 1, At, B1); PG8_BAR;
.LBB0_159:
	s_add_i32 s89, s30, 2
	s_add_u32 s44, s4, 0x80
	s_addc_u32 s45, s5, 0
	s_add_u32 s100, s4, s38
	s_addc_u32 s101, s5, 0
	s_add_i32 s58, 0, 0x10000
	ds_read_b128 v[130:133], v251
	ds_read_b128 v[134:137], v251 offset:1024
	ds_read_b128 v[138:141], v251 offset:2048
	ds_read_b128 v[142:145], v251 offset:3072
	s_cmp_eq_u32 s61, s30
	s_cselect_b32 s45, s79, s45
	s_cselect_b32 s44, s78, s44
	s_cselect_b32 s53, s47, s24
	s_cselect_b32 s52, s46, s23
	s_add_i32 m0, s69, 0xc000
	ds_read_b128 v[146:149], v223
	ds_read_b128 v[150:153], v223 offset:1024
	ds_read_b128 v[154:157], v223 offset:2048
	ds_read_b128 v[158:161], v223 offset:3072
	ds_read_b128 v[162:165], v223 offset:4096
	ds_read_b128 v[166:169], v223 offset:5120
	ds_read_b128 v[170:173], v223 offset:6144
	global_load_lds_dwordx4 v0, s[100:101]
	s_add_i32 m0, s69, 0xe000
	ds_read_b128 v[174:177], v223 offset:7168
	global_load_lds_dwordx4 v182, s[100:101]
	s_waitcnt lgkmcnt(8)
	s_barrier
	s_waitcnt lgkmcnt(0)
	v_mfma_f32_16x16x32_bf16 v[126:129], v[130:133], v[146:149], v[126:129]
	v_mfma_f32_16x16x32_bf16 v[122:125], v[138:141], v[146:149], v[122:125]
	v_mfma_f32_16x16x32_bf16 v[110:113], v[130:133], v[154:157], v[110:113]
	v_mfma_f32_16x16x32_bf16 v[106:109], v[138:141], v[154:157], v[106:109]
	v_mfma_f32_16x16x32_bf16 v[94:97], v[130:133], v[162:165], v[94:97]
	v_mfma_f32_16x16x32_bf16 v[90:93], v[138:141], v[162:165], v[90:93]
	v_mfma_f32_16x16x32_bf16 v[78:81], v[130:133], v[170:173], v[78:81]
	v_mfma_f32_16x16x32_bf16 v[74:77], v[138:141], v[170:173], v[74:77]
	v_mfma_f32_16x16x32_bf16 v[126:129], v[134:137], v[150:153], v[126:129]
	v_mfma_f32_16x16x32_bf16 v[122:125], v[142:145], v[150:153], v[122:125]
	v_mfma_f32_16x16x32_bf16 v[110:113], v[134:137], v[158:161], v[110:113]
	v_mfma_f32_16x16x32_bf16 v[106:109], v[142:145], v[158:161], v[106:109]
	v_mfma_f32_16x16x32_bf16 v[94:97], v[134:137], v[166:169], v[94:97]
	v_mfma_f32_16x16x32_bf16 v[90:93], v[142:145], v[166:169], v[90:93]
	v_mfma_f32_16x16x32_bf16 v[78:81], v[134:137], v[174:177], v[78:81]
	v_mfma_f32_16x16x32_bf16 v[74:77], v[142:145], v[174:177], v[74:77]
	s_barrier
	s_add_i32 s30, 0, 0x14000
	s_add_i32 s58, s58, s68
	s_add_u32 s98, s52, 0x80
	s_addc_u32 s99, s53, 0
	s_mov_b32 m0, s58
	ds_read_b128 v[188:191], v251 offset:16384
	ds_read_b128 v[192:195], v251 offset:17408
	ds_read_b128 v[196:199], v251 offset:18432
	global_load_lds_dwordx4 v0, s[52:53]
	s_add_i32 m0, s58, 0x2000
	ds_read_b128 v[224:227], v251 offset:19456
	global_load_lds_dwordx4 v182, s[52:53]
	s_barrier
	s_waitcnt lgkmcnt(0)
	v_mfma_f32_16x16x32_bf16 v[118:121], v[188:191], v[146:149], v[118:121]
	v_mfma_f32_16x16x32_bf16 v[114:117], v[196:199], v[146:149], v[114:117]
	v_mfma_f32_16x16x32_bf16 v[102:105], v[188:191], v[154:157], v[102:105]
	v_mfma_f32_16x16x32_bf16 v[98:101], v[196:199], v[154:157], v[98:101]
	v_mfma_f32_16x16x32_bf16 v[86:89], v[188:191], v[162:165], v[86:89]
	v_mfma_f32_16x16x32_bf16 v[82:85], v[196:199], v[162:165], v[82:85]
	v_mfma_f32_16x16x32_bf16 v[70:73], v[188:191], v[170:173], v[70:73]
	v_mfma_f32_16x16x32_bf16 v[66:69], v[196:199], v[170:173], v[66:69]
	v_mfma_f32_16x16x32_bf16 v[118:121], v[192:195], v[150:153], v[118:121]
	v_mfma_f32_16x16x32_bf16 v[114:117], v[224:227], v[150:153], v[114:117]
	v_mfma_f32_16x16x32_bf16 v[102:105], v[192:195], v[158:161], v[102:105]
	v_mfma_f32_16x16x32_bf16 v[98:101], v[224:227], v[158:161], v[98:101]
	v_mfma_f32_16x16x32_bf16 v[86:89], v[192:195], v[166:169], v[86:89]
	v_mfma_f32_16x16x32_bf16 v[82:85], v[224:227], v[166:169], v[82:85]
	v_mfma_f32_16x16x32_bf16 v[70:73], v[192:195], v[174:177], v[70:73]
	v_mfma_f32_16x16x32_bf16 v[66:69], v[224:227], v[174:177], v[66:69]
	s_barrier
	s_mov_b32 m0, s69
	s_add_u32 s100, s44, 0x80
	s_addc_u32 s101, s45, 0
	ds_read_b128 v[146:149], v223 offset:16384
	ds_read_b128 v[150:153], v223 offset:17408
	ds_read_b128 v[154:157], v223 offset:18432
	ds_read_b128 v[158:161], v223 offset:19456
	ds_read_b128 v[162:165], v223 offset:20480
	ds_read_b128 v[166:169], v223 offset:21504
	ds_read_b128 v[170:173], v223 offset:22528
	global_load_lds_dwordx4 v0, s[44:45]
	s_mov_b32 m0, s74
	ds_read_b128 v[174:177], v223 offset:23552
	global_load_lds_dwordx4 v182, s[44:45]
	s_barrier
	s_waitcnt lgkmcnt(0)
	v_mfma_f32_16x16x32_bf16 v[62:65], v[130:133], v[146:149], v[62:65]
	v_mfma_f32_16x16x32_bf16 v[58:61], v[138:141], v[146:149], v[58:61]
	v_mfma_f32_16x16x32_bf16 v[46:49], v[130:133], v[154:157], v[46:49]
	v_mfma_f32_16x16x32_bf16 v[42:45], v[138:141], v[154:157], v[42:45]
	v_mfma_f32_16x16x32_bf16 v[30:33], v[130:133], v[162:165], v[30:33]
	v_mfma_f32_16x16x32_bf16 v[26:29], v[138:141], v[162:165], v[26:29]
	v_mfma_f32_16x16x32_bf16 v[14:17], v[130:133], v[170:173], v[14:17]
	v_mfma_f32_16x16x32_bf16 v[10:13], v[138:141], v[170:173], v[10:13]
	v_mfma_f32_16x16x32_bf16 v[62:65], v[134:137], v[150:153], v[62:65]
	v_mfma_f32_16x16x32_bf16 v[58:61], v[142:145], v[150:153], v[58:61]
	v_mfma_f32_16x16x32_bf16 v[46:49], v[134:137], v[158:161], v[46:49]
	v_mfma_f32_16x16x32_bf16 v[42:45], v[142:145], v[158:161], v[42:45]
	v_mfma_f32_16x16x32_bf16 v[30:33], v[134:137], v[166:169], v[30:33]
	v_mfma_f32_16x16x32_bf16 v[26:29], v[142:145], v[166:169], v[26:29]
	v_mfma_f32_16x16x32_bf16 v[14:17], v[134:137], v[174:177], v[14:17]
	v_mfma_f32_16x16x32_bf16 v[10:13], v[142:145], v[174:177], v[10:13]
	s_barrier
	s_add_u32 s52, s52, s38
	s_addc_u32 s53, s53, 0
	s_add_i32 s30, s30, s68
	s_mov_b32 m0, s30
	s_nop 0
	global_load_lds_dwordx4 v0, s[52:53]
	s_add_i32 m0, s30, 0x2000
	s_nop 0
	global_load_lds_dwordx4 v182, s[52:53]
	s_waitcnt vmcnt(6)
	s_barrier
; #define PG8_STAGE(bufoff, gbase, voff) do { _Pragma("unroll") for (int _i = 0; _i < 2; ++_i) \
;         __builtin_amdgcn_global_load_lds((const unsigned*)((const char*)(gbase) + (voff)[_i]), (LAS unsigned*)(lds + (bufoff) + ldsw + _i * 8192), 16, 0, 0); } while (0)
; #define PG8_LDA(dst, b, h) do { _Pragma("unroll") for (int m = 0; m < 4; ++m) _Pragma("unroll") for (int k = 0; k < 2; ++k) dst[m][k] = *(const LAS bf16x8*)(lds + PG8_SA(b, h) + aoff + m * 2048 + k * 1024); } while (0)
; #define PG8_LDB(dst, b, h) do { _Pragma("unroll") for (int n = 0; n < 2; ++n) _Pragma("unroll") for (int k = 0; k < 2; ++k) dst[n][k] = *(const LAS bf16x8*)(lds + PG8_SB(b, h) + boff + n * 2048 + k * 1024); } while (0)
; #define PG8_MMA(ai, bj, At, Bt) do { __builtin_amdgcn_s_setprio(1); _Pragma("unroll") for (int m = 0; m < 4; ++m) _Pragma("unroll") for (int n = 0; n < 2; ++n) _Pragma("unroll") for (int k = 0; k < 2; ++k) \
;         acc[ai][bj][m][n] = __builtin_amdgcn_mfma_f32_16x16x32_bf16(Bt[n][k], At[m][k], acc[ai][bj][m][n], 0, 0, 0); __builtin_amdgcn_s_setprio(0); } while (0)
; #define PG8_WAIT_V(n) asm volatile("s_waitcnt vmcnt(" #n ")" ::: "memory")
; #define PG8_WAIT_L(n) asm volatile("s_waitcnt lgkmcnt(" #n ")" ::: "memory")
; #define PG8_BAR __builtin_amdgcn_s_barrier()
; #define PG8_SCHED __builtin_amdgcn_sched_barrier(0)
; template <int MODE, class EpiT, class Sched>
; __device__ __forceinline__ void gemm_phase(LAS unsigned char* lds, const Gemm g, const Sched& S, const EpiT& E) {
;     ...
;             PG8_WAIT_V(6); PG8_BAR; PG8_MMA(1, 1, At, B1); PG8_BAR;
;             PG8_LDB(B0, 1, 0); PG8_SCHED; PG8_LDA(At, 1, 0); PG8_STAGE(PG8_SA(0, 1), a2 + hstep, voffA);
;             PG8_WAIT_L(8); PG8_BAR; PG8_WAIT_L(0); PG8_MMA(0, 0, At, B0); PG8_BAR; PG8_SCHED;
;             PG8_LDB(B1, 1, 1); PG8_STAGE(PG8_SB(1, 0), b3, voffB);
;             PG8_BAR; PG8_WAIT_L(0); PG8_MMA(0, 1, At, B1); PG8_BAR;
;             PG8_LDA(At, 1, 1); PG8_STAGE(PG8_SA(1, 0), a3, voffA);
;             PG8_BAR; PG8_WAIT_L(0); PG8_MMA(1, 0, At, B0); PG8_BAR; PG8_SCHED;
	v_mfma_f32_16x16x32_bf16 v[54:57], v[188:191], v[146:149], v[54:57]
	v_mfma_f32_16x16x32_bf16 v[50:53], v[196:199], v[146:149], v[50:53]
	v_mfma_f32_16x16x32_bf16 v[38:41], v[188:191], v[154:157], v[38:41]
	v_mfma_f32_16x16x32_bf16 v[34:37], v[196:199], v[154:157], v[34:37]
	v_mfma_f32_16x16x32_bf16 v[22:25], v[188:191], v[162:165], v[22:25]
	v_mfma_f32_16x16x32_bf16 v[18:21], v[196:199], v[162:165], v[18:21]
	v_mfma_f32_16x16x32_bf16 v[6:9], v[188:191], v[170:173], v[6:9]
	v_mfma_f32_16x16x32_bf16 v[2:5], v[196:199], v[170:173], v[2:5]
	v_mfma_f32_16x16x32_bf16 v[54:57], v[192:195], v[150:153], v[54:57]
	v_mfma_f32_16x16x32_bf16 v[50:53], v[224:227], v[150:153], v[50:53]
	v_mfma_f32_16x16x32_bf16 v[38:41], v[192:195], v[158:161], v[38:41]
	v_mfma_f32_16x16x32_bf16 v[34:37], v[224:227], v[158:161], v[34:37]
	v_mfma_f32_16x16x32_bf16 v[22:25], v[192:195], v[166:169], v[22:25]
	v_mfma_f32_16x16x32_bf16 v[18:21], v[224:227], v[166:169], v[18:21]
	v_mfma_f32_16x16x32_bf16 v[6:9], v[192:195], v[174:177], v[6:9]
	v_mfma_f32_16x16x32_bf16 v[2:5], v[224:227], v[174:177], v[2:5]
	s_barrier
	s_add_i32 s30, 0, 0x18000
	ds_read_b128 v[130:133], v251 offset:32768
	ds_read_b128 v[134:137], v251 offset:33792
	ds_read_b128 v[138:141], v251 offset:34816
	ds_read_b128 v[142:145], v251 offset:35840
	s_add_u32 s44, s44, s38
	s_addc_u32 s45, s45, 0
	s_mov_b32 m0, s75
	ds_read_b128 v[146:149], v223 offset:32768
	ds_read_b128 v[150:153], v223 offset:33792
	ds_read_b128 v[154:157], v223 offset:34816
	ds_read_b128 v[158:161], v223 offset:35840
	ds_read_b128 v[162:165], v223 offset:36864
	ds_read_b128 v[166:169], v223 offset:37888
	ds_read_b128 v[170:173], v223 offset:38912
	global_load_lds_dwordx4 v0, s[44:45]
	s_mov_b32 m0, s9
	ds_read_b128 v[174:177], v223 offset:39936
	global_load_lds_dwordx4 v182, s[44:45]
	s_waitcnt lgkmcnt(8)
	s_barrier
	s_waitcnt lgkmcnt(0)
	v_mfma_f32_16x16x32_bf16 v[126:129], v[130:133], v[146:149], v[126:129]
	v_mfma_f32_16x16x32_bf16 v[122:125], v[138:141], v[146:149], v[122:125]
	v_mfma_f32_16x16x32_bf16 v[110:113], v[130:133], v[154:157], v[110:113]
	v_mfma_f32_16x16x32_bf16 v[106:109], v[138:141], v[154:157], v[106:109]
	v_mfma_f32_16x16x32_bf16 v[94:97], v[130:133], v[162:165], v[94:97]
	v_mfma_f32_16x16x32_bf16 v[90:93], v[138:141], v[162:165], v[90:93]
	v_mfma_f32_16x16x32_bf16 v[78:81], v[130:133], v[170:173], v[78:81]
	v_mfma_f32_16x16x32_bf16 v[74:77], v[138:141], v[170:173], v[74:77]
	v_mfma_f32_16x16x32_bf16 v[126:129], v[134:137], v[150:153], v[126:129]
	v_mfma_f32_16x16x32_bf16 v[122:125], v[142:145], v[150:153], v[122:125]
	v_mfma_f32_16x16x32_bf16 v[110:113], v[134:137], v[158:161], v[110:113]
	v_mfma_f32_16x16x32_bf16 v[106:109], v[142:145], v[158:161], v[106:109]
	v_mfma_f32_16x16x32_bf16 v[94:97], v[134:137], v[166:169], v[94:97]
	v_mfma_f32_16x16x32_bf16 v[90:93], v[142:145], v[166:169], v[90:93]
	v_mfma_f32_16x16x32_bf16 v[78:81], v[134:137], v[174:177], v[78:81]
	v_mfma_f32_16x16x32_bf16 v[74:77], v[142:145], v[174:177], v[74:77]
	s_barrier
	s_add_i32 s44, 0, 0x1c000
	s_add_i32 s30, s30, s68
	s_mov_b32 m0, s30
	ds_read_b128 v[188:191], v251 offset:49152
	ds_read_b128 v[192:195], v251 offset:50176
	ds_read_b128 v[196:199], v251 offset:51200
	global_load_lds_dwordx4 v0, s[98:99]
	s_add_i32 m0, s30, 0x2000
	ds_read_b128 v[224:227], v251 offset:52224
	global_load_lds_dwordx4 v182, s[98:99]
	s_barrier
	s_waitcnt lgkmcnt(0)
	v_mfma_f32_16x16x32_bf16 v[118:121], v[188:191], v[146:149], v[118:121]
	v_mfma_f32_16x16x32_bf16 v[114:117], v[196:199], v[146:149], v[114:117]
	v_mfma_f32_16x16x32_bf16 v[102:105], v[188:191], v[154:157], v[102:105]
	v_mfma_f32_16x16x32_bf16 v[98:101], v[196:199], v[154:157], v[98:101]
	v_mfma_f32_16x16x32_bf16 v[86:89], v[188:191], v[162:165], v[86:89]
	v_mfma_f32_16x16x32_bf16 v[82:85], v[196:199], v[162:165], v[82:85]
	v_mfma_f32_16x16x32_bf16 v[70:73], v[188:191], v[170:173], v[70:73]
	v_mfma_f32_16x16x32_bf16 v[66:69], v[196:199], v[170:173], v[66:69]
	v_mfma_f32_16x16x32_bf16 v[118:121], v[192:195], v[150:153], v[118:121]
	v_mfma_f32_16x16x32_bf16 v[114:117], v[224:227], v[150:153], v[114:117]
	v_mfma_f32_16x16x32_bf16 v[102:105], v[192:195], v[158:161], v[102:105]
	v_mfma_f32_16x16x32_bf16 v[98:101], v[224:227], v[158:161], v[98:101]
	v_mfma_f32_16x16x32_bf16 v[86:89], v[192:195], v[166:169], v[86:89]
	v_mfma_f32_16x16x32_bf16 v[82:85], v[224:227], v[166:169], v[82:85]
	v_mfma_f32_16x16x32_bf16 v[70:73], v[192:195], v[174:177], v[70:73]
	v_mfma_f32_16x16x32_bf16 v[66:69], v[224:227], v[174:177], v[66:69]
	s_barrier
	s_mov_b32 m0, s57
	ds_read_b128 v[146:149], v223 offset:49152
	ds_read_b128 v[150:153], v223 offset:50176
	ds_read_b128 v[154:157], v223 offset:51200
	ds_read_b128 v[158:161], v223 offset:52224
	ds_read_b128 v[162:165], v223 offset:53248
	ds_read_b128 v[166:169], v223 offset:54272
	ds_read_b128 v[170:173], v223 offset:55296
	global_load_lds_dwordx4 v0, s[100:101]
	s_mov_b32 m0, s60
	ds_read_b128 v[174:177], v223 offset:56320
	global_load_lds_dwordx4 v182, s[100:101]
	s_barrier
	s_waitcnt lgkmcnt(0)
	v_mfma_f32_16x16x32_bf16 v[62:65], v[130:133], v[146:149], v[62:65]
	v_mfma_f32_16x16x32_bf16 v[58:61], v[138:141], v[146:149], v[58:61]
	v_mfma_f32_16x16x32_bf16 v[46:49], v[130:133], v[154:157], v[46:49]
	v_mfma_f32_16x16x32_bf16 v[42:45], v[138:141], v[154:157], v[42:45]
	v_mfma_f32_16x16x32_bf16 v[30:33], v[130:133], v[162:165], v[30:33]
	v_mfma_f32_16x16x32_bf16 v[26:29], v[138:141], v[162:165], v[26:29]
	v_mfma_f32_16x16x32_bf16 v[14:17], v[130:133], v[170:173], v[14:17]
	v_mfma_f32_16x16x32_bf16 v[10:13], v[138:141], v[170:173], v[10:13]
	v_mfma_f32_16x16x32_bf16 v[62:65], v[134:137], v[150:153], v[62:65]
	v_mfma_f32_16x16x32_bf16 v[58:61], v[142:145], v[150:153], v[58:61]
	v_mfma_f32_16x16x32_bf16 v[46:49], v[134:137], v[158:161], v[46:49]
	v_mfma_f32_16x16x32_bf16 v[42:45], v[142:145], v[158:161], v[42:45]
	v_mfma_f32_16x16x32_bf16 v[30:33], v[134:137], v[166:169], v[30:33]
	v_mfma_f32_16x16x32_bf16 v[26:29], v[142:145], v[166:169], v[26:29]
	v_mfma_f32_16x16x32_bf16 v[14:17], v[134:137], v[174:177], v[14:17]
	v_mfma_f32_16x16x32_bf16 v[10:13], v[142:145], v[174:177], v[10:13]
	s_barrier
; #define PG8_STAGE(bufoff, gbase, voff) do { _Pragma("unroll") for (int _i = 0; _i < 2; ++_i) \
;         __builtin_amdgcn_global_load_lds((const unsigned*)((const char*)(gbase) + (voff)[_i]), (LAS unsigned*)(lds + (bufoff) + ldsw + _i * 8192), 16, 0, 0); } while (0)
; #define PG8_MMA(ai, bj, At, Bt) do { __builtin_amdgcn_s_setprio(1); _Pragma("unroll") for (int m = 0; m < 4; ++m) _Pragma("unroll") for (int n = 0; n < 2; ++n) _Pragma("unroll") for (int k = 0; k < 2; ++k) \
;         acc[ai][bj][m][n] = __builtin_amdgcn_mfma_f32_16x16x32_bf16(Bt[n][k], At[m][k], acc[ai][bj][m][n], 0, 0, 0); __builtin_amdgcn_s_setprio(0); } while (0)
; #define PG8_WAIT_V(n) asm volatile("s_waitcnt vmcnt(" #n ")" ::: "memory")
; #define PG8_BAR __builtin_amdgcn_s_barrier()
;     __device__ __forceinline__ void scales2(const Unit& u, int wr, int fr, int fq, float& sA, float& sB) const {
;         const int rowA = u.pm * BM + wr * 64 + fq * 16 + fr;
;         const f32x4* pa = (const f32x4*)(ssq_in + (size_t)rowA * 16); const f32x4* pb = (const f32x4*)(ssq_in + (size_t)(rowA + HALF) * 16);
;         const f32x4 a0 = pa[0], a1 = pa[1], a2 = pa[2], a3 = pa[3], b0 = pb[0], b1 = pb[1], b2 = pb[2], b3 = pb[3];
;         const float ta = (((a0[0] + a0[1]) + (a0[2] + a0[3])) + ((a1[0] + a1[1]) + (a1[2] + a1[3]))) + (((a2[0] + a2[1]) + (a2[2] + a2[3])) + ((a3[0] + a3[1]) + (a3[2] + a3[3])));
;         const float tb = (((b0[0] + b0[1]) + (b0[2] + b0[3])) + ((b1[0] + b1[1]) + (b1[2] + b1[3]))) + (((b2[0] + b2[1]) + (b2[2] + b2[3])) + ((b3[0] + b3[1]) + (b3[2] + b3[3])));
;         sA = rsqrtf(ta * (1.0f / 1024.0f) + EPS); sB = rsqrtf(tb * (1.0f / 1024.0f) + EPS);
; template <int MODE, class EpiT, class Sched>
; __device__ __forceinline__ void gemm_phase(LAS unsigned char* lds, const Gemm g, const Sched& S, const EpiT& E) {
;     ...
;             PG8_STAGE(PG8_SB(1, 1), b3 + hstep, voffB);
;             PG8_WAIT_V(6); PG8_BAR; PG8_MMA(1, 1, At, B1); PG8_BAR;
;         }
	s_add_i32 s30, s44, s68
	s_add_u32 s98, s98, s38
	s_addc_u32 s99, s99, 0
	s_mov_b32 m0, s30
	s_nop 0
	global_load_lds_dwordx4 v0, s[98:99]
	s_add_i32 m0, s30, 0x2000
	s_nop 0
	global_load_lds_dwordx4 v182, s[98:99]
	s_waitcnt vmcnt(6)
	s_barrier
	v_mfma_f32_16x16x32_bf16 v[54:57], v[188:191], v[146:149], v[54:57]
	v_mfma_f32_16x16x32_bf16 v[50:53], v[196:199], v[146:149], v[50:53]
	v_mfma_f32_16x16x32_bf16 v[38:41], v[188:191], v[154:157], v[38:41]
	v_mfma_f32_16x16x32_bf16 v[34:37], v[196:199], v[154:157], v[34:37]
	v_mfma_f32_16x16x32_bf16 v[22:25], v[188:191], v[162:165], v[22:25]
	v_mfma_f32_16x16x32_bf16 v[18:21], v[196:199], v[162:165], v[18:21]
	v_mfma_f32_16x16x32_bf16 v[6:9], v[188:191], v[170:173], v[6:9]
	v_mfma_f32_16x16x32_bf16 v[2:5], v[196:199], v[170:173], v[2:5]
	v_mfma_f32_16x16x32_bf16 v[54:57], v[192:195], v[150:153], v[54:57]
	v_mfma_f32_16x16x32_bf16 v[50:53], v[224:227], v[150:153], v[50:53]
	v_mfma_f32_16x16x32_bf16 v[38:41], v[192:195], v[158:161], v[38:41]
	v_mfma_f32_16x16x32_bf16 v[34:37], v[224:227], v[158:161], v[34:37]
	v_mfma_f32_16x16x32_bf16 v[22:25], v[192:195], v[166:169], v[22:25]
	v_mfma_f32_16x16x32_bf16 v[18:21], v[224:227], v[166:169], v[18:21]
	v_mfma_f32_16x16x32_bf16 v[6:9], v[192:195], v[174:177], v[6:9]
	v_mfma_f32_16x16x32_bf16 v[2:5], v[224:227], v[174:177], v[2:5]
	s_barrier
	s_add_u32 s4, s4, 0x100
	s_addc_u32 s5, s5, 0
	s_add_u32 s23, s23, 0x100
	s_addc_u32 s24, s24, 0
	s_cmp_ge_u32 s89, s21
	s_mov_b32 s30, s89
	s_cbranch_scc0 .LBB0_159
	s_lshl_b32 s4, s22, 8
	s_add_i32 s4, s4, s56
	v_or_b32_e32 v130, s4, v222
	v_ashrrev_i32_e32 v131, 31, v130
	v_lshlrev_b64 v[130:131], 6, v[130:131]
	v_lshl_add_u64 v[146:147], s[66:67], 0, v[130:131]
	global_load_dwordx4 v[130:133], v[146:147], off offset:16
	global_load_dwordx4 v[134:137], v[146:147], off offset:48
	global_load_dwordx4 v[138:141], v[146:147], off
	global_load_dwordx4 v[142:145], v[146:147], off offset:32
	v_or_b32_e32 v192, s4, v181
	s_mov_b64 s[4:5], 0x2000
	v_lshl_add_u64 v[158:159], v[146:147], 0, s[4:5]
	v_add_co_u32_e32 v146, vcc, 0x2000, v146
	s_mov_b32 s4, 0x3a800000
	s_nop 0
	v_addc_co_u32_e32 v147, vcc, 0, v147, vcc
	global_load_dwordx4 v[146:149], v[146:147], off
	s_nop 0
	global_load_dwordx4 v[150:153], v[158:159], off offset:16
	global_load_dwordx4 v[154:157], v[158:159], off offset:48
	s_nop 0
	global_load_dwordx4 v[158:161], v[158:159], off offset:32
	v_lshl_or_b32 v188, s2, 8, v221
	v_ashrrev_i32_e32 v193, 31, v192
	v_ashrrev_i32_e32 v189, 31, v188
	v_or_b32_e32 v194, 16, v192
	v_ashrrev_i32_e32 v195, 31, v194
	s_waitcnt vmcnt(0)
	v_mov_b32_e32 v162, v138
	v_mov_b32_e32 v163, v142
	v_mov_b32_e32 v142, v139
	v_pk_add_f32 v[138:139], v[162:163], v[142:143]
	v_mov_b32_e32 v142, v140
	v_mov_b32_e32 v143, v144
	v_mov_b32_e32 v144, v141
	v_pk_add_f32 v[140:141], v[142:143], v[144:145]
	s_nop 0
	v_pk_add_f32 v[138:139], v[138:139], v[140:141]
	v_mov_b32_e32 v140, v130
	v_mov_b32_e32 v141, v134
	v_mov_b32_e32 v134, v131
	v_pk_add_f32 v[130:131], v[140:141], v[134:135]
	v_mov_b32_e32 v134, v132
	v_mov_b32_e32 v135, v136
	v_mov_b32_e32 v136, v133
	v_pk_add_f32 v[132:133], v[134:135], v[136:137]
	v_mov_b32_e32 v134, v148
	v_pk_add_f32 v[130:131], v[130:131], v[132:133]
	v_mov_b32_e32 v132, v146
	v_mov_b32_e32 v133, v158
	v_mov_b32_e32 v158, v147
	v_mov_b32_e32 v135, v160
	v_mov_b32_e32 v160, v149
	v_pk_add_f32 v[132:133], v[132:133], v[158:159]
	v_pk_add_f32 v[134:135], v[134:135], v[160:161]
	v_mov_b32_e32 v136, v152
	v_pk_add_f32 v[132:133], v[132:133], v[134:135]
	v_mov_b32_e32 v134, v150
	v_mov_b32_e32 v135, v154
	v_mov_b32_e32 v154, v151
	v_mov_b32_e32 v137, v156
	v_mov_b32_e32 v156, v153
	v_pk_add_f32 v[134:135], v[134:135], v[154:155]
	v_pk_add_f32 v[136:137], v[136:137], v[156:157]
	v_pk_add_f32 v[130:131], v[138:139], v[130:131]
	v_pk_add_f32 v[134:135], v[134:135], v[136:137]
	s_nop 0
	v_pk_add_f32 v[132:133], v[132:133], v[134:135]
	v_mov_b32_e32 v135, v130
	v_mov_b32_e32 v134, v132
	v_mov_b32_e32 v130, v133
	v_pk_add_f32 v[130:131], v[134:135], v[130:131]
	s_nop 0
	v_pk_fma_f32 v[190:191], v[130:131], s[4:5], v[178:179] op_sel_hi:[1,0,0]
	s_mov_b32 s4, 0x800000
	v_mul_f32_e32 v130, 0x4b800000, v191
	v_cmp_gt_f32_e64 s[44:45], s4, v191
	v_cmp_gt_f32_e32 vcc, s4, v190
	s_nop 0
	v_cndmask_b32_e64 v130, v191, v130, s[44:45]
	v_rsq_f32_e32 v130, v130
	s_nop 0
	v_mul_f32_e32 v131, 0x45800000, v130
	v_cndmask_b32_e64 v226, v130, v131, s[44:45]
	v_lshlrev_b64 v[130:131], 10, v[192:193]
	v_lshl_add_u64 v[130:131], v[130:131], 0, v[188:189]
	v_lshlrev_b64 v[198:199], 1, v[130:131]
	v_lshl_add_u64 v[130:131], s[34:35], 0, v[198:199]
	v_lshl_add_u64 v[132:133], s[92:93], 0, v[198:199]
	global_load_dwordx4 v[170:173], v[130:131], off
	global_load_dwordx4 v[174:177], v[132:133], off
	v_lshl_add_u64 v[134:135], s[6:7], 0, v[198:199]
	global_load_dwordx4 v[166:169], v[134:135], off
	global_load_dwordx4 v[158:161], v[130:131], off offset:256
	global_load_dwordx4 v[162:165], v[132:133], off offset:256
	global_load_dwordx4 v[146:149], v[134:135], off offset:256
	v_and_b32_e32 v130, 64, v205
	v_or_b32_e32 v200, v130, v181
	v_lshlrev_b32_e32 v225, 2, v200
	ds_bpermute_b32 v200, v225, v226
	v_xor_b32_e32 v131, 16, v205
	v_add_u32_e32 v130, 64, v130
	v_cmp_lt_i32_e64 s[44:45], v131, v130
	s_waitcnt lgkmcnt(0)
;     template <int mode> __device__ __forceinline__ void run(const f32x4 (&acc)[2][2][4][2], const Unit& u, int wr, int wc, int fr, int fq, const LAS float* sc) const {
;     ...
;             for (int g = 0; g < 8; ++g) {
;                 const int ai = g >> 2, m = g & 3, cb = g & 1, nb = cb ^ 1;
;                 const int row = row0 + ai * HALF + m * 16;
;                 const size_t off = (size_t)row * D + col0;
;                 if (g < 7) {
;                     const size_t offn = (size_t)(row0 + ((g + 1) >> 2) * HALF + ((g + 1) & 3) * 16) * D + col0;
; #pragma unroll
;                     for (int bj = 0; bj < 2; ++bj) {
;                         const size_t o = offn + bj * HALF;
;                         if (mode == 5) { xi[nb][2 * bj] = *(const f32x4*)(xin + o); xi[nb][2 * bj + 1] = *(const f32x4*)(xin + o + 4); }
;                         else { xh[nb][bj] = *(const u32x4*)(hin + o); xl[nb][bj] = *(const u32x4*)(lin + o); }
;                         if (mode == 4) pq[nb][bj] = *(const u32x4*)(ob + o);
;                     }
;                 }
;                 float s = 1.f;
;                 if (mode == 4) s = __shfl(ai ? sB : sA, m * 16 + fr);
;                 float ss = 0.f;
; #pragma unroll
;                 for (int bj = 0; bj < 2; ++bj) {
;                     u32x4 wh, wl;
; #pragma unroll
;                     for (int n = 0; n < 2; ++n) {
;                         const int q = 2 * bj + n;
;                         const unsigned h0 = n ? xh[cb][bj].z : xh[cb][bj].x, h1 = n ? xh[cb][bj].w : xh[cb][bj].y, l0 = n ? xl[cb][bj].z : xl[cb][bj].x, l1 = n ? xl[cb][bj].w : xl[cb][bj].y;
;                         f32x4 xo;
;                         if (mode == 5) xo = xi[cb][q];
;                         else { xo[0] = bf_lo(h0) + bf_lo(l0); xo[1] = bf_hi(h0) + bf_hi(l0); xo[2] = bf_lo(h1) + bf_lo(l1); xo[3] = bf_hi(h1) + bf_hi(l1); }
;                         f32x4 v;
;                         if (mode != 4) v = xo + acc[ai][bj][m][n] * alpha + bvv[q];
;                         else {
;                             const f32x4 a = acc[ai][bj][m][n] * s;
;                             const unsigned p0 = n ? pq[cb][bj].z : pq[cb][bj].x, p1 = n ? pq[cb][bj].w : pq[cb][bj].y;
;                             v[0] = xo[0] + sigmoidf_(a[0]) * bf_lo(p0); v[1] = xo[1] + sigmoidf_(a[1]) * bf_hi(p0);
	v_pk_mul_f32 v[126:127], v[126:127], v[200:201] op_sel_hi:[1,0]
	v_cndmask_b32_e64 v131, v205, v131, s[44:45]
	v_lshlrev_b32_e32 v191, 2, v131
	v_xor_b32_e32 v131, 32, v205
	v_mul_f32_e32 v126, 0xbfb8aa3b, v126
	v_cmp_lt_i32_e64 s[44:45], v131, v130
	v_exp_f32_e32 v126, v126
	v_pk_mul_f32 v[128:129], v[128:129], v[200:201] op_sel_hi:[1,0]
	v_cndmask_b32_e64 v130, v205, v131, s[44:45]
	v_lshlrev_b32_e32 v224, 2, v130
	v_lshlrev_b64 v[130:131], 10, v[194:195]
	v_lshl_add_u64 v[130:131], v[130:131], 0, v[188:189]
	v_lshlrev_b64 v[196:197], 1, v[130:131]
	v_add_f32_e32 v126, 1.0, v126
	v_lshl_add_u64 v[130:131], s[34:35], 0, v[196:197]
	v_lshl_add_u64 v[132:133], s[92:93], 0, v[196:197]
	v_lshl_add_u64 v[228:229], s[6:7], 0, v[196:197]
	v_rcp_f32_e32 v126, v126
	global_load_dwordx4 v[150:153], v[130:131], off
	global_load_dwordx4 v[154:157], v[132:133], off
	global_load_dwordx4 v[142:145], v[228:229], off
	global_load_dwordx4 v[134:137], v[130:131], off offset:256
	global_load_dwordx4 v[138:141], v[132:133], off offset:256
	s_nop 0
	global_load_dwordx4 v[130:133], v[228:229], off offset:256
	v_pk_mul_f32 v[122:123], v[122:123], v[200:201] op_sel_hi:[1,0]
	v_pk_mul_f32 v[124:125], v[124:125], v[200:201] op_sel_hi:[1,0]
	v_mul_f32_e32 v122, 0xbfb8aa3b, v122
	v_exp_f32_e32 v122, v122
	v_pk_mul_f32 v[118:119], v[118:119], v[200:201] op_sel_hi:[1,0]
	v_pk_mul_f32 v[120:121], v[120:121], v[200:201] op_sel_hi:[1,0]
	v_mul_f32_e32 v118, 0xbfb8aa3b, v118
	v_add_f32_e32 v122, 1.0, v122
	v_rcp_f32_e32 v122, v122
	v_exp_f32_e32 v118, v118
	v_pk_mul_f32 v[114:115], v[114:115], v[200:201] op_sel_hi:[1,0]
	v_pk_mul_f32 v[116:117], v[116:117], v[200:201] op_sel_hi:[1,0]
	v_mul_f32_e32 v114, 0xbfb8aa3b, v114
	v_add_f32_e32 v118, 1.0, v118
	v_rcp_f32_e32 v118, v118
	v_exp_f32_e32 v114, v114
	s_lshl_b32 s44, s2, 2
	s_ashr_i32 s45, s44, 31
	v_add_f32_e32 v114, 1.0, v114
	v_rcp_f32_e32 v114, v114
	s_waitcnt vmcnt(11)
	v_lshlrev_b32_e32 v227, 16, v170
	s_waitcnt vmcnt(10)
	v_lshlrev_b32_e32 v228, 16, v174
	v_and_b32_e32 v174, 0xffff0000, v174
	v_and_b32_e32 v170, 0xffff0000, v170
	v_add_f32_e32 v227, v228, v227
	v_add_f32_e32 v170, v174, v170
	v_lshlrev_b32_e32 v174, 16, v171
	v_lshlrev_b32_e32 v228, 16, v175
	v_and_b32_e32 v175, 0xffff0000, v175
	v_and_b32_e32 v171, 0xffff0000, v171
	v_add_f32_e32 v171, v175, v171
	s_waitcnt vmcnt(9)
	v_lshlrev_b32_e32 v175, 16, v166
	v_fmac_f32_e32 v227, v126, v175
	v_mul_f32_e32 v126, 0xbfb8aa3b, v127
	v_exp_f32_e32 v126, v126
	v_and_b32_e32 v127, 0xffff0000, v166
	v_add_f32_e32 v174, v228, v174
	v_add_f32_e32 v126, 1.0, v126
	v_rcp_f32_e32 v126, v126
	s_nop 0
	v_fmac_f32_e32 v170, v126, v127
	v_mul_f32_e32 v126, 0xbfb8aa3b, v128
	v_exp_f32_e32 v126, v126
	v_lshlrev_b32_e32 v127, 16, v167
	v_add_f32_e32 v126, 1.0, v126
	v_rcp_f32_e32 v126, v126
	s_nop 0
	v_fmac_f32_e32 v174, v126, v127
	v_mul_f32_e32 v126, 0xbfb8aa3b, v129
	v_exp_f32_e32 v126, v126
	v_and_b32_e32 v127, 0xffff0000, v167
	v_add_f32_e32 v126, 1.0, v126
	v_rcp_f32_e32 v126, v126
	s_nop 0
	v_fmac_f32_e32 v171, v126, v127
	v_cvt_pk_bf16_f32 v126, v227, v170
	v_cvt_pk_bf16_f32 v127, v174, v171
	s_nop 0
	v_lshlrev_b32_e32 v128, 16, v126
	v_and_b32_e32 v129, 0xffff0000, v126
	v_sub_f32_e32 v128, v227, v128
	v_sub_f32_e32 v129, v170, v129
	v_cvt_pk_bf16_f32 v166, v128, v129
	v_lshlrev_b32_e32 v128, 16, v127
	v_and_b32_e32 v129, 0xffff0000, v127
	v_sub_f32_e32 v128, v174, v128
	v_sub_f32_e32 v129, v171, v129
	v_cvt_pk_bf16_f32 v167, v128, v129
	v_mul_f32_e32 v128, v170, v170
	v_mul_f32_e32 v129, v171, v171
	v_fmac_f32_e32 v128, v227, v227
	v_fmac_f32_e32 v129, v174, v174
	v_add_f32_e32 v170, v128, v129
	v_lshlrev_b32_e32 v128, 16, v172
	v_lshlrev_b32_e32 v129, 16, v176
	v_add_f32_e32 v171, v129, v128
	v_and_b32_e32 v128, 0xffff0000, v176
	v_and_b32_e32 v129, 0xffff0000, v172
	v_add_f32_e32 v172, v128, v129
	v_lshlrev_b32_e32 v128, 16, v173
	v_lshlrev_b32_e32 v129, 16, v177
	v_add_f32_e32 v174, v129, v128
	v_and_b32_e32 v128, 0xffff0000, v177
	v_and_b32_e32 v129, 0xffff0000, v173
	v_add_f32_e32 v173, v128, v129
	v_lshlrev_b32_e32 v128, 16, v168
	v_fmac_f32_e32 v171, v122, v128
	v_mul_f32_e32 v122, 0xbfb8aa3b, v123
	v_exp_f32_e32 v122, v122
	v_and_b32_e32 v123, 0xffff0000, v168
	v_add_f32_e32 v122, 1.0, v122
	v_rcp_f32_e32 v122, v122
	s_nop 0
	v_fmac_f32_e32 v172, v122, v123
	v_mul_f32_e32 v122, 0xbfb8aa3b, v124
	v_exp_f32_e32 v122, v122
	v_lshlrev_b32_e32 v123, 16, v169
	v_cvt_pk_bf16_f32 v128, v171, v172
	v_add_f32_e32 v122, 1.0, v122
	v_rcp_f32_e32 v122, v122
	s_nop 0
	v_fmac_f32_e32 v174, v122, v123
	v_mul_f32_e32 v122, 0xbfb8aa3b, v125
	v_exp_f32_e32 v122, v122
	v_and_b32_e32 v123, 0xffff0000, v169
	v_lshl_add_u64 v[124:125], s[28:29], 0, v[198:199]
	v_add_f32_e32 v122, 1.0, v122
	v_rcp_f32_e32 v122, v122
	s_nop 0
	v_fmac_f32_e32 v173, v122, v123
	v_lshlrev_b32_e32 v122, 16, v128
	v_and_b32_e32 v123, 0xffff0000, v128
	v_sub_f32_e32 v122, v171, v122
	v_sub_f32_e32 v123, v172, v123
	v_cvt_pk_bf16_f32 v129, v174, v173
	v_cvt_pk_bf16_f32 v168, v122, v123
	s_nop 0
	v_lshlrev_b32_e32 v122, 16, v129
	v_and_b32_e32 v123, 0xffff0000, v129
	v_sub_f32_e32 v122, v174, v122
	v_sub_f32_e32 v123, v173, v123
	v_cvt_pk_bf16_f32 v169, v122, v123
	v_mul_f32_e32 v122, v172, v172
	v_mul_f32_e32 v123, v173, v173
	v_fmac_f32_e32 v122, v171, v171
	v_fmac_f32_e32 v123, v174, v174
	v_add_f32_e32 v122, v122, v123
	v_add_f32_e32 v170, v170, v122
	v_lshl_add_u64 v[122:123], s[10:11], 0, v[198:199]
	global_store_dwordx4 v[122:123], v[126:129], off
	global_store_dwordx4 v[124:125], v[166:169], off
	s_waitcnt vmcnt(10)
; __device__ __forceinline__ float bf_lo(unsigned w) { return __uint_as_float(w << 16); }
; __device__ __forceinline__ float bf_hi(unsigned w) { return __uint_as_float(w & 0xffff0000u); }
;     template <int mode> __device__ __forceinline__ void run(const f32x4 (&acc)[2][2][4][2], const Unit& u, int wr, int wc, int fr, int fq, const LAS float* sc) const {
;     ...
;                 for (int bj = 0; bj < 2; ++bj) {
;                     u32x4 wh, wl;
; #pragma unroll
;                     for (int n = 0; n < 2; ++n) {
;                         const int q = 2 * bj + n;
;                         const unsigned h0 = n ? xh[cb][bj].z : xh[cb][bj].x, h1 = n ? xh[cb][bj].w : xh[cb][bj].y, l0 = n ? xl[cb][bj].z : xl[cb][bj].x, l1 = n ? xl[cb][bj].w : xl[cb][bj].y;
;                         f32x4 xo;
;                         if (mode == 5) xo = xi[cb][q];
;                         else { xo[0] = bf_lo(h0) + bf_lo(l0); xo[1] = bf_hi(h0) + bf_hi(l0); xo[2] = bf_lo(h1) + bf_lo(l1); xo[3] = bf_hi(h1) + bf_hi(l1); }
;                         f32x4 v;
;                         if (mode != 4) v = xo + acc[ai][bj][m][n] * alpha + bvv[q];
;                         else {
;                             const f32x4 a = acc[ai][bj][m][n] * s;
;                             const unsigned p0 = n ? pq[cb][bj].z : pq[cb][bj].x, p1 = n ? pq[cb][bj].w : pq[cb][bj].y;
;                             v[0] = xo[0] + sigmoidf_(a[0]) * bf_lo(p0); v[1] = xo[1] + sigmoidf_(a[1]) * bf_hi(p0);
;                             v[2] = xo[2] + sigmoidf_(a[2]) * bf_lo(p1); v[3] = xo[3] + sigmoidf_(a[3]) * bf_hi(p1);
;                         }
;                         const unsigned w0 = pk2(v[0], v[1]), w1 = pk2(v[2], v[3]);
;                         const unsigned m0 = pk2(v[0] - bf_lo(w0), v[1] - bf_hi(w0)), m1 = pk2(v[2] - bf_lo(w1), v[3] - bf_hi(w1));
;                         if (n == 0) { wh.x = w0; wh.y = w1; wl.x = m0; wl.y = m1; } else { wh.z = w0; wh.w = w1; wl.z = m0; wl.w = m1; }
;                         ss += (v[0] * v[0] + v[1] * v[1]) + (v[2] * v[2] + v[3] * v[3]);
;                     }
;                     *(u32x4*)(xb + off + bj * HALF) = wh;
;                     *(u32x4*)(lout + off + bj * HALF) = wl;
;                 }
;                 ss += __shfl_xor(ss, 16); ss += __shfl_xor(ss, 32);
;                 if (fq == 0) ssq_out[(size_t)row * 16 + u.pn * 4 + wc] = ss;
	v_lshlrev_b32_e32 v126, 16, v158
	s_waitcnt vmcnt(9)
	v_lshlrev_b32_e32 v127, 16, v162
	v_add_f32_e32 v128, v127, v126
	v_and_b32_e32 v126, 0xffff0000, v162
	v_and_b32_e32 v127, 0xffff0000, v158
	v_add_f32_e32 v129, v126, v127
	v_lshlrev_b32_e32 v126, 16, v159
	v_lshlrev_b32_e32 v127, 16, v163
	v_add_f32_e32 v158, v127, v126
	v_and_b32_e32 v126, 0xffff0000, v163
	v_and_b32_e32 v127, 0xffff0000, v159
	v_add_f32_e32 v159, v126, v127
	s_waitcnt vmcnt(8)
	v_lshlrev_b32_e32 v126, 16, v146
	v_fmac_f32_e32 v128, v118, v126
	v_mul_f32_e32 v118, 0xbfb8aa3b, v119
	v_exp_f32_e32 v118, v118
	v_and_b32_e32 v119, 0xffff0000, v146
	v_add_f32_e32 v118, 1.0, v118
	v_rcp_f32_e32 v118, v118
	s_nop 0
	v_fmac_f32_e32 v129, v118, v119
	v_mul_f32_e32 v118, 0xbfb8aa3b, v120
	v_exp_f32_e32 v118, v118
	v_lshlrev_b32_e32 v119, 16, v147
	v_add_f32_e32 v118, 1.0, v118
	v_rcp_f32_e32 v118, v118
	s_nop 0
	v_fmac_f32_e32 v158, v118, v119
	v_mul_f32_e32 v118, 0xbfb8aa3b, v121
	v_exp_f32_e32 v118, v118
	v_and_b32_e32 v119, 0xffff0000, v147
	v_add_f32_e32 v118, 1.0, v118
	v_rcp_f32_e32 v118, v118
	s_nop 0
	v_fmac_f32_e32 v159, v118, v119
	v_cvt_pk_bf16_f32 v118, v128, v129
	v_cvt_pk_bf16_f32 v119, v158, v159
	s_nop 0
	v_lshlrev_b32_e32 v120, 16, v118
	v_and_b32_e32 v121, 0xffff0000, v118
	v_sub_f32_e32 v120, v128, v120
	v_sub_f32_e32 v121, v129, v121
	v_cvt_pk_bf16_f32 v126, v120, v121
	v_lshlrev_b32_e32 v120, 16, v119
	v_and_b32_e32 v121, 0xffff0000, v119
	v_sub_f32_e32 v120, v158, v120
	v_sub_f32_e32 v121, v159, v121
	v_cvt_pk_bf16_f32 v127, v120, v121
	v_mul_f32_e32 v120, v129, v129
	v_mul_f32_e32 v121, v159, v159
	v_fmac_f32_e32 v120, v128, v128
	v_fmac_f32_e32 v121, v158, v158
	v_add_f32_e32 v120, v120, v121
	v_add_f32_e32 v146, v120, v170
	v_lshlrev_b32_e32 v120, 16, v160
	v_lshlrev_b32_e32 v121, 16, v164
	v_add_f32_e32 v147, v121, v120
	v_and_b32_e32 v120, 0xffff0000, v164
	v_and_b32_e32 v121, 0xffff0000, v160
	v_add_f32_e32 v158, v120, v121
	v_lshlrev_b32_e32 v120, 16, v161
	v_lshlrev_b32_e32 v121, 16, v165
	v_add_f32_e32 v159, v121, v120
	v_and_b32_e32 v120, 0xffff0000, v165
	v_and_b32_e32 v121, 0xffff0000, v161
	v_add_f32_e32 v160, v120, v121
	v_lshlrev_b32_e32 v120, 16, v148
	v_fmac_f32_e32 v147, v114, v120
	v_mul_f32_e32 v114, 0xbfb8aa3b, v115
	v_exp_f32_e32 v114, v114
	v_and_b32_e32 v115, 0xffff0000, v148
	v_add_f32_e32 v114, 1.0, v114
	v_rcp_f32_e32 v114, v114
	s_nop 0
	v_fmac_f32_e32 v158, v114, v115
	v_mul_f32_e32 v114, 0xbfb8aa3b, v116
	v_exp_f32_e32 v114, v114
	v_lshlrev_b32_e32 v115, 16, v149
	v_cvt_pk_bf16_f32 v120, v147, v158
	v_add_f32_e32 v114, 1.0, v114
	v_rcp_f32_e32 v114, v114
	s_nop 0
	v_fmac_f32_e32 v159, v114, v115
	v_mul_f32_e32 v114, 0xbfb8aa3b, v117
	v_exp_f32_e32 v114, v114
	v_and_b32_e32 v115, 0xffff0000, v149
	v_add_f32_e32 v114, 1.0, v114
	v_rcp_f32_e32 v114, v114
	s_nop 0
	v_fmac_f32_e32 v160, v114, v115
	v_lshlrev_b32_e32 v114, 16, v120
	v_and_b32_e32 v115, 0xffff0000, v120
	v_sub_f32_e32 v114, v147, v114
	v_sub_f32_e32 v115, v158, v115
	v_cvt_pk_bf16_f32 v121, v159, v160
	v_cvt_pk_bf16_f32 v128, v114, v115
	s_nop 0
	v_lshlrev_b32_e32 v114, 16, v121
	v_and_b32_e32 v115, 0xffff0000, v121
	v_sub_f32_e32 v114, v159, v114
	v_sub_f32_e32 v115, v160, v115
	v_cvt_pk_bf16_f32 v129, v114, v115
	v_mul_f32_e32 v114, v158, v158
	v_mul_f32_e32 v115, v160, v160
	v_fmac_f32_e32 v114, v147, v147
	v_fmac_f32_e32 v115, v159, v159
	v_add_f32_e32 v114, v114, v115
	v_add_f32_e32 v114, v114, v146
	ds_bpermute_b32 v115, v191, v114
	global_store_dwordx4 v[122:123], v[118:121], off offset:256
	global_store_dwordx4 v[124:125], v[126:129], off offset:256
	s_waitcnt lgkmcnt(0)
	v_add_f32_e32 v114, v114, v115
	ds_bpermute_b32 v115, v224, v114
	s_and_saveexec_b64 s[4:5], s[40:41]
	s_cbranch_execz .LBB0_162
	v_lshlrev_b64 v[116:117], 6, v[192:193]
	v_lshl_add_u64 v[116:117], s[62:63], 0, v[116:117]
	v_lshl_add_u64 v[116:117], s[44:45], 2, v[116:117]
	s_lshl_b32 s24, s20, 2
	v_lshl_add_u64 v[116:117], v[116:117], 0, s[24:25]
	s_waitcnt lgkmcnt(0)
	v_add_f32_e32 v114, v114, v115
	global_store_dword v[116:117], v114, off

; #define PG8_STAGE(bufoff, gbase, voff) do { _Pragma("unroll") for (int _i = 0; _i < 2; ++_i) \
;         __builtin_amdgcn_global_load_lds((const unsigned*)((const char*)(gbase) + (voff)[_i]), (LAS unsigned*)(lds + (bufoff) + ldsw + _i * 8192), 16, 0, 0); } while (0)
; #define PG8_LDA(dst, b, h) do { _Pragma("unroll") for (int m = 0; m < 4; ++m) _Pragma("unroll") for (int k = 0; k < 2; ++k) dst[m][k] = *(const LAS bf16x8*)(lds + PG8_SA(b, h) + aoff + m * 2048 + k * 1024); } while (0)
; #define PG8_LDB(dst, b, h) do { _Pragma("unroll") for (int n = 0; n < 2; ++n) _Pragma("unroll") for (int k = 0; k < 2; ++k) dst[n][k] = *(const LAS bf16x8*)(lds + PG8_SB(b, h) + boff + n * 2048 + k * 1024); } while (0)
; #define PG8_MMA(ai, bj, At, Bt) do { __builtin_amdgcn_s_setprio(1); _Pragma("unroll") for (int m = 0; m < 4; ++m) _Pragma("unroll") for (int n = 0; n < 2; ++n) _Pragma("unroll") for (int k = 0; k < 2; ++k) \
;         acc[ai][bj][m][n] = __builtin_amdgcn_mfma_f32_16x16x32_bf16(Bt[n][k], At[m][k], acc[ai][bj][m][n], 0, 0, 0); __builtin_amdgcn_s_setprio(0); } while (0)
; #define PG8_WAIT_V(n) asm volatile("s_waitcnt vmcnt(" #n ")" ::: "memory")
; #define PG8_WAIT_L(n) asm volatile("s_waitcnt lgkmcnt(" #n ")" ::: "memory")
; #define PG8_BAR __builtin_amdgcn_s_barrier()
; #define PG8_SCHED __builtin_amdgcn_sched_barrier(0)
; template <int MODE, class EpiT, class Sched>
; __device__ __forceinline__ void gemm_phase(LAS unsigned char* lds, const Gemm g, const Sched& S, const EpiT& E) {
;     ...
;             PG8_LDB(B0, 0, 0); PG8_SCHED; PG8_LDA(At, 0, 0); PG8_STAGE(PG8_SA(1, 1), a1 + hstep, voffA);
;             PG8_WAIT_L(8); PG8_BAR; PG8_WAIT_L(0); PG8_MMA(0, 0, At, B0); PG8_BAR; PG8_SCHED;
;             PG8_LDB(B1, 0, 1); PG8_STAGE(PG8_SB(0, 0), b2, voffB);
;             PG8_BAR; PG8_WAIT_L(0); PG8_MMA(0, 1, At, B1); PG8_BAR;
;             PG8_LDA(At, 0, 1); PG8_STAGE(PG8_SA(0, 0), a2, voffA);
;             PG8_BAR; PG8_WAIT_L(0); PG8_MMA(1, 0, At, B0); PG8_BAR; PG8_SCHED;
;             PG8_STAGE(PG8_SB(0, 1), b2 + hstep, voffB);
;             PG8_WAIT_V(6); PG8_BAR; PG8_MMA(1, 1, At, B1); PG8_BAR;
.LBB0_195:
	s_add_i32 vcc_lo, s44, 2
	s_add_u32 s52, s4, 0x80
	s_addc_u32 s45, s5, 0
	s_add_u32 s100, s4, s38
	s_addc_u32 s101, s5, 0
	ds_read_b128 v[58:61], v249
	ds_read_b128 v[62:65], v249 offset:1024
	ds_read_b128 v[70:73], v249 offset:2048
	ds_read_b128 v[74:77], v249 offset:3072
	s_cmp_eq_u32 s75, s44
	s_cselect_b32 s44, s68, s52
	s_cselect_b32 s45, s69, s45
	s_cselect_b32 s53, s47, s90
	s_cselect_b32 s52, s46, s89
	s_add_i32 m0, s21, 0xc000
	ds_read_b128 v[138:141], v196
	ds_read_b128 v[142:145], v196 offset:1024
	ds_read_b128 v[146:149], v196 offset:2048
	ds_read_b128 v[150:153], v196 offset:3072
	ds_read_b128 v[162:165], v196 offset:4096
	ds_read_b128 v[166:169], v196 offset:5120
	ds_read_b128 v[170:173], v196 offset:6144
	global_load_lds_dwordx4 v0, s[100:101]
	s_add_i32 m0, s21, 0xe000
	ds_read_b128 v[184:187], v196 offset:7168
	global_load_lds_dwordx4 v174, s[100:101]
	s_waitcnt lgkmcnt(8)
	s_barrier
	s_waitcnt lgkmcnt(0)
	v_mfma_f32_16x16x32_bf16 v[158:161], v[58:61], v[138:141], v[158:161]
	v_mfma_f32_16x16x32_bf16 v[154:157], v[70:73], v[138:141], v[154:157]
	v_mfma_f32_16x16x32_bf16 v[126:129], v[58:61], v[146:149], v[126:129]
	v_mfma_f32_16x16x32_bf16 v[122:125], v[70:73], v[146:149], v[122:125]
	v_mfma_f32_16x16x32_bf16 v[110:113], v[58:61], v[162:165], v[110:113]
	v_mfma_f32_16x16x32_bf16 v[106:109], v[70:73], v[162:165], v[106:109]
	v_mfma_f32_16x16x32_bf16 v[94:97], v[58:61], v[170:173], v[94:97]
	v_mfma_f32_16x16x32_bf16 v[90:93], v[70:73], v[170:173], v[90:93]
	v_mfma_f32_16x16x32_bf16 v[158:161], v[62:65], v[142:145], v[158:161]
	v_mfma_f32_16x16x32_bf16 v[154:157], v[74:77], v[142:145], v[154:157]
	v_mfma_f32_16x16x32_bf16 v[126:129], v[62:65], v[150:153], v[126:129]
	v_mfma_f32_16x16x32_bf16 v[122:125], v[74:77], v[150:153], v[122:125]
	v_mfma_f32_16x16x32_bf16 v[110:113], v[62:65], v[166:169], v[110:113]
	v_mfma_f32_16x16x32_bf16 v[106:109], v[74:77], v[166:169], v[106:109]
	v_mfma_f32_16x16x32_bf16 v[94:97], v[62:65], v[184:187], v[94:97]
	v_mfma_f32_16x16x32_bf16 v[90:93], v[74:77], v[184:187], v[90:93]
	s_barrier
	ds_read_b128 v[188:191], v249 offset:16384
	ds_read_b128 v[220:223], v249 offset:17408
	ds_read_b128 v[224:227], v249 offset:18432
	ds_read_b128 v[228:231], v249 offset:19456
	s_add_u32 s98, s52, 0x80
	s_addc_u32 s99, s53, 0
	s_add_i32 m0, s20, 0x10000
	s_nop 0
	global_load_lds_dwordx4 v0, s[52:53]
	s_add_i32 m0, s20, 0x12000
	s_nop 0
	global_load_lds_dwordx4 v174, s[52:53]
	s_barrier
	s_waitcnt lgkmcnt(0)
	v_mfma_f32_16x16x32_bf16 v[134:137], v[188:191], v[138:141], v[134:137]
	v_mfma_f32_16x16x32_bf16 v[130:133], v[224:227], v[138:141], v[130:133]
	v_mfma_f32_16x16x32_bf16 v[118:121], v[188:191], v[146:149], v[118:121]
	v_mfma_f32_16x16x32_bf16 v[114:117], v[224:227], v[146:149], v[114:117]
	v_mfma_f32_16x16x32_bf16 v[102:105], v[188:191], v[162:165], v[102:105]
	v_mfma_f32_16x16x32_bf16 v[98:101], v[224:227], v[162:165], v[98:101]
	v_mfma_f32_16x16x32_bf16 v[86:89], v[188:191], v[170:173], v[86:89]
	v_mfma_f32_16x16x32_bf16 v[82:85], v[224:227], v[170:173], v[82:85]
	v_mfma_f32_16x16x32_bf16 v[134:137], v[220:223], v[142:145], v[134:137]
	v_mfma_f32_16x16x32_bf16 v[130:133], v[228:231], v[142:145], v[130:133]
	v_mfma_f32_16x16x32_bf16 v[118:121], v[220:223], v[150:153], v[118:121]
	v_mfma_f32_16x16x32_bf16 v[114:117], v[228:231], v[150:153], v[114:117]
	v_mfma_f32_16x16x32_bf16 v[102:105], v[220:223], v[166:169], v[102:105]
	v_mfma_f32_16x16x32_bf16 v[98:101], v[228:231], v[166:169], v[98:101]
	v_mfma_f32_16x16x32_bf16 v[86:89], v[220:223], v[184:187], v[86:89]
	v_mfma_f32_16x16x32_bf16 v[82:85], v[228:231], v[184:187], v[82:85]
	s_barrier
	s_mov_b32 m0, s21
	s_add_u32 s100, s44, 0x80
	s_addc_u32 s101, s45, 0
	ds_read_b128 v[138:141], v196 offset:16384
	ds_read_b128 v[142:145], v196 offset:17408
	ds_read_b128 v[146:149], v196 offset:18432
	ds_read_b128 v[150:153], v196 offset:19456
	ds_read_b128 v[162:165], v196 offset:20480
	ds_read_b128 v[166:169], v196 offset:21504
	ds_read_b128 v[170:173], v196 offset:22528
	global_load_lds_dwordx4 v0, s[44:45]
	s_mov_b32 m0, s50
	ds_read_b128 v[184:187], v196 offset:23552
	global_load_lds_dwordx4 v174, s[44:45]
	s_barrier
	s_waitcnt lgkmcnt(0)
	v_mfma_f32_16x16x32_bf16 v[78:81], v[58:61], v[138:141], v[78:81]
	v_mfma_f32_16x16x32_bf16 v[66:69], v[70:73], v[138:141], v[66:69]
	v_mfma_f32_16x16x32_bf16 v[46:49], v[58:61], v[146:149], v[46:49]
	v_mfma_f32_16x16x32_bf16 v[42:45], v[70:73], v[146:149], v[42:45]
	v_mfma_f32_16x16x32_bf16 v[30:33], v[58:61], v[162:165], v[30:33]
	v_mfma_f32_16x16x32_bf16 v[26:29], v[70:73], v[162:165], v[26:29]
	v_mfma_f32_16x16x32_bf16 v[14:17], v[58:61], v[170:173], v[14:17]
	v_mfma_f32_16x16x32_bf16 v[10:13], v[70:73], v[170:173], v[10:13]
	v_mfma_f32_16x16x32_bf16 v[78:81], v[62:65], v[142:145], v[78:81]
	v_mfma_f32_16x16x32_bf16 v[66:69], v[74:77], v[142:145], v[66:69]
	v_mfma_f32_16x16x32_bf16 v[46:49], v[62:65], v[150:153], v[46:49]
	v_mfma_f32_16x16x32_bf16 v[42:45], v[74:77], v[150:153], v[42:45]
	v_mfma_f32_16x16x32_bf16 v[30:33], v[62:65], v[166:169], v[30:33]
	v_mfma_f32_16x16x32_bf16 v[26:29], v[74:77], v[166:169], v[26:29]
	v_mfma_f32_16x16x32_bf16 v[14:17], v[62:65], v[184:187], v[14:17]
	v_mfma_f32_16x16x32_bf16 v[10:13], v[74:77], v[184:187], v[10:13]
	s_barrier
	s_add_u32 s52, s52, s38
	s_addc_u32 s53, s53, 0
	s_add_i32 m0, s20, 0x14000
	s_nop 0
	global_load_lds_dwordx4 v0, s[52:53]
	s_add_i32 m0, s20, 0x16000
	s_nop 0
	global_load_lds_dwordx4 v174, s[52:53]
	s_waitcnt vmcnt(6)
	s_barrier
; #define PG8_STAGE(bufoff, gbase, voff) do { _Pragma("unroll") for (int _i = 0; _i < 2; ++_i) \
;         __builtin_amdgcn_global_load_lds((const unsigned*)((const char*)(gbase) + (voff)[_i]), (LAS unsigned*)(lds + (bufoff) + ldsw + _i * 8192), 16, 0, 0); } while (0)
; #define PG8_LDA(dst, b, h) do { _Pragma("unroll") for (int m = 0; m < 4; ++m) _Pragma("unroll") for (int k = 0; k < 2; ++k) dst[m][k] = *(const LAS bf16x8*)(lds + PG8_SA(b, h) + aoff + m * 2048 + k * 1024); } while (0)
; #define PG8_LDB(dst, b, h) do { _Pragma("unroll") for (int n = 0; n < 2; ++n) _Pragma("unroll") for (int k = 0; k < 2; ++k) dst[n][k] = *(const LAS bf16x8*)(lds + PG8_SB(b, h) + boff + n * 2048 + k * 1024); } while (0)
; #define PG8_MMA(ai, bj, At, Bt) do { __builtin_amdgcn_s_setprio(1); _Pragma("unroll") for (int m = 0; m < 4; ++m) _Pragma("unroll") for (int n = 0; n < 2; ++n) _Pragma("unroll") for (int k = 0; k < 2; ++k) \
;         acc[ai][bj][m][n] = __builtin_amdgcn_mfma_f32_16x16x32_bf16(Bt[n][k], At[m][k], acc[ai][bj][m][n], 0, 0, 0); __builtin_amdgcn_s_setprio(0); } while (0)
; #define PG8_WAIT_V(n) asm volatile("s_waitcnt vmcnt(" #n ")" ::: "memory")
; #define PG8_WAIT_L(n) asm volatile("s_waitcnt lgkmcnt(" #n ")" ::: "memory")
; #define PG8_BAR __builtin_amdgcn_s_barrier()
; #define PG8_SCHED __builtin_amdgcn_sched_barrier(0)
; template <int MODE, class EpiT, class Sched>
; __device__ __forceinline__ void gemm_phase(LAS unsigned char* lds, const Gemm g, const Sched& S, const EpiT& E) {
;     ...
;             PG8_WAIT_V(6); PG8_BAR; PG8_MMA(1, 1, At, B1); PG8_BAR;
;             PG8_LDB(B0, 1, 0); PG8_SCHED; PG8_LDA(At, 1, 0); PG8_STAGE(PG8_SA(0, 1), a2 + hstep, voffA);
;             PG8_WAIT_L(8); PG8_BAR; PG8_WAIT_L(0); PG8_MMA(0, 0, At, B0); PG8_BAR; PG8_SCHED;
;             PG8_LDB(B1, 1, 1); PG8_STAGE(PG8_SB(1, 0), b3, voffB);
;             PG8_BAR; PG8_WAIT_L(0); PG8_MMA(0, 1, At, B1); PG8_BAR;
	v_mfma_f32_16x16x32_bf16 v[54:57], v[188:191], v[138:141], v[54:57]
	v_mfma_f32_16x16x32_bf16 v[50:53], v[224:227], v[138:141], v[50:53]
	v_mfma_f32_16x16x32_bf16 v[38:41], v[188:191], v[146:149], v[38:41]
	v_mfma_f32_16x16x32_bf16 v[34:37], v[224:227], v[146:149], v[34:37]
	v_mfma_f32_16x16x32_bf16 v[22:25], v[188:191], v[162:165], v[22:25]
	v_mfma_f32_16x16x32_bf16 v[18:21], v[224:227], v[162:165], v[18:21]
	v_mfma_f32_16x16x32_bf16 v[6:9], v[188:191], v[170:173], v[6:9]
	v_mfma_f32_16x16x32_bf16 v[2:5], v[224:227], v[170:173], v[2:5]
	v_mfma_f32_16x16x32_bf16 v[54:57], v[220:223], v[142:145], v[54:57]
	v_mfma_f32_16x16x32_bf16 v[50:53], v[228:231], v[142:145], v[50:53]
	v_mfma_f32_16x16x32_bf16 v[38:41], v[220:223], v[150:153], v[38:41]
	v_mfma_f32_16x16x32_bf16 v[34:37], v[228:231], v[150:153], v[34:37]
	v_mfma_f32_16x16x32_bf16 v[22:25], v[220:223], v[166:169], v[22:25]
	v_mfma_f32_16x16x32_bf16 v[18:21], v[228:231], v[166:169], v[18:21]
	v_mfma_f32_16x16x32_bf16 v[6:9], v[220:223], v[184:187], v[6:9]
	v_mfma_f32_16x16x32_bf16 v[2:5], v[228:231], v[184:187], v[2:5]
	s_barrier
	ds_read_b128 v[58:61], v249 offset:32768
	ds_read_b128 v[62:65], v249 offset:33792
	ds_read_b128 v[70:73], v249 offset:34816
	ds_read_b128 v[74:77], v249 offset:35840
	s_add_u32 s44, s44, s38
	s_addc_u32 s45, s45, 0
	s_mov_b32 m0, s51
	ds_read_b128 v[138:141], v196 offset:32768
	ds_read_b128 v[142:145], v196 offset:33792
	ds_read_b128 v[146:149], v196 offset:34816
	ds_read_b128 v[150:153], v196 offset:35840
	ds_read_b128 v[162:165], v196 offset:36864
	ds_read_b128 v[166:169], v196 offset:37888
	ds_read_b128 v[170:173], v196 offset:38912
	global_load_lds_dwordx4 v0, s[44:45]
	s_mov_b32 m0, s56
	ds_read_b128 v[184:187], v196 offset:39936
	global_load_lds_dwordx4 v174, s[44:45]
	s_waitcnt lgkmcnt(8)
	s_barrier
	s_waitcnt lgkmcnt(0)
	v_mfma_f32_16x16x32_bf16 v[158:161], v[58:61], v[138:141], v[158:161]
	v_mfma_f32_16x16x32_bf16 v[154:157], v[70:73], v[138:141], v[154:157]
	v_mfma_f32_16x16x32_bf16 v[126:129], v[58:61], v[146:149], v[126:129]
	v_mfma_f32_16x16x32_bf16 v[122:125], v[70:73], v[146:149], v[122:125]
	v_mfma_f32_16x16x32_bf16 v[110:113], v[58:61], v[162:165], v[110:113]
	v_mfma_f32_16x16x32_bf16 v[106:109], v[70:73], v[162:165], v[106:109]
	v_mfma_f32_16x16x32_bf16 v[94:97], v[58:61], v[170:173], v[94:97]
	v_mfma_f32_16x16x32_bf16 v[90:93], v[70:73], v[170:173], v[90:93]
	v_mfma_f32_16x16x32_bf16 v[158:161], v[62:65], v[142:145], v[158:161]
	v_mfma_f32_16x16x32_bf16 v[154:157], v[74:77], v[142:145], v[154:157]
	v_mfma_f32_16x16x32_bf16 v[126:129], v[62:65], v[150:153], v[126:129]
	v_mfma_f32_16x16x32_bf16 v[122:125], v[74:77], v[150:153], v[122:125]
	v_mfma_f32_16x16x32_bf16 v[110:113], v[62:65], v[166:169], v[110:113]
	v_mfma_f32_16x16x32_bf16 v[106:109], v[74:77], v[166:169], v[106:109]
	v_mfma_f32_16x16x32_bf16 v[94:97], v[62:65], v[184:187], v[94:97]
	v_mfma_f32_16x16x32_bf16 v[90:93], v[74:77], v[184:187], v[90:93]
	s_barrier
	s_add_i32 m0, s20, 0x18000
	ds_read_b128 v[188:191], v249 offset:49152
	ds_read_b128 v[220:223], v249 offset:50176
	ds_read_b128 v[224:227], v249 offset:51200
	global_load_lds_dwordx4 v0, s[98:99]
	s_add_i32 m0, s20, 0x1a000
	ds_read_b128 v[228:231], v249 offset:52224
	global_load_lds_dwordx4 v174, s[98:99]
	s_barrier
	s_waitcnt lgkmcnt(0)
	v_mfma_f32_16x16x32_bf16 v[134:137], v[188:191], v[138:141], v[134:137]
	v_mfma_f32_16x16x32_bf16 v[130:133], v[224:227], v[138:141], v[130:133]
	v_mfma_f32_16x16x32_bf16 v[118:121], v[188:191], v[146:149], v[118:121]
	v_mfma_f32_16x16x32_bf16 v[114:117], v[224:227], v[146:149], v[114:117]
	v_mfma_f32_16x16x32_bf16 v[102:105], v[188:191], v[162:165], v[102:105]
	v_mfma_f32_16x16x32_bf16 v[98:101], v[224:227], v[162:165], v[98:101]
	v_mfma_f32_16x16x32_bf16 v[86:89], v[188:191], v[170:173], v[86:89]
	v_mfma_f32_16x16x32_bf16 v[82:85], v[224:227], v[170:173], v[82:85]
	v_mfma_f32_16x16x32_bf16 v[134:137], v[220:223], v[142:145], v[134:137]
	v_mfma_f32_16x16x32_bf16 v[130:133], v[228:231], v[142:145], v[130:133]
	v_mfma_f32_16x16x32_bf16 v[118:121], v[220:223], v[150:153], v[118:121]
	v_mfma_f32_16x16x32_bf16 v[114:117], v[228:231], v[150:153], v[114:117]
	v_mfma_f32_16x16x32_bf16 v[102:105], v[220:223], v[166:169], v[102:105]
	v_mfma_f32_16x16x32_bf16 v[98:101], v[228:231], v[166:169], v[98:101]
	v_mfma_f32_16x16x32_bf16 v[86:89], v[220:223], v[184:187], v[86:89]
	v_mfma_f32_16x16x32_bf16 v[82:85], v[228:231], v[184:187], v[82:85]
	s_barrier
; #define PG8_STAGE(bufoff, gbase, voff) do { _Pragma("unroll") for (int _i = 0; _i < 2; ++_i) \
;         __builtin_amdgcn_global_load_lds((const unsigned*)((const char*)(gbase) + (voff)[_i]), (LAS unsigned*)(lds + (bufoff) + ldsw + _i * 8192), 16, 0, 0); } while (0)
; #define PG8_LDA(dst, b, h) do { _Pragma("unroll") for (int m = 0; m < 4; ++m) _Pragma("unroll") for (int k = 0; k < 2; ++k) dst[m][k] = *(const LAS bf16x8*)(lds + PG8_SA(b, h) + aoff + m * 2048 + k * 1024); } while (0)
; #define PG8_MMA(ai, bj, At, Bt) do { __builtin_amdgcn_s_setprio(1); _Pragma("unroll") for (int m = 0; m < 4; ++m) _Pragma("unroll") for (int n = 0; n < 2; ++n) _Pragma("unroll") for (int k = 0; k < 2; ++k) \
;         acc[ai][bj][m][n] = __builtin_amdgcn_mfma_f32_16x16x32_bf16(Bt[n][k], At[m][k], acc[ai][bj][m][n], 0, 0, 0); __builtin_amdgcn_s_setprio(0); } while (0)
; #define PG8_WAIT_V(n) asm volatile("s_waitcnt vmcnt(" #n ")" ::: "memory")
; #define PG8_WAIT_L(n) asm volatile("s_waitcnt lgkmcnt(" #n ")" ::: "memory")
; #define PG8_BAR __builtin_amdgcn_s_barrier()
; #define PG8_SCHED __builtin_amdgcn_sched_barrier(0)
;     template <int mode> __device__ __forceinline__ void run(const f32x4 (&acc)[2][2][4][2], const Unit& u, int wr, int wc, int fr, int fq, const LAS float* sc) const {
;     ...
;             f32x4 bvv[4];
; #pragma unroll
;             for (int q = 0; q < 4; ++q) bvv[q] = (mode != 4 && bias) ? *(const f32x4*)(bias + col0 + (q >> 1) * HALF + (q & 1) * 4) : (f32x4){0.f, 0.f, 0.f, 0.f};
; template <int MODE, class EpiT, class Sched>
; __device__ __forceinline__ void gemm_phase(LAS unsigned char* lds, const Gemm g, const Sched& S, const EpiT& E) {
;     ...
;             PG8_LDA(At, 1, 1); PG8_STAGE(PG8_SA(1, 0), a3, voffA);
;             PG8_BAR; PG8_WAIT_L(0); PG8_MMA(1, 0, At, B0); PG8_BAR; PG8_SCHED;
;             PG8_STAGE(PG8_SB(1, 1), b3 + hstep, voffB);
;             PG8_WAIT_V(6); PG8_BAR; PG8_MMA(1, 1, At, B1); PG8_BAR;
;         }
	s_mov_b32 m0, s61
	ds_read_b128 v[138:141], v196 offset:49152
	ds_read_b128 v[142:145], v196 offset:50176
	ds_read_b128 v[146:149], v196 offset:51200
	ds_read_b128 v[150:153], v196 offset:52224
	ds_read_b128 v[162:165], v196 offset:53248
	ds_read_b128 v[166:169], v196 offset:54272
	ds_read_b128 v[170:173], v196 offset:55296
	global_load_lds_dwordx4 v0, s[100:101]
	s_mov_b32 m0, s74
	ds_read_b128 v[184:187], v196 offset:56320
	global_load_lds_dwordx4 v174, s[100:101]
	s_barrier
	s_waitcnt lgkmcnt(0)
	v_mfma_f32_16x16x32_bf16 v[78:81], v[58:61], v[138:141], v[78:81]
	v_mfma_f32_16x16x32_bf16 v[66:69], v[70:73], v[138:141], v[66:69]
	v_mfma_f32_16x16x32_bf16 v[46:49], v[58:61], v[146:149], v[46:49]
	v_mfma_f32_16x16x32_bf16 v[42:45], v[70:73], v[146:149], v[42:45]
	v_mfma_f32_16x16x32_bf16 v[30:33], v[58:61], v[162:165], v[30:33]
	v_mfma_f32_16x16x32_bf16 v[26:29], v[70:73], v[162:165], v[26:29]
	v_mfma_f32_16x16x32_bf16 v[14:17], v[58:61], v[170:173], v[14:17]
	v_mfma_f32_16x16x32_bf16 v[10:13], v[70:73], v[170:173], v[10:13]
	v_mfma_f32_16x16x32_bf16 v[78:81], v[62:65], v[142:145], v[78:81]
	v_mfma_f32_16x16x32_bf16 v[66:69], v[74:77], v[142:145], v[66:69]
	v_mfma_f32_16x16x32_bf16 v[46:49], v[62:65], v[150:153], v[46:49]
	v_mfma_f32_16x16x32_bf16 v[42:45], v[74:77], v[150:153], v[42:45]
	v_mfma_f32_16x16x32_bf16 v[30:33], v[62:65], v[166:169], v[30:33]
	v_mfma_f32_16x16x32_bf16 v[26:29], v[74:77], v[166:169], v[26:29]
	v_mfma_f32_16x16x32_bf16 v[14:17], v[62:65], v[184:187], v[14:17]
	v_mfma_f32_16x16x32_bf16 v[10:13], v[74:77], v[184:187], v[10:13]
	s_barrier
	s_add_u32 s98, s98, s38
	s_addc_u32 s99, s99, 0
	s_add_i32 m0, s20, 0x1c000
	s_nop 0
	global_load_lds_dwordx4 v0, s[98:99]
	s_add_i32 m0, s20, 0x1e000
	s_nop 0
	global_load_lds_dwordx4 v174, s[98:99]
	s_waitcnt vmcnt(6)
	s_barrier
	v_mfma_f32_16x16x32_bf16 v[54:57], v[188:191], v[138:141], v[54:57]
	v_mfma_f32_16x16x32_bf16 v[50:53], v[224:227], v[138:141], v[50:53]
	v_mfma_f32_16x16x32_bf16 v[38:41], v[188:191], v[146:149], v[38:41]
	v_mfma_f32_16x16x32_bf16 v[34:37], v[224:227], v[146:149], v[34:37]
	v_mfma_f32_16x16x32_bf16 v[22:25], v[188:191], v[162:165], v[22:25]
	v_mfma_f32_16x16x32_bf16 v[18:21], v[224:227], v[162:165], v[18:21]
	v_mfma_f32_16x16x32_bf16 v[6:9], v[188:191], v[170:173], v[6:9]
	v_mfma_f32_16x16x32_bf16 v[2:5], v[224:227], v[170:173], v[2:5]
	v_mfma_f32_16x16x32_bf16 v[54:57], v[220:223], v[142:145], v[54:57]
	v_mfma_f32_16x16x32_bf16 v[50:53], v[228:231], v[142:145], v[50:53]
	v_mfma_f32_16x16x32_bf16 v[38:41], v[220:223], v[150:153], v[38:41]
	v_mfma_f32_16x16x32_bf16 v[34:37], v[228:231], v[150:153], v[34:37]
	v_mfma_f32_16x16x32_bf16 v[22:25], v[220:223], v[166:169], v[22:25]
	v_mfma_f32_16x16x32_bf16 v[18:21], v[228:231], v[166:169], v[18:21]
	v_mfma_f32_16x16x32_bf16 v[6:9], v[220:223], v[184:187], v[6:9]
	v_mfma_f32_16x16x32_bf16 v[2:5], v[228:231], v[184:187], v[2:5]
	s_barrier
	s_add_u32 s4, s4, 0x100
	s_addc_u32 s5, s5, 0
	s_add_u32 s89, s89, 0x100
	s_addc_u32 s90, s90, 0
	s_cmp_ge_u32 vcc_lo, s60
	s_mov_b32 s44, vcc_lo
	s_cbranch_scc0 .LBB0_195
	v_lshl_or_b32 v186, s24, 8, v195
	v_ashrrev_i32_e32 v187, 31, v186
	v_mov_b32_e32 v70, 0
	v_cndmask_b32_e64 v58, 0, 1, s[78:79]
	v_lshl_add_u64 v[138:139], v[186:187], 2, s[12:13]
	v_cmp_ne_u32_e64 s[44:45], 1, v58
	s_andn2_b64 vcc, exec, s[78:79]
	v_mov_b32_e32 v74, 0
	v_mov_b32_e32 v75, v70
	v_mov_b32_e32 v184, 0
	v_mov_b32_e32 v185, v70
	s_cbranch_vccnz .LBB0_198
	global_load_dwordx4 v[74:77], v[138:139], off
	s_waitcnt vmcnt(0)
	v_mov_b32_e32 v184, v76
	v_mov_b32_e32 v185, v77

; #define PG8_STAGE(bufoff, gbase, voff) do { _Pragma("unroll") for (int _i = 0; _i < 2; ++_i) \
;         __builtin_amdgcn_global_load_lds((const unsigned*)((const char*)(gbase) + (voff)[_i]), (LAS unsigned*)(lds + (bufoff) + ldsw + _i * 8192), 16, 0, 0); } while (0)
; #define PG8_LDA(dst, b, h) do { _Pragma("unroll") for (int m = 0; m < 4; ++m) _Pragma("unroll") for (int k = 0; k < 2; ++k) dst[m][k] = *(const LAS bf16x8*)(lds + PG8_SA(b, h) + aoff + m * 2048 + k * 1024); } while (0)
; #define PG8_LDB(dst, b, h) do { _Pragma("unroll") for (int n = 0; n < 2; ++n) _Pragma("unroll") for (int k = 0; k < 2; ++k) dst[n][k] = *(const LAS bf16x8*)(lds + PG8_SB(b, h) + boff + n * 2048 + k * 1024); } while (0)
; #define PG8_MMA(ai, bj, At, Bt) do { __builtin_amdgcn_s_setprio(1); _Pragma("unroll") for (int m = 0; m < 4; ++m) _Pragma("unroll") for (int n = 0; n < 2; ++n) _Pragma("unroll") for (int k = 0; k < 2; ++k) \
;         acc[ai][bj][m][n] = __builtin_amdgcn_mfma_f32_16x16x32_bf16(Bt[n][k], At[m][k], acc[ai][bj][m][n], 0, 0, 0); __builtin_amdgcn_s_setprio(0); } while (0)
; #define PG8_WAIT_L(n) asm volatile("s_waitcnt lgkmcnt(" #n ")" ::: "memory")
; #define PG8_BAR __builtin_amdgcn_s_barrier()
; #define PG8_SCHED __builtin_amdgcn_sched_barrier(0)
; template <int MODE, class EpiT, class Sched>
; __device__ __forceinline__ void gemm_phase(LAS unsigned char* lds, const Gemm g, const Sched& S, const EpiT& E) {
;     ...
;             PG8_LDB(B0, 0, 0); PG8_SCHED; PG8_LDA(At, 0, 0); PG8_STAGE(PG8_SA(1, 1), a1 + hstep, voffA);
;             PG8_WAIT_L(8); PG8_BAR; PG8_WAIT_L(0); PG8_MMA(0, 0, At, B0); PG8_BAR; PG8_SCHED;
;             PG8_LDB(B1, 0, 1); PG8_STAGE(PG8_SB(0, 0), b2, voffB);
;             PG8_BAR; PG8_WAIT_L(0); PG8_MMA(0, 1, At, B1); PG8_BAR;
;             PG8_LDA(At, 0, 1); PG8_STAGE(PG8_SA(0, 0), a2, voffA);
;             PG8_BAR; PG8_WAIT_L(0); PG8_MMA(1, 0, At, B0); PG8_BAR; PG8_SCHED;
.LBB0_280:
	s_add_i32 s68, s46, 2
	s_add_u32 s52, s10, s44
	s_addc_u32 s47, s11, s45
	s_add_u32 s58, s4, s44
	s_addc_u32 s53, s5, s45
	s_add_u32 s100, s10, s44
	s_addc_u32 s101, s11, s45
	s_add_u32 s100, s100, s22
	s_addc_u32 s101, s101, 0
	s_sub_u32 s100, s100, 0x80
	s_subb_u32 s101, s101, 0
	s_add_i32 s59, 0, 0x10000
	ds_read_b128 v[134:137], v250
	ds_read_b128 v[138:141], v250 offset:1024
	ds_read_b128 v[142:145], v250 offset:2048
	ds_read_b128 v[152:155], v250 offset:3072
	s_cmp_eq_u32 s60, s46
	s_cselect_b32 s46, s34, s52
	s_cselect_b32 s47, s35, s47
	s_cselect_b32 s53, s39, s53
	s_cselect_b32 s52, s38, s58
	s_add_i32 m0, s30, 0xc000
	ds_read_b128 v[162:165], v160
	ds_read_b128 v[166:169], v160 offset:1024
	ds_read_b128 v[170:173], v160 offset:2048
	ds_read_b128 v[174:177], v160 offset:3072
	ds_read_b128 v[182:185], v160 offset:4096
	ds_read_b128 v[186:189], v160 offset:5120
	ds_read_b128 v[190:193], v160 offset:6144
	global_load_lds_dwordx4 v0, s[100:101]
	s_add_i32 m0, s30, 0xe000
	ds_read_b128 v[194:197], v160 offset:7168
	global_load_lds_dwordx4 v146, s[100:101]
	s_waitcnt lgkmcnt(8)
	s_barrier
	s_waitcnt lgkmcnt(0)
	v_mfma_f32_16x16x32_bf16 v[126:129], v[134:137], v[162:165], v[126:129]
	v_mfma_f32_16x16x32_bf16 v[122:125], v[142:145], v[162:165], v[122:125]
	v_mfma_f32_16x16x32_bf16 v[118:121], v[134:137], v[170:173], v[118:121]
	v_mfma_f32_16x16x32_bf16 v[114:117], v[142:145], v[170:173], v[114:117]
	v_mfma_f32_16x16x32_bf16 v[110:113], v[134:137], v[182:185], v[110:113]
	v_mfma_f32_16x16x32_bf16 v[106:109], v[142:145], v[182:185], v[106:109]
	v_mfma_f32_16x16x32_bf16 v[102:105], v[134:137], v[190:193], v[102:105]
	v_mfma_f32_16x16x32_bf16 v[98:101], v[142:145], v[190:193], v[98:101]
	v_mfma_f32_16x16x32_bf16 v[126:129], v[138:141], v[166:169], v[126:129]
	v_mfma_f32_16x16x32_bf16 v[122:125], v[152:155], v[166:169], v[122:125]
	v_mfma_f32_16x16x32_bf16 v[118:121], v[138:141], v[174:177], v[118:121]
	v_mfma_f32_16x16x32_bf16 v[114:117], v[152:155], v[174:177], v[114:117]
	v_mfma_f32_16x16x32_bf16 v[110:113], v[138:141], v[186:189], v[110:113]
	v_mfma_f32_16x16x32_bf16 v[106:109], v[152:155], v[186:189], v[106:109]
	v_mfma_f32_16x16x32_bf16 v[102:105], v[138:141], v[194:197], v[102:105]
	v_mfma_f32_16x16x32_bf16 v[98:101], v[152:155], v[194:197], v[98:101]
	s_barrier
	s_add_i32 s58, 0, 0x14000
	s_add_i32 s59, s59, s24
	s_add_u32 s98, s52, 0x80
	s_addc_u32 s99, s53, 0
	s_mov_b32 m0, s59
	ds_read_b128 v[220:223], v250 offset:16384
	ds_read_b128 v[224:227], v250 offset:17408
	ds_read_b128 v[228:231], v250 offset:18432
	global_load_lds_dwordx4 v0, s[52:53]
	s_add_i32 m0, s59, 0x2000
	ds_read_b128 v[232:235], v250 offset:19456
	global_load_lds_dwordx4 v146, s[52:53]
	s_barrier
	s_waitcnt lgkmcnt(0)
	v_mfma_f32_16x16x32_bf16 v[94:97], v[220:223], v[162:165], v[94:97]
	v_mfma_f32_16x16x32_bf16 v[90:93], v[228:231], v[162:165], v[90:93]
	v_mfma_f32_16x16x32_bf16 v[86:89], v[220:223], v[170:173], v[86:89]
	v_mfma_f32_16x16x32_bf16 v[82:85], v[228:231], v[170:173], v[82:85]
	v_mfma_f32_16x16x32_bf16 v[78:81], v[220:223], v[182:185], v[78:81]
	v_mfma_f32_16x16x32_bf16 v[74:77], v[228:231], v[182:185], v[74:77]
	v_mfma_f32_16x16x32_bf16 v[70:73], v[220:223], v[190:193], v[70:73]
	v_mfma_f32_16x16x32_bf16 v[66:69], v[228:231], v[190:193], v[66:69]
	v_mfma_f32_16x16x32_bf16 v[94:97], v[224:227], v[166:169], v[94:97]
	v_mfma_f32_16x16x32_bf16 v[90:93], v[232:235], v[166:169], v[90:93]
	v_mfma_f32_16x16x32_bf16 v[86:89], v[224:227], v[174:177], v[86:89]
	v_mfma_f32_16x16x32_bf16 v[82:85], v[232:235], v[174:177], v[82:85]
	v_mfma_f32_16x16x32_bf16 v[78:81], v[224:227], v[186:189], v[78:81]
	v_mfma_f32_16x16x32_bf16 v[74:77], v[232:235], v[186:189], v[74:77]
	v_mfma_f32_16x16x32_bf16 v[70:73], v[224:227], v[194:197], v[70:73]
	v_mfma_f32_16x16x32_bf16 v[66:69], v[232:235], v[194:197], v[66:69]
	s_barrier
	s_mov_b32 m0, s30
	s_add_u32 s100, s46, 0x80
	s_addc_u32 s101, s47, 0
	ds_read_b128 v[162:165], v160 offset:16384
	ds_read_b128 v[166:169], v160 offset:17408
	ds_read_b128 v[170:173], v160 offset:18432
	ds_read_b128 v[174:177], v160 offset:19456
	ds_read_b128 v[182:185], v160 offset:20480
	ds_read_b128 v[186:189], v160 offset:21504
	ds_read_b128 v[190:193], v160 offset:22528
	global_load_lds_dwordx4 v0, s[46:47]
	s_mov_b32 m0, s50
	ds_read_b128 v[194:197], v160 offset:23552
	global_load_lds_dwordx4 v146, s[46:47]
	s_barrier
	s_waitcnt lgkmcnt(0)
	v_mfma_f32_16x16x32_bf16 v[62:65], v[134:137], v[162:165], v[62:65]
	v_mfma_f32_16x16x32_bf16 v[58:61], v[142:145], v[162:165], v[58:61]
	v_mfma_f32_16x16x32_bf16 v[54:57], v[134:137], v[170:173], v[54:57]
	v_mfma_f32_16x16x32_bf16 v[50:53], v[142:145], v[170:173], v[50:53]
	v_mfma_f32_16x16x32_bf16 v[46:49], v[134:137], v[182:185], v[46:49]
	v_mfma_f32_16x16x32_bf16 v[42:45], v[142:145], v[182:185], v[42:45]
	v_mfma_f32_16x16x32_bf16 v[38:41], v[134:137], v[190:193], v[38:41]
	v_mfma_f32_16x16x32_bf16 v[34:37], v[142:145], v[190:193], v[34:37]
	v_mfma_f32_16x16x32_bf16 v[62:65], v[138:141], v[166:169], v[62:65]
	v_mfma_f32_16x16x32_bf16 v[58:61], v[152:155], v[166:169], v[58:61]
	v_mfma_f32_16x16x32_bf16 v[54:57], v[138:141], v[174:177], v[54:57]
	v_mfma_f32_16x16x32_bf16 v[50:53], v[152:155], v[174:177], v[50:53]
	v_mfma_f32_16x16x32_bf16 v[46:49], v[138:141], v[186:189], v[46:49]
	v_mfma_f32_16x16x32_bf16 v[42:45], v[152:155], v[186:189], v[42:45]
	v_mfma_f32_16x16x32_bf16 v[38:41], v[138:141], v[194:197], v[38:41]
	v_mfma_f32_16x16x32_bf16 v[34:37], v[152:155], v[194:197], v[34:37]
	s_barrier
; #define PG8_STAGE(bufoff, gbase, voff) do { _Pragma("unroll") for (int _i = 0; _i < 2; ++_i) \
;         __builtin_amdgcn_global_load_lds((const unsigned*)((const char*)(gbase) + (voff)[_i]), (LAS unsigned*)(lds + (bufoff) + ldsw + _i * 8192), 16, 0, 0); } while (0)
; #define PG8_LDA(dst, b, h) do { _Pragma("unroll") for (int m = 0; m < 4; ++m) _Pragma("unroll") for (int k = 0; k < 2; ++k) dst[m][k] = *(const LAS bf16x8*)(lds + PG8_SA(b, h) + aoff + m * 2048 + k * 1024); } while (0)
; #define PG8_LDB(dst, b, h) do { _Pragma("unroll") for (int n = 0; n < 2; ++n) _Pragma("unroll") for (int k = 0; k < 2; ++k) dst[n][k] = *(const LAS bf16x8*)(lds + PG8_SB(b, h) + boff + n * 2048 + k * 1024); } while (0)
; #define PG8_MMA(ai, bj, At, Bt) do { __builtin_amdgcn_s_setprio(1); _Pragma("unroll") for (int m = 0; m < 4; ++m) _Pragma("unroll") for (int n = 0; n < 2; ++n) _Pragma("unroll") for (int k = 0; k < 2; ++k) \
;         acc[ai][bj][m][n] = __builtin_amdgcn_mfma_f32_16x16x32_bf16(Bt[n][k], At[m][k], acc[ai][bj][m][n], 0, 0, 0); __builtin_amdgcn_s_setprio(0); } while (0)
; #define PG8_WAIT_V(n) asm volatile("s_waitcnt vmcnt(" #n ")" ::: "memory")
; #define PG8_WAIT_L(n) asm volatile("s_waitcnt lgkmcnt(" #n ")" ::: "memory")
; #define PG8_BAR __builtin_amdgcn_s_barrier()
; #define PG8_SCHED __builtin_amdgcn_sched_barrier(0)
; template <int MODE, class EpiT, class Sched>
; __device__ __forceinline__ void gemm_phase(LAS unsigned char* lds, const Gemm g, const Sched& S, const EpiT& E) {
;     ...
;             PG8_STAGE(PG8_SB(0, 1), b2 + hstep, voffB);
;             PG8_WAIT_V(6); PG8_BAR; PG8_MMA(1, 1, At, B1); PG8_BAR;
;             PG8_LDB(B0, 1, 0); PG8_SCHED; PG8_LDA(At, 1, 0); PG8_STAGE(PG8_SA(0, 1), a2 + hstep, voffA);
;             PG8_WAIT_L(8); PG8_BAR; PG8_WAIT_L(0); PG8_MMA(0, 0, At, B0); PG8_BAR; PG8_SCHED;
;             PG8_LDB(B1, 1, 1); PG8_STAGE(PG8_SB(1, 0), b3, voffB);
;             PG8_BAR; PG8_WAIT_L(0); PG8_MMA(0, 1, At, B1); PG8_BAR;
	s_add_u32 s52, s52, s22
	s_addc_u32 s53, s53, 0
	s_add_i32 s58, s58, s24
	s_mov_b32 m0, s58
	s_nop 0
	global_load_lds_dwordx4 v0, s[52:53]
	s_add_i32 m0, s58, 0x2000
	s_nop 0
	global_load_lds_dwordx4 v146, s[52:53]
	s_waitcnt vmcnt(6)
	s_barrier
	v_mfma_f32_16x16x32_bf16 v[30:33], v[220:223], v[162:165], v[30:33]
	v_mfma_f32_16x16x32_bf16 v[26:29], v[228:231], v[162:165], v[26:29]
	v_mfma_f32_16x16x32_bf16 v[22:25], v[220:223], v[170:173], v[22:25]
	v_mfma_f32_16x16x32_bf16 v[18:21], v[228:231], v[170:173], v[18:21]
	v_mfma_f32_16x16x32_bf16 v[14:17], v[220:223], v[182:185], v[14:17]
	v_mfma_f32_16x16x32_bf16 v[10:13], v[228:231], v[182:185], v[10:13]
	v_mfma_f32_16x16x32_bf16 v[6:9], v[220:223], v[190:193], v[6:9]
	v_mfma_f32_16x16x32_bf16 v[2:5], v[228:231], v[190:193], v[2:5]
	v_mfma_f32_16x16x32_bf16 v[30:33], v[224:227], v[166:169], v[30:33]
	v_mfma_f32_16x16x32_bf16 v[26:29], v[232:235], v[166:169], v[26:29]
	v_mfma_f32_16x16x32_bf16 v[22:25], v[224:227], v[174:177], v[22:25]
	v_mfma_f32_16x16x32_bf16 v[18:21], v[232:235], v[174:177], v[18:21]
	v_mfma_f32_16x16x32_bf16 v[14:17], v[224:227], v[186:189], v[14:17]
	v_mfma_f32_16x16x32_bf16 v[10:13], v[232:235], v[186:189], v[10:13]
	v_mfma_f32_16x16x32_bf16 v[6:9], v[224:227], v[194:197], v[6:9]
	v_mfma_f32_16x16x32_bf16 v[2:5], v[232:235], v[194:197], v[2:5]
	s_barrier
	s_add_i32 s52, 0, 0x18000
	ds_read_b128 v[134:137], v250 offset:32768
	ds_read_b128 v[138:141], v250 offset:33792
	ds_read_b128 v[142:145], v250 offset:34816
	ds_read_b128 v[152:155], v250 offset:35840
	s_add_u32 s46, s46, s22
	s_addc_u32 s47, s47, 0
	s_mov_b32 m0, s51
	ds_read_b128 v[162:165], v160 offset:32768
	ds_read_b128 v[166:169], v160 offset:33792
	ds_read_b128 v[170:173], v160 offset:34816
	ds_read_b128 v[174:177], v160 offset:35840
	ds_read_b128 v[182:185], v160 offset:36864
	ds_read_b128 v[186:189], v160 offset:37888
	ds_read_b128 v[190:193], v160 offset:38912
	global_load_lds_dwordx4 v0, s[46:47]
	s_mov_b32 m0, s54
	ds_read_b128 v[194:197], v160 offset:39936
	global_load_lds_dwordx4 v146, s[46:47]
	s_waitcnt lgkmcnt(8)
	s_barrier
	s_waitcnt lgkmcnt(0)
	v_mfma_f32_16x16x32_bf16 v[126:129], v[134:137], v[162:165], v[126:129]
	v_mfma_f32_16x16x32_bf16 v[122:125], v[142:145], v[162:165], v[122:125]
	v_mfma_f32_16x16x32_bf16 v[118:121], v[134:137], v[170:173], v[118:121]
	v_mfma_f32_16x16x32_bf16 v[114:117], v[142:145], v[170:173], v[114:117]
	v_mfma_f32_16x16x32_bf16 v[110:113], v[134:137], v[182:185], v[110:113]
	v_mfma_f32_16x16x32_bf16 v[106:109], v[142:145], v[182:185], v[106:109]
	v_mfma_f32_16x16x32_bf16 v[102:105], v[134:137], v[190:193], v[102:105]
	v_mfma_f32_16x16x32_bf16 v[98:101], v[142:145], v[190:193], v[98:101]
	v_mfma_f32_16x16x32_bf16 v[126:129], v[138:141], v[166:169], v[126:129]
	v_mfma_f32_16x16x32_bf16 v[122:125], v[152:155], v[166:169], v[122:125]
	v_mfma_f32_16x16x32_bf16 v[118:121], v[138:141], v[174:177], v[118:121]
	v_mfma_f32_16x16x32_bf16 v[114:117], v[152:155], v[174:177], v[114:117]
	v_mfma_f32_16x16x32_bf16 v[110:113], v[138:141], v[186:189], v[110:113]
	v_mfma_f32_16x16x32_bf16 v[106:109], v[152:155], v[186:189], v[106:109]
	v_mfma_f32_16x16x32_bf16 v[102:105], v[138:141], v[194:197], v[102:105]
	v_mfma_f32_16x16x32_bf16 v[98:101], v[152:155], v[194:197], v[98:101]
	s_barrier
	s_add_i32 s46, 0, 0x1c000
	s_add_i32 s47, s52, s24
	s_mov_b32 m0, s47
	ds_read_b128 v[220:223], v250 offset:49152
	ds_read_b128 v[224:227], v250 offset:50176
	ds_read_b128 v[228:231], v250 offset:51200
	global_load_lds_dwordx4 v0, s[98:99]
	s_add_i32 m0, s47, 0x2000
	ds_read_b128 v[232:235], v250 offset:52224
	global_load_lds_dwordx4 v146, s[98:99]
	s_barrier
; #define PG8_STAGE(bufoff, gbase, voff) do { _Pragma("unroll") for (int _i = 0; _i < 2; ++_i) \
;         __builtin_amdgcn_global_load_lds((const unsigned*)((const char*)(gbase) + (voff)[_i]), (LAS unsigned*)(lds + (bufoff) + ldsw + _i * 8192), 16, 0, 0); } while (0)
; #define PG8_LDA(dst, b, h) do { _Pragma("unroll") for (int m = 0; m < 4; ++m) _Pragma("unroll") for (int k = 0; k < 2; ++k) dst[m][k] = *(const LAS bf16x8*)(lds + PG8_SA(b, h) + aoff + m * 2048 + k * 1024); } while (0)
; #define PG8_MMA(ai, bj, At, Bt) do { __builtin_amdgcn_s_setprio(1); _Pragma("unroll") for (int m = 0; m < 4; ++m) _Pragma("unroll") for (int n = 0; n < 2; ++n) _Pragma("unroll") for (int k = 0; k < 2; ++k) \
;         acc[ai][bj][m][n] = __builtin_amdgcn_mfma_f32_16x16x32_bf16(Bt[n][k], At[m][k], acc[ai][bj][m][n], 0, 0, 0); __builtin_amdgcn_s_setprio(0); } while (0)
; #define PG8_WAIT_V(n) asm volatile("s_waitcnt vmcnt(" #n ")" ::: "memory")
; #define PG8_WAIT_L(n) asm volatile("s_waitcnt lgkmcnt(" #n ")" ::: "memory")
; #define PG8_BAR __builtin_amdgcn_s_barrier()
; #define PG8_SCHED __builtin_amdgcn_sched_barrier(0)
;     template <int mode> __device__ __forceinline__ void run(const f32x4 (&acc)[2][2][4][2], const Unit& u, int wr, int wc, int fr, int fq, const LAS float* sc) const {
;     ...
;             f32x4 bv[2][2];
; #pragma unroll
;             for (int bj = 0; bj < 2; ++bj)
; #pragma unroll
;                 for (int n = 0; n < 2; ++n) bv[bj][n] = bias ? *(const f32x4*)(bias + col0 + bj * HALF + 4 * n) : (f32x4){0.f, 0.f, 0.f, 0.f};
; template <int MODE, class EpiT, class Sched>
; __device__ __forceinline__ void gemm_phase(LAS unsigned char* lds, const Gemm g, const Sched& S, const EpiT& E) {
;     ...
;             PG8_BAR; PG8_WAIT_L(0); PG8_MMA(0, 1, At, B1); PG8_BAR;
;             PG8_LDA(At, 1, 1); PG8_STAGE(PG8_SA(1, 0), a3, voffA);
;             PG8_BAR; PG8_WAIT_L(0); PG8_MMA(1, 0, At, B0); PG8_BAR; PG8_SCHED;
;             PG8_STAGE(PG8_SB(1, 1), b3 + hstep, voffB);
;             PG8_WAIT_V(6); PG8_BAR; PG8_MMA(1, 1, At, B1); PG8_BAR;
;         }
	s_waitcnt lgkmcnt(0)
	v_mfma_f32_16x16x32_bf16 v[94:97], v[220:223], v[162:165], v[94:97]
	v_mfma_f32_16x16x32_bf16 v[90:93], v[228:231], v[162:165], v[90:93]
	v_mfma_f32_16x16x32_bf16 v[86:89], v[220:223], v[170:173], v[86:89]
	v_mfma_f32_16x16x32_bf16 v[82:85], v[228:231], v[170:173], v[82:85]
	v_mfma_f32_16x16x32_bf16 v[78:81], v[220:223], v[182:185], v[78:81]
	v_mfma_f32_16x16x32_bf16 v[74:77], v[228:231], v[182:185], v[74:77]
	v_mfma_f32_16x16x32_bf16 v[70:73], v[220:223], v[190:193], v[70:73]
	v_mfma_f32_16x16x32_bf16 v[66:69], v[228:231], v[190:193], v[66:69]
	v_mfma_f32_16x16x32_bf16 v[94:97], v[224:227], v[166:169], v[94:97]
	v_mfma_f32_16x16x32_bf16 v[90:93], v[232:235], v[166:169], v[90:93]
	v_mfma_f32_16x16x32_bf16 v[86:89], v[224:227], v[174:177], v[86:89]
	v_mfma_f32_16x16x32_bf16 v[82:85], v[232:235], v[174:177], v[82:85]
	v_mfma_f32_16x16x32_bf16 v[78:81], v[224:227], v[186:189], v[78:81]
	v_mfma_f32_16x16x32_bf16 v[74:77], v[232:235], v[186:189], v[74:77]
	v_mfma_f32_16x16x32_bf16 v[70:73], v[224:227], v[194:197], v[70:73]
	v_mfma_f32_16x16x32_bf16 v[66:69], v[232:235], v[194:197], v[66:69]
	s_barrier
	s_mov_b32 m0, s56
	ds_read_b128 v[162:165], v160 offset:49152
	ds_read_b128 v[166:169], v160 offset:50176
	ds_read_b128 v[170:173], v160 offset:51200
	ds_read_b128 v[174:177], v160 offset:52224
	ds_read_b128 v[182:185], v160 offset:53248
	ds_read_b128 v[186:189], v160 offset:54272
	ds_read_b128 v[190:193], v160 offset:55296
	global_load_lds_dwordx4 v0, s[100:101]
	s_mov_b32 m0, s57
	ds_read_b128 v[194:197], v160 offset:56320
	global_load_lds_dwordx4 v146, s[100:101]
	s_barrier
	s_waitcnt lgkmcnt(0)
	v_mfma_f32_16x16x32_bf16 v[62:65], v[134:137], v[162:165], v[62:65]
	v_mfma_f32_16x16x32_bf16 v[58:61], v[142:145], v[162:165], v[58:61]
	v_mfma_f32_16x16x32_bf16 v[54:57], v[134:137], v[170:173], v[54:57]
	v_mfma_f32_16x16x32_bf16 v[50:53], v[142:145], v[170:173], v[50:53]
	v_mfma_f32_16x16x32_bf16 v[46:49], v[134:137], v[182:185], v[46:49]
	v_mfma_f32_16x16x32_bf16 v[42:45], v[142:145], v[182:185], v[42:45]
	v_mfma_f32_16x16x32_bf16 v[38:41], v[134:137], v[190:193], v[38:41]
	v_mfma_f32_16x16x32_bf16 v[34:37], v[142:145], v[190:193], v[34:37]
	v_mfma_f32_16x16x32_bf16 v[62:65], v[138:141], v[166:169], v[62:65]
	v_mfma_f32_16x16x32_bf16 v[58:61], v[152:155], v[166:169], v[58:61]
	v_mfma_f32_16x16x32_bf16 v[54:57], v[138:141], v[174:177], v[54:57]
	v_mfma_f32_16x16x32_bf16 v[50:53], v[152:155], v[174:177], v[50:53]
	v_mfma_f32_16x16x32_bf16 v[46:49], v[138:141], v[186:189], v[46:49]
	v_mfma_f32_16x16x32_bf16 v[42:45], v[152:155], v[186:189], v[42:45]
	v_mfma_f32_16x16x32_bf16 v[38:41], v[138:141], v[194:197], v[38:41]
	v_mfma_f32_16x16x32_bf16 v[34:37], v[152:155], v[194:197], v[34:37]
	s_barrier
	s_add_i32 s46, s46, s24
	s_add_u32 s98, s98, s22
	s_addc_u32 s99, s99, 0
	s_mov_b32 m0, s46
	s_nop 0
	global_load_lds_dwordx4 v0, s[98:99]
	s_add_i32 m0, s46, 0x2000
	s_nop 0
	global_load_lds_dwordx4 v146, s[98:99]
	s_waitcnt vmcnt(6)
	s_barrier
	v_mfma_f32_16x16x32_bf16 v[30:33], v[220:223], v[162:165], v[30:33]
	v_mfma_f32_16x16x32_bf16 v[26:29], v[228:231], v[162:165], v[26:29]
	v_mfma_f32_16x16x32_bf16 v[22:25], v[220:223], v[170:173], v[22:25]
	v_mfma_f32_16x16x32_bf16 v[18:21], v[228:231], v[170:173], v[18:21]
	v_mfma_f32_16x16x32_bf16 v[14:17], v[220:223], v[182:185], v[14:17]
	v_mfma_f32_16x16x32_bf16 v[10:13], v[228:231], v[182:185], v[10:13]
	v_mfma_f32_16x16x32_bf16 v[6:9], v[220:223], v[190:193], v[6:9]
	v_mfma_f32_16x16x32_bf16 v[2:5], v[228:231], v[190:193], v[2:5]
	v_mfma_f32_16x16x32_bf16 v[30:33], v[224:227], v[166:169], v[30:33]
	v_mfma_f32_16x16x32_bf16 v[26:29], v[232:235], v[166:169], v[26:29]
	v_mfma_f32_16x16x32_bf16 v[22:25], v[224:227], v[174:177], v[22:25]
	v_mfma_f32_16x16x32_bf16 v[18:21], v[232:235], v[174:177], v[18:21]
	v_mfma_f32_16x16x32_bf16 v[14:17], v[224:227], v[186:189], v[14:17]
	v_mfma_f32_16x16x32_bf16 v[10:13], v[232:235], v[186:189], v[10:13]
	v_mfma_f32_16x16x32_bf16 v[6:9], v[224:227], v[194:197], v[6:9]
	v_mfma_f32_16x16x32_bf16 v[2:5], v[232:235], v[194:197], v[2:5]
	s_barrier
	s_add_u32 s44, s44, 0x100
	s_addc_u32 s45, s45, 0
	s_cmp_ge_u32 s68, s55
	s_mov_b32 s46, s68
	s_cbranch_scc0 .LBB0_280
	v_lshl_or_b32 v152, s3, 8, v159
	v_ashrrev_i32_e32 v153, 31, v152
	v_cndmask_b32_e64 v131, 0, 1, s[28:29]
	v_lshl_add_u64 v[154:155], v[152:153], 2, s[12:13]
	v_mov_b32_e32 v130, 0
	v_cmp_ne_u32_e64 s[44:45], 1, v131
	s_andn2_b64 vcc, exec, s[28:29]
	v_mov_b32_e32 v134, 0
	v_mov_b32_e32 v135, 0
	v_mov_b32_e32 v136, 0
	v_mov_b32_e32 v137, 0
	s_cbranch_vccnz .LBB0_283
	global_load_dwordx4 v[134:137], v[154:155], off

; #define PG8_STAGE(bufoff, gbase, voff) do { _Pragma("unroll") for (int _i = 0; _i < 2; ++_i) \
;         __builtin_amdgcn_global_load_lds((const unsigned*)((const char*)(gbase) + (voff)[_i]), (LAS unsigned*)(lds + (bufoff) + ldsw + _i * 8192), 16, 0, 0); } while (0)
; #define PG8_LDA(dst, b, h) do { _Pragma("unroll") for (int m = 0; m < 4; ++m) _Pragma("unroll") for (int k = 0; k < 2; ++k) dst[m][k] = *(const LAS bf16x8*)(lds + PG8_SA(b, h) + aoff + m * 2048 + k * 1024); } while (0)
; #define PG8_LDB(dst, b, h) do { _Pragma("unroll") for (int n = 0; n < 2; ++n) _Pragma("unroll") for (int k = 0; k < 2; ++k) dst[n][k] = *(const LAS bf16x8*)(lds + PG8_SB(b, h) + boff + n * 2048 + k * 1024); } while (0)
; #define PG8_MMA(ai, bj, At, Bt) do { __builtin_amdgcn_s_setprio(1); _Pragma("unroll") for (int m = 0; m < 4; ++m) _Pragma("unroll") for (int n = 0; n < 2; ++n) _Pragma("unroll") for (int k = 0; k < 2; ++k) \
;         acc[ai][bj][m][n] = __builtin_amdgcn_mfma_f32_16x16x32_bf16(Bt[n][k], At[m][k], acc[ai][bj][m][n], 0, 0, 0); __builtin_amdgcn_s_setprio(0); } while (0)
; #define PG8_WAIT_V(n) asm volatile("s_waitcnt vmcnt(" #n ")" ::: "memory")
; #define PG8_WAIT_L(n) asm volatile("s_waitcnt lgkmcnt(" #n ")" ::: "memory")
; #define PG8_BAR __builtin_amdgcn_s_barrier()
; #define PG8_SCHED __builtin_amdgcn_sched_barrier(0)
; template <int MODE, class EpiT, class Sched>
; __device__ __forceinline__ void gemm_phase(LAS unsigned char* lds, const Gemm g, const Sched& S, const EpiT& E) {
;     ...
;             PG8_LDB(B0, 0, 0); PG8_SCHED; PG8_LDA(At, 0, 0); PG8_STAGE(PG8_SA(1, 1), a1 + hstep, voffA);
;             PG8_WAIT_L(8); PG8_BAR; PG8_WAIT_L(0); PG8_MMA(0, 0, At, B0); PG8_BAR; PG8_SCHED;
;             PG8_LDB(B1, 0, 1); PG8_STAGE(PG8_SB(0, 0), b2, voffB);
;             PG8_BAR; PG8_WAIT_L(0); PG8_MMA(0, 1, At, B1); PG8_BAR;
;             PG8_LDA(At, 0, 1); PG8_STAGE(PG8_SA(0, 0), a2, voffA);
;             PG8_BAR; PG8_WAIT_L(0); PG8_MMA(1, 0, At, B0); PG8_BAR; PG8_SCHED;
;             PG8_STAGE(PG8_SB(0, 1), b2 + hstep, voffB);
;             PG8_WAIT_V(6); PG8_BAR; PG8_MMA(1, 1, At, B1); PG8_BAR;
.LBB0_332:
	s_add_i32 s23, s22, 2
	s_add_u32 s30, s12, s4
	s_addc_u32 s38, s13, s5
	s_add_u32 s44, s10, s4
	s_addc_u32 s45, s11, s5
	ds_read_b128 v[146:149], v145
	ds_read_b128 v[150:153], v145 offset:1024
	ds_read_b128 v[154:157], v145 offset:2048
	ds_read_b128 v[158:161], v145 offset:3072
	s_cmp_eq_u32 s55, s22
	s_cselect_b32 s39, s29, s38
	s_cselect_b32 s38, s28, s30
	s_cselect_b32 s45, s35, s45
	s_cselect_b32 s44, s34, s44
	s_add_i32 m0, s47, 0xc000
	ds_read_b128 v[162:165], v144
	ds_read_b128 v[166:169], v144 offset:1024
	ds_read_b128 v[170:173], v144 offset:2048
	ds_read_b128 v[174:177], v144 offset:3072
	ds_read_b128 v[182:185], v144 offset:4096
	ds_read_b128 v[186:189], v144 offset:5120
	ds_read_b128 v[190:193], v144 offset:6144
	global_load_lds_dwordx4 v0, s[100:101]
	s_add_i32 m0, s47, 0xe000
	ds_read_b128 v[194:197], v144 offset:7168
	global_load_lds_dwordx4 v130, s[100:101]
	s_waitcnt lgkmcnt(8)
	s_barrier
	s_waitcnt lgkmcnt(0)
	v_mfma_f32_16x16x32_bf16 v[126:129], v[146:149], v[162:165], v[126:129]
	v_mfma_f32_16x16x32_bf16 v[122:125], v[154:157], v[162:165], v[122:125]
	v_mfma_f32_16x16x32_bf16 v[118:121], v[146:149], v[170:173], v[118:121]
	v_mfma_f32_16x16x32_bf16 v[114:117], v[154:157], v[170:173], v[114:117]
	v_mfma_f32_16x16x32_bf16 v[110:113], v[146:149], v[182:185], v[110:113]
	v_mfma_f32_16x16x32_bf16 v[106:109], v[154:157], v[182:185], v[106:109]
	v_mfma_f32_16x16x32_bf16 v[102:105], v[146:149], v[190:193], v[102:105]
	v_mfma_f32_16x16x32_bf16 v[98:101], v[154:157], v[190:193], v[98:101]
	v_mfma_f32_16x16x32_bf16 v[126:129], v[150:153], v[166:169], v[126:129]
	v_mfma_f32_16x16x32_bf16 v[122:125], v[158:161], v[166:169], v[122:125]
	v_mfma_f32_16x16x32_bf16 v[118:121], v[150:153], v[174:177], v[118:121]
	v_mfma_f32_16x16x32_bf16 v[114:117], v[158:161], v[174:177], v[114:117]
	v_mfma_f32_16x16x32_bf16 v[110:113], v[150:153], v[186:189], v[110:113]
	v_mfma_f32_16x16x32_bf16 v[106:109], v[158:161], v[186:189], v[106:109]
	v_mfma_f32_16x16x32_bf16 v[102:105], v[150:153], v[194:197], v[102:105]
	v_mfma_f32_16x16x32_bf16 v[98:101], v[158:161], v[194:197], v[98:101]
	s_barrier
	s_add_u32 s98, s44, 0x80
	s_addc_u32 s99, s45, 0
	s_add_i32 m0, s46, 0x10000
	ds_read_b128 v[220:223], v145 offset:16384
	ds_read_b128 v[224:227], v145 offset:17408
	ds_read_b128 v[228:231], v145 offset:18432
	global_load_lds_dwordx4 v0, s[44:45]
	s_add_i32 m0, s46, 0x12000
	ds_read_b128 v[232:235], v145 offset:19456
	global_load_lds_dwordx4 v130, s[44:45]
	s_barrier
	s_waitcnt lgkmcnt(0)
	v_mfma_f32_16x16x32_bf16 v[94:97], v[220:223], v[162:165], v[94:97]
	v_mfma_f32_16x16x32_bf16 v[90:93], v[228:231], v[162:165], v[90:93]
	v_mfma_f32_16x16x32_bf16 v[86:89], v[220:223], v[170:173], v[86:89]
	v_mfma_f32_16x16x32_bf16 v[82:85], v[228:231], v[170:173], v[82:85]
	v_mfma_f32_16x16x32_bf16 v[78:81], v[220:223], v[182:185], v[78:81]
	v_mfma_f32_16x16x32_bf16 v[74:77], v[228:231], v[182:185], v[74:77]
	v_mfma_f32_16x16x32_bf16 v[70:73], v[220:223], v[190:193], v[70:73]
	v_mfma_f32_16x16x32_bf16 v[66:69], v[228:231], v[190:193], v[66:69]
	v_mfma_f32_16x16x32_bf16 v[94:97], v[224:227], v[166:169], v[94:97]
	v_mfma_f32_16x16x32_bf16 v[90:93], v[232:235], v[166:169], v[90:93]
	v_mfma_f32_16x16x32_bf16 v[86:89], v[224:227], v[174:177], v[86:89]
	v_mfma_f32_16x16x32_bf16 v[82:85], v[232:235], v[174:177], v[82:85]
	v_mfma_f32_16x16x32_bf16 v[78:81], v[224:227], v[186:189], v[78:81]
	v_mfma_f32_16x16x32_bf16 v[74:77], v[232:235], v[186:189], v[74:77]
	v_mfma_f32_16x16x32_bf16 v[70:73], v[224:227], v[194:197], v[70:73]
	v_mfma_f32_16x16x32_bf16 v[66:69], v[232:235], v[194:197], v[66:69]
	s_barrier
	s_mov_b32 m0, s47
	ds_read_b128 v[162:165], v144 offset:16384
	ds_read_b128 v[166:169], v144 offset:17408
	ds_read_b128 v[170:173], v144 offset:18432
	ds_read_b128 v[174:177], v144 offset:19456
	ds_read_b128 v[182:185], v144 offset:20480
	ds_read_b128 v[186:189], v144 offset:21504
	ds_read_b128 v[190:193], v144 offset:22528
	global_load_lds_dwordx4 v0, s[38:39]
	s_mov_b32 m0, s50
	ds_read_b128 v[194:197], v144 offset:23552
	global_load_lds_dwordx4 v130, s[38:39]
	s_barrier
	s_waitcnt lgkmcnt(0)
	v_mfma_f32_16x16x32_bf16 v[62:65], v[146:149], v[162:165], v[62:65]
	v_mfma_f32_16x16x32_bf16 v[58:61], v[154:157], v[162:165], v[58:61]
	v_mfma_f32_16x16x32_bf16 v[54:57], v[146:149], v[170:173], v[54:57]
	v_mfma_f32_16x16x32_bf16 v[50:53], v[154:157], v[170:173], v[50:53]
	v_mfma_f32_16x16x32_bf16 v[46:49], v[146:149], v[182:185], v[46:49]
	v_mfma_f32_16x16x32_bf16 v[42:45], v[154:157], v[182:185], v[42:45]
	v_mfma_f32_16x16x32_bf16 v[38:41], v[146:149], v[190:193], v[38:41]
	v_mfma_f32_16x16x32_bf16 v[34:37], v[154:157], v[190:193], v[34:37]
	v_mfma_f32_16x16x32_bf16 v[62:65], v[150:153], v[166:169], v[62:65]
	v_mfma_f32_16x16x32_bf16 v[58:61], v[158:161], v[166:169], v[58:61]
	v_mfma_f32_16x16x32_bf16 v[54:57], v[150:153], v[174:177], v[54:57]
	v_mfma_f32_16x16x32_bf16 v[50:53], v[158:161], v[174:177], v[50:53]
	v_mfma_f32_16x16x32_bf16 v[46:49], v[150:153], v[186:189], v[46:49]
	v_mfma_f32_16x16x32_bf16 v[42:45], v[158:161], v[186:189], v[42:45]
	v_mfma_f32_16x16x32_bf16 v[38:41], v[150:153], v[194:197], v[38:41]
	v_mfma_f32_16x16x32_bf16 v[34:37], v[158:161], v[194:197], v[34:37]
	s_barrier
	s_add_u32 s44, s44, s21
	s_addc_u32 s45, s45, 0
	s_add_i32 m0, s46, 0x14000
	s_nop 0
	global_load_lds_dwordx4 v0, s[44:45]
	s_add_i32 m0, s46, 0x16000
	s_nop 0
	global_load_lds_dwordx4 v130, s[44:45]
	s_waitcnt vmcnt(6)
	s_barrier
; #define PG8_STAGE(bufoff, gbase, voff) do { _Pragma("unroll") for (int _i = 0; _i < 2; ++_i) \
;         __builtin_amdgcn_global_load_lds((const unsigned*)((const char*)(gbase) + (voff)[_i]), (LAS unsigned*)(lds + (bufoff) + ldsw + _i * 8192), 16, 0, 0); } while (0)
; #define PG8_LDA(dst, b, h) do { _Pragma("unroll") for (int m = 0; m < 4; ++m) _Pragma("unroll") for (int k = 0; k < 2; ++k) dst[m][k] = *(const LAS bf16x8*)(lds + PG8_SA(b, h) + aoff + m * 2048 + k * 1024); } while (0)
; #define PG8_LDB(dst, b, h) do { _Pragma("unroll") for (int n = 0; n < 2; ++n) _Pragma("unroll") for (int k = 0; k < 2; ++k) dst[n][k] = *(const LAS bf16x8*)(lds + PG8_SB(b, h) + boff + n * 2048 + k * 1024); } while (0)
; #define PG8_MMA(ai, bj, At, Bt) do { __builtin_amdgcn_s_setprio(1); _Pragma("unroll") for (int m = 0; m < 4; ++m) _Pragma("unroll") for (int n = 0; n < 2; ++n) _Pragma("unroll") for (int k = 0; k < 2; ++k) \
;         acc[ai][bj][m][n] = __builtin_amdgcn_mfma_f32_16x16x32_bf16(Bt[n][k], At[m][k], acc[ai][bj][m][n], 0, 0, 0); __builtin_amdgcn_s_setprio(0); } while (0)
; #define PG8_WAIT_V(n) asm volatile("s_waitcnt vmcnt(" #n ")" ::: "memory")
; #define PG8_WAIT_L(n) asm volatile("s_waitcnt lgkmcnt(" #n ")" ::: "memory")
; #define PG8_BAR __builtin_amdgcn_s_barrier()
; #define PG8_SCHED __builtin_amdgcn_sched_barrier(0)
; template <int MODE, class EpiT, class Sched>
; __device__ __forceinline__ void gemm_phase(LAS unsigned char* lds, const Gemm g, const Sched& S, const EpiT& E) {
;     ...
;             PG8_WAIT_V(6); PG8_BAR; PG8_MMA(1, 1, At, B1); PG8_BAR;
;             PG8_LDB(B0, 1, 0); PG8_SCHED; PG8_LDA(At, 1, 0); PG8_STAGE(PG8_SA(0, 1), a2 + hstep, voffA);
;             PG8_WAIT_L(8); PG8_BAR; PG8_WAIT_L(0); PG8_MMA(0, 0, At, B0); PG8_BAR; PG8_SCHED;
;             PG8_LDB(B1, 1, 1); PG8_STAGE(PG8_SB(1, 0), b3, voffB);
;             PG8_BAR; PG8_WAIT_L(0); PG8_MMA(0, 1, At, B1); PG8_BAR;
;             PG8_LDA(At, 1, 1); PG8_STAGE(PG8_SA(1, 0), a3, voffA);
;             PG8_BAR; PG8_WAIT_L(0); PG8_MMA(1, 0, At, B0); PG8_BAR; PG8_SCHED;
	v_mfma_f32_16x16x32_bf16 v[30:33], v[220:223], v[162:165], v[30:33]
	v_mfma_f32_16x16x32_bf16 v[26:29], v[228:231], v[162:165], v[26:29]
	v_mfma_f32_16x16x32_bf16 v[22:25], v[220:223], v[170:173], v[22:25]
	v_mfma_f32_16x16x32_bf16 v[18:21], v[228:231], v[170:173], v[18:21]
	v_mfma_f32_16x16x32_bf16 v[14:17], v[220:223], v[182:185], v[14:17]
	v_mfma_f32_16x16x32_bf16 v[10:13], v[228:231], v[182:185], v[10:13]
	v_mfma_f32_16x16x32_bf16 v[6:9], v[220:223], v[190:193], v[6:9]
	v_mfma_f32_16x16x32_bf16 v[2:5], v[228:231], v[190:193], v[2:5]
	v_mfma_f32_16x16x32_bf16 v[30:33], v[224:227], v[166:169], v[30:33]
	v_mfma_f32_16x16x32_bf16 v[26:29], v[232:235], v[166:169], v[26:29]
	v_mfma_f32_16x16x32_bf16 v[22:25], v[224:227], v[174:177], v[22:25]
	v_mfma_f32_16x16x32_bf16 v[18:21], v[232:235], v[174:177], v[18:21]
	v_mfma_f32_16x16x32_bf16 v[14:17], v[224:227], v[186:189], v[14:17]
	v_mfma_f32_16x16x32_bf16 v[10:13], v[232:235], v[186:189], v[10:13]
	v_mfma_f32_16x16x32_bf16 v[6:9], v[224:227], v[194:197], v[6:9]
	v_mfma_f32_16x16x32_bf16 v[2:5], v[232:235], v[194:197], v[2:5]
	s_barrier
	ds_read_b128 v[146:149], v145 offset:32768
	ds_read_b128 v[150:153], v145 offset:33792
	ds_read_b128 v[154:157], v145 offset:34816
	ds_read_b128 v[158:161], v145 offset:35840
	s_add_u32 s38, s38, s21
	s_addc_u32 s39, s39, 0
	s_mov_b32 m0, s51
	ds_read_b128 v[162:165], v144 offset:32768
	ds_read_b128 v[166:169], v144 offset:33792
	ds_read_b128 v[170:173], v144 offset:34816
	ds_read_b128 v[174:177], v144 offset:35840
	ds_read_b128 v[182:185], v144 offset:36864
	ds_read_b128 v[186:189], v144 offset:37888
	ds_read_b128 v[190:193], v144 offset:38912
	global_load_lds_dwordx4 v0, s[38:39]
	s_mov_b32 m0, s52
	ds_read_b128 v[194:197], v144 offset:39936
	global_load_lds_dwordx4 v130, s[38:39]
	s_waitcnt lgkmcnt(8)
	s_barrier
	s_waitcnt lgkmcnt(0)
	v_mfma_f32_16x16x32_bf16 v[126:129], v[146:149], v[162:165], v[126:129]
	v_mfma_f32_16x16x32_bf16 v[122:125], v[154:157], v[162:165], v[122:125]
	v_mfma_f32_16x16x32_bf16 v[118:121], v[146:149], v[170:173], v[118:121]
	v_mfma_f32_16x16x32_bf16 v[114:117], v[154:157], v[170:173], v[114:117]
	v_mfma_f32_16x16x32_bf16 v[110:113], v[146:149], v[182:185], v[110:113]
	v_mfma_f32_16x16x32_bf16 v[106:109], v[154:157], v[182:185], v[106:109]
	v_mfma_f32_16x16x32_bf16 v[102:105], v[146:149], v[190:193], v[102:105]
	v_mfma_f32_16x16x32_bf16 v[98:101], v[154:157], v[190:193], v[98:101]
	v_mfma_f32_16x16x32_bf16 v[126:129], v[150:153], v[166:169], v[126:129]
	v_mfma_f32_16x16x32_bf16 v[122:125], v[158:161], v[166:169], v[122:125]
	v_mfma_f32_16x16x32_bf16 v[118:121], v[150:153], v[174:177], v[118:121]
	v_mfma_f32_16x16x32_bf16 v[114:117], v[158:161], v[174:177], v[114:117]
	v_mfma_f32_16x16x32_bf16 v[110:113], v[150:153], v[186:189], v[110:113]
	v_mfma_f32_16x16x32_bf16 v[106:109], v[158:161], v[186:189], v[106:109]
	v_mfma_f32_16x16x32_bf16 v[102:105], v[150:153], v[194:197], v[102:105]
	v_mfma_f32_16x16x32_bf16 v[98:101], v[158:161], v[194:197], v[98:101]
	s_barrier
	s_add_i32 m0, s46, 0x18000
	ds_read_b128 v[220:223], v145 offset:49152
	ds_read_b128 v[224:227], v145 offset:50176
	ds_read_b128 v[228:231], v145 offset:51200
	global_load_lds_dwordx4 v0, s[98:99]
	s_add_i32 m0, s46, 0x1a000
	ds_read_b128 v[232:235], v145 offset:52224
	global_load_lds_dwordx4 v130, s[98:99]
	s_barrier
	s_waitcnt lgkmcnt(0)
	v_mfma_f32_16x16x32_bf16 v[94:97], v[220:223], v[162:165], v[94:97]
	v_mfma_f32_16x16x32_bf16 v[90:93], v[228:231], v[162:165], v[90:93]
	v_mfma_f32_16x16x32_bf16 v[86:89], v[220:223], v[170:173], v[86:89]
	v_mfma_f32_16x16x32_bf16 v[82:85], v[228:231], v[170:173], v[82:85]
	v_mfma_f32_16x16x32_bf16 v[78:81], v[220:223], v[182:185], v[78:81]
	v_mfma_f32_16x16x32_bf16 v[74:77], v[228:231], v[182:185], v[74:77]
	v_mfma_f32_16x16x32_bf16 v[70:73], v[220:223], v[190:193], v[70:73]
	v_mfma_f32_16x16x32_bf16 v[66:69], v[228:231], v[190:193], v[66:69]
	v_mfma_f32_16x16x32_bf16 v[94:97], v[224:227], v[166:169], v[94:97]
	v_mfma_f32_16x16x32_bf16 v[90:93], v[232:235], v[166:169], v[90:93]
	v_mfma_f32_16x16x32_bf16 v[86:89], v[224:227], v[174:177], v[86:89]
	v_mfma_f32_16x16x32_bf16 v[82:85], v[232:235], v[174:177], v[82:85]
	v_mfma_f32_16x16x32_bf16 v[78:81], v[224:227], v[186:189], v[78:81]
	v_mfma_f32_16x16x32_bf16 v[74:77], v[232:235], v[186:189], v[74:77]
	v_mfma_f32_16x16x32_bf16 v[70:73], v[224:227], v[194:197], v[70:73]
	v_mfma_f32_16x16x32_bf16 v[66:69], v[232:235], v[194:197], v[66:69]
	s_barrier
	s_mov_b32 m0, s53
	s_sub_u32 s98, s38, s21
	s_subb_u32 s99, s39, 0
	s_add_u32 s98, s98, 0x80
	s_addc_u32 s99, s99, 0
	ds_read_b128 v[162:165], v144 offset:49152
	ds_read_b128 v[166:169], v144 offset:50176
	ds_read_b128 v[170:173], v144 offset:51200
	ds_read_b128 v[174:177], v144 offset:52224
	ds_read_b128 v[182:185], v144 offset:53248
	ds_read_b128 v[186:189], v144 offset:54272
	ds_read_b128 v[190:193], v144 offset:55296
	global_load_lds_dwordx4 v0, s[98:99]
	s_mov_b32 m0, s54
	ds_read_b128 v[194:197], v144 offset:56320
	global_load_lds_dwordx4 v130, s[98:99]
	s_barrier
	s_waitcnt lgkmcnt(0)
	v_mfma_f32_16x16x32_bf16 v[62:65], v[146:149], v[162:165], v[62:65]
	v_mfma_f32_16x16x32_bf16 v[58:61], v[154:157], v[162:165], v[58:61]
	v_mfma_f32_16x16x32_bf16 v[54:57], v[146:149], v[170:173], v[54:57]
	v_mfma_f32_16x16x32_bf16 v[50:53], v[154:157], v[170:173], v[50:53]
	v_mfma_f32_16x16x32_bf16 v[46:49], v[146:149], v[182:185], v[46:49]
	v_mfma_f32_16x16x32_bf16 v[42:45], v[154:157], v[182:185], v[42:45]
	v_mfma_f32_16x16x32_bf16 v[38:41], v[146:149], v[190:193], v[38:41]
	v_mfma_f32_16x16x32_bf16 v[34:37], v[154:157], v[190:193], v[34:37]
	v_mfma_f32_16x16x32_bf16 v[62:65], v[150:153], v[166:169], v[62:65]
	v_mfma_f32_16x16x32_bf16 v[58:61], v[158:161], v[166:169], v[58:61]
	v_mfma_f32_16x16x32_bf16 v[54:57], v[150:153], v[174:177], v[54:57]
	v_mfma_f32_16x16x32_bf16 v[50:53], v[158:161], v[174:177], v[50:53]
	v_mfma_f32_16x16x32_bf16 v[46:49], v[150:153], v[186:189], v[46:49]
	v_mfma_f32_16x16x32_bf16 v[42:45], v[158:161], v[186:189], v[42:45]
	v_mfma_f32_16x16x32_bf16 v[38:41], v[150:153], v[194:197], v[38:41]
	v_mfma_f32_16x16x32_bf16 v[34:37], v[158:161], v[194:197], v[34:37]
	s_barrier
; __device__ __forceinline__ unsigned pk2(float lo, float hi) { unsigned r; asm volatile("v_cvt_pk_bf16_f32 %0, %1, %2" : "=v"(r) : "v"(lo), "v"(hi)); return r; }
; __device__ __forceinline__ float siluf_(float x) { return x * __builtin_amdgcn_rcpf(1.0f + __expf(-x)); }
; #define PG8_STAGE(bufoff, gbase, voff) do { _Pragma("unroll") for (int _i = 0; _i < 2; ++_i) \
;         __builtin_amdgcn_global_load_lds((const unsigned*)((const char*)(gbase) + (voff)[_i]), (LAS unsigned*)(lds + (bufoff) + ldsw + _i * 8192), 16, 0, 0); } while (0)
; #define PG8_MMA(ai, bj, At, Bt) do { __builtin_amdgcn_s_setprio(1); _Pragma("unroll") for (int m = 0; m < 4; ++m) _Pragma("unroll") for (int n = 0; n < 2; ++n) _Pragma("unroll") for (int k = 0; k < 2; ++k) \
;         acc[ai][bj][m][n] = __builtin_amdgcn_mfma_f32_16x16x32_bf16(Bt[n][k], At[m][k], acc[ai][bj][m][n], 0, 0, 0); __builtin_amdgcn_s_setprio(0); } while (0)
; #define PG8_WAIT_V(n) asm volatile("s_waitcnt vmcnt(" #n ")" ::: "memory")
; #define PG8_BAR __builtin_amdgcn_s_barrier()
;     template <int mode> __device__ __forceinline__ void run(const f32x4 (&acc)[2][2][4][2], const Unit& u, int wr, int wc, int fr, int fq, const LAS float* sc) const {
;     ...
;         if (mode == 0) {
;             const int col0 = u.pn * HALF + wc * 32 + 8 * fq;
; #pragma unroll
;             for (int ai = 0; ai < 2; ++ai)
; #pragma unroll
;                 for (int m = 0; m < 4; ++m) {
;                     const int row = row0 + ai * HALF + m * 16;
;                     const float s = sc[ai * HALF + wr * 64 + m * 16 + fr];
;                     const f32x4 g0 = acc[ai][0][m][0] * s, u0 = acc[ai][1][m][0] * s, g1 = acc[ai][0][m][1] * s, u1 = acc[ai][1][m][1] * s;
;                     u32x4 w;
;                     w.x = pk2(siluf_(g0[0]) * u0[0], siluf_(g0[1]) * u0[1]); w.y = pk2(siluf_(g0[2]) * u0[2], siluf_(g0[3]) * u0[3]);
;                     w.z = pk2(siluf_(g1[0]) * u1[0], siluf_(g1[1]) * u1[1]); w.w = pk2(siluf_(g1[2]) * u1[2], siluf_(g1[3]) * u1[3]);
;                     *(u32x4*)(ob + (size_t)row * FF + col0) = w;
; template <int MODE, class EpiT, class Sched>
; __device__ __forceinline__ void gemm_phase(LAS unsigned char* lds, const Gemm g, const Sched& S, const EpiT& E) {
;     ...
;             PG8_STAGE(PG8_SB(1, 1), b3 + hstep, voffB);
;             PG8_WAIT_V(6); PG8_BAR; PG8_MMA(1, 1, At, B1); PG8_BAR;
;         }
	s_add_u32 s98, s44, 0x80
	s_addc_u32 s99, s45, 0
	s_add_i32 m0, s46, 0x1c000
	s_nop 0
	global_load_lds_dwordx4 v0, s[98:99]
	s_add_i32 m0, s46, 0x1e000
	s_nop 0
	global_load_lds_dwordx4 v130, s[98:99]
	s_waitcnt vmcnt(6)
	s_barrier
	v_mfma_f32_16x16x32_bf16 v[30:33], v[220:223], v[162:165], v[30:33]
	v_mfma_f32_16x16x32_bf16 v[26:29], v[228:231], v[162:165], v[26:29]
	v_mfma_f32_16x16x32_bf16 v[22:25], v[220:223], v[170:173], v[22:25]
	v_mfma_f32_16x16x32_bf16 v[18:21], v[228:231], v[170:173], v[18:21]
	v_mfma_f32_16x16x32_bf16 v[14:17], v[220:223], v[182:185], v[14:17]
	v_mfma_f32_16x16x32_bf16 v[10:13], v[228:231], v[182:185], v[10:13]
	v_mfma_f32_16x16x32_bf16 v[6:9], v[220:223], v[190:193], v[6:9]
	v_mfma_f32_16x16x32_bf16 v[2:5], v[228:231], v[190:193], v[2:5]
	v_mfma_f32_16x16x32_bf16 v[30:33], v[224:227], v[166:169], v[30:33]
	v_mfma_f32_16x16x32_bf16 v[26:29], v[232:235], v[166:169], v[26:29]
	v_mfma_f32_16x16x32_bf16 v[22:25], v[224:227], v[174:177], v[22:25]
	v_mfma_f32_16x16x32_bf16 v[18:21], v[232:235], v[174:177], v[18:21]
	v_mfma_f32_16x16x32_bf16 v[14:17], v[224:227], v[186:189], v[14:17]
	v_mfma_f32_16x16x32_bf16 v[10:13], v[232:235], v[186:189], v[10:13]
	v_mfma_f32_16x16x32_bf16 v[6:9], v[224:227], v[194:197], v[6:9]
	v_mfma_f32_16x16x32_bf16 v[2:5], v[232:235], v[194:197], v[2:5]
	s_barrier
	s_add_u32 s4, s4, 0x100
	s_addc_u32 s5, s5, 0
	s_add_u32 s100, s100, 0x100
	s_addc_u32 s101, s101, 0
	s_cmp_ge_u32 s23, s16
	s_mov_b32 s22, s23
	s_cbranch_scc0 .LBB0_332
	v_lshl_add_u32 v145, s57, 10, v142
	ds_read_b32 v136, v145
	v_lshl_or_b32 v138, s8, 7, v143
	v_lshl_add_u32 v146, s9, 8, v140
	v_ashrrev_i32_e32 v139, 31, v138
	v_lshlrev_b64 v[138:139], 1, v[138:139]
	s_waitcnt lgkmcnt(0)
	v_pk_mul_f32 v[148:149], v[126:127], v[136:137] op_sel_hi:[1,0]
	v_pk_mul_f32 v[154:155], v[94:95], v[136:137] op_sel_hi:[1,0]
	v_mul_f32_e32 v147, 0xbfb8aa3b, v148
	v_exp_f32_e32 v147, v147
	v_pk_mul_f32 v[150:151], v[128:129], v[136:137] op_sel_hi:[1,0]
	v_pk_mul_f32 v[152:153], v[96:97], v[136:137] op_sel_hi:[1,0]
	v_pk_mul_f32 v[158:159], v[122:123], v[136:137] op_sel_hi:[1,0]
	v_add_f32_e32 v147, 1.0, v147
	v_rcp_f32_e32 v147, v147
	v_pk_mul_f32 v[156:157], v[124:125], v[136:137] op_sel_hi:[1,0]
	v_pk_mul_f32 v[160:161], v[92:93], v[136:137] op_sel_hi:[1,0]
	v_pk_mul_f32 v[136:137], v[90:91], v[136:137] op_sel_hi:[1,0]
	v_mul_f32_e32 v147, v148, v147
	v_mul_f32_e32 v148, 0xbfb8aa3b, v149
	v_exp_f32_e32 v148, v148
	v_mul_f32_e32 v147, v154, v147
	s_and_b64 vcc, exec, s[42:43]
	v_add_f32_e32 v148, 1.0, v148
	v_rcp_f32_e32 v148, v148
	s_nop 0
	v_mul_f32_e32 v148, v149, v148
	v_mul_f32_e32 v148, v155, v148
	v_cvt_pk_bf16_f32 v148, v147, v148
	v_mul_f32_e32 v147, 0xbfb8aa3b, v150
	v_mul_f32_e32 v149, 0xbfb8aa3b, v151
	v_exp_f32_e32 v147, v147
	v_exp_f32_e32 v149, v149
	v_add_f32_e32 v147, 1.0, v147
	v_add_f32_e32 v149, 1.0, v149
	v_rcp_f32_e32 v147, v147
	v_rcp_f32_e32 v149, v149
	v_mul_f32_e32 v147, v150, v147
	v_mul_f32_e32 v149, v151, v149
	v_mul_f32_e32 v147, v152, v147
	v_mul_f32_e32 v149, v153, v149
	v_cvt_pk_bf16_f32 v149, v147, v149
	v_mul_f32_e32 v147, 0xbfb8aa3b, v158
	v_exp_f32_e32 v147, v147
	s_nop 0
	v_add_f32_e32 v147, 1.0, v147
	v_rcp_f32_e32 v147, v147
	s_nop 0
	v_mul_f32_e32 v147, v158, v147
	v_mul_f32_e32 v136, v136, v147
	v_mul_f32_e32 v147, 0xbfb8aa3b, v159
	v_exp_f32_e32 v147, v147
	s_nop 0
	v_add_f32_e32 v147, 1.0, v147
	v_rcp_f32_e32 v147, v147
	s_nop 0
	v_mul_f32_e32 v147, v159, v147
	v_mul_f32_e32 v137, v137, v147
	v_cvt_pk_bf16_f32 v150, v136, v137
	v_mul_f32_e32 v136, 0xbfb8aa3b, v156
	v_mul_f32_e32 v137, 0xbfb8aa3b, v157
	v_exp_f32_e32 v136, v136
	v_exp_f32_e32 v137, v137
	v_or_b32_e32 v147, 16, v146
	v_add_f32_e32 v136, 1.0, v136
	v_add_f32_e32 v137, 1.0, v137
	v_rcp_f32_e32 v136, v136
	v_rcp_f32_e32 v137, v137
	v_mul_f32_e32 v136, v156, v136
	v_mul_f32_e32 v137, v157, v137
	v_mul_f32_e32 v136, v160, v136
	v_mul_f32_e32 v137, v161, v137
	v_cvt_pk_bf16_f32 v151, v136, v137
	v_mov_b64_e32 v[136:137], s[6:7]
	v_mad_i64_i32 v[152:153], s[4:5], v146, s33, v[136:137]
	v_lshl_add_u64 v[152:153], v[152:153], 0, v[138:139]
	global_store_dwordx4 v[152:153], v[148:151], off
	ds_read_b32 v148, v145 offset:64
	s_waitcnt lgkmcnt(0)
	v_pk_mul_f32 v[152:153], v[118:119], v[148:149] op_sel_hi:[1,0]
	v_pk_mul_f32 v[150:151], v[120:121], v[148:149] op_sel_hi:[1,0]
	v_pk_mul_f32 v[154:155], v[88:89], v[148:149] op_sel_hi:[1,0]
	v_pk_mul_f32 v[156:157], v[86:87], v[148:149] op_sel_hi:[1,0]
	v_pk_mul_f32 v[158:159], v[116:117], v[148:149] op_sel_hi:[1,0]
	v_pk_mul_f32 v[160:161], v[114:115], v[148:149] op_sel_hi:[1,0]
	v_pk_mul_f32 v[162:163], v[84:85], v[148:149] op_sel_hi:[1,0]
	v_pk_mul_f32 v[164:165], v[82:83], v[148:149] op_sel_hi:[1,0]
	v_mul_f32_e32 v148, 0xbfb8aa3b, v152
	v_mul_f32_e32 v149, 0xbfb8aa3b, v153
	v_exp_f32_e32 v148, v148
	v_exp_f32_e32 v149, v149
	v_add_f32_e32 v148, 1.0, v148
	v_add_f32_e32 v149, 1.0, v149
	v_rcp_f32_e32 v148, v148
	v_rcp_f32_e32 v149, v149
	v_mul_f32_e32 v148, v152, v148
	v_mul_f32_e32 v149, v153, v149
	v_mul_f32_e32 v148, v156, v148
	v_mul_f32_e32 v149, v157, v149
	v_cvt_pk_bf16_f32 v148, v148, v149
	v_mul_f32_e32 v149, 0xbfb8aa3b, v150
	v_exp_f32_e32 v149, v149
	v_mul_f32_e32 v152, 0xbfb8aa3b, v159
	v_exp_f32_e32 v152, v152
	v_add_f32_e32 v149, 1.0, v149
	v_rcp_f32_e32 v149, v149
	v_add_f32_e32 v152, 1.0, v152
	v_rcp_f32_e32 v152, v152
	v_mul_f32_e32 v149, v150, v149
	v_mul_f32_e32 v150, 0xbfb8aa3b, v151
	v_exp_f32_e32 v150, v150
	v_mul_f32_e32 v149, v154, v149
	v_mul_f32_e32 v152, v159, v152
	v_mul_f32_e32 v152, v163, v152
	v_add_f32_e32 v150, 1.0, v150
	v_rcp_f32_e32 v150, v150
	s_nop 0
	v_mul_f32_e32 v150, v151, v150
	v_mul_f32_e32 v150, v155, v150
	v_cvt_pk_bf16_f32 v149, v149, v150
	v_mul_f32_e32 v150, 0xbfb8aa3b, v160
	v_mul_f32_e32 v151, 0xbfb8aa3b, v161
	v_exp_f32_e32 v150, v150
	v_exp_f32_e32 v151, v151
	v_add_f32_e32 v150, 1.0, v150
	v_add_f32_e32 v151, 1.0, v151
	v_rcp_f32_e32 v150, v150
	v_rcp_f32_e32 v151, v151
	v_mul_f32_e32 v150, v160, v150
	v_mul_f32_e32 v151, v161, v151
	v_mul_f32_e32 v150, v164, v150
	v_mul_f32_e32 v151, v165, v151
	v_cvt_pk_bf16_f32 v150, v150, v151
	v_mul_f32_e32 v151, 0xbfb8aa3b, v158
	v_exp_f32_e32 v151, v151
	s_nop 0
	v_add_f32_e32 v151, 1.0, v151
	v_rcp_f32_e32 v151, v151
	s_nop 0
	v_mul_f32_e32 v151, v158, v151
	v_mul_f32_e32 v151, v162, v151
	v_cvt_pk_bf16_f32 v151, v151, v152
	v_mad_i64_i32 v[152:153], s[4:5], v147, s33, v[136:137]
	v_lshl_add_u64 v[152:153], v[152:153], 0, v[138:139]
	global_store_dwordx4 v[152:153], v[148:151], off
	ds_read_b32 v148, v145 offset:128
	v_or_b32_e32 v147, 32, v146
	s_waitcnt lgkmcnt(0)
; __device__ __forceinline__ unsigned pk2(float lo, float hi) { unsigned r; asm volatile("v_cvt_pk_bf16_f32 %0, %1, %2" : "=v"(r) : "v"(lo), "v"(hi)); return r; }
; __device__ __forceinline__ float siluf_(float x) { return x * __builtin_amdgcn_rcpf(1.0f + __expf(-x)); }
;     template <int mode> __device__ __forceinline__ void run(const f32x4 (&acc)[2][2][4][2], const Unit& u, int wr, int wc, int fr, int fq, const LAS float* sc) const {
;     ...
; #pragma unroll
;             for (int ai = 0; ai < 2; ++ai)
; #pragma unroll
;                 for (int m = 0; m < 4; ++m) {
;                     const int row = row0 + ai * HALF + m * 16;
;                     const float s = sc[ai * HALF + wr * 64 + m * 16 + fr];
;                     const f32x4 g0 = acc[ai][0][m][0] * s, u0 = acc[ai][1][m][0] * s, g1 = acc[ai][0][m][1] * s, u1 = acc[ai][1][m][1] * s;
;                     u32x4 w;
;                     w.x = pk2(siluf_(g0[0]) * u0[0], siluf_(g0[1]) * u0[1]); w.y = pk2(siluf_(g0[2]) * u0[2], siluf_(g0[3]) * u0[3]);
;                     w.z = pk2(siluf_(g1[0]) * u1[0], siluf_(g1[1]) * u1[1]); w.w = pk2(siluf_(g1[2]) * u1[2], siluf_(g1[3]) * u1[3]);
;                     *(u32x4*)(ob + (size_t)row * FF + col0) = w;
	v_pk_mul_f32 v[152:153], v[110:111], v[148:149] op_sel_hi:[1,0]
	v_pk_mul_f32 v[150:151], v[112:113], v[148:149] op_sel_hi:[1,0]
	v_pk_mul_f32 v[154:155], v[80:81], v[148:149] op_sel_hi:[1,0]
	v_pk_mul_f32 v[156:157], v[78:79], v[148:149] op_sel_hi:[1,0]
	v_pk_mul_f32 v[158:159], v[108:109], v[148:149] op_sel_hi:[1,0]
	v_pk_mul_f32 v[160:161], v[106:107], v[148:149] op_sel_hi:[1,0]
	v_pk_mul_f32 v[162:163], v[76:77], v[148:149] op_sel_hi:[1,0]
	v_pk_mul_f32 v[164:165], v[74:75], v[148:149] op_sel_hi:[1,0]
	v_mul_f32_e32 v148, 0xbfb8aa3b, v152
	v_mul_f32_e32 v149, 0xbfb8aa3b, v153
	v_exp_f32_e32 v148, v148
	v_exp_f32_e32 v149, v149
	v_add_f32_e32 v148, 1.0, v148
	v_add_f32_e32 v149, 1.0, v149
	v_rcp_f32_e32 v148, v148
	v_rcp_f32_e32 v149, v149
	v_mul_f32_e32 v148, v152, v148
	v_mul_f32_e32 v149, v153, v149
	v_mul_f32_e32 v148, v156, v148
	v_mul_f32_e32 v149, v157, v149
	v_cvt_pk_bf16_f32 v148, v148, v149
	v_mul_f32_e32 v149, 0xbfb8aa3b, v150
	v_exp_f32_e32 v149, v149
	v_mul_f32_e32 v152, 0xbfb8aa3b, v159
	v_exp_f32_e32 v152, v152
	v_add_f32_e32 v149, 1.0, v149
	v_rcp_f32_e32 v149, v149
	v_add_f32_e32 v152, 1.0, v152
	v_rcp_f32_e32 v152, v152
	v_mul_f32_e32 v149, v150, v149
	v_mul_f32_e32 v150, 0xbfb8aa3b, v151
	v_exp_f32_e32 v150, v150
	v_mul_f32_e32 v149, v154, v149
	v_mul_f32_e32 v152, v159, v152
	v_mul_f32_e32 v152, v163, v152
	v_add_f32_e32 v150, 1.0, v150
	v_rcp_f32_e32 v150, v150
	s_nop 0
	v_mul_f32_e32 v150, v151, v150
	v_mul_f32_e32 v150, v155, v150
	v_cvt_pk_bf16_f32 v149, v149, v150
	v_mul_f32_e32 v150, 0xbfb8aa3b, v160
	v_mul_f32_e32 v151, 0xbfb8aa3b, v161
	v_exp_f32_e32 v150, v150
	v_exp_f32_e32 v151, v151
	v_add_f32_e32 v150, 1.0, v150
	v_add_f32_e32 v151, 1.0, v151
	v_rcp_f32_e32 v150, v150
	v_rcp_f32_e32 v151, v151
	v_mul_f32_e32 v150, v160, v150
	v_mul_f32_e32 v151, v161, v151
	v_mul_f32_e32 v150, v164, v150
	v_mul_f32_e32 v151, v165, v151
	v_cvt_pk_bf16_f32 v150, v150, v151
	v_mul_f32_e32 v151, 0xbfb8aa3b, v158
	v_exp_f32_e32 v151, v151
	s_nop 0
	v_add_f32_e32 v151, 1.0, v151
	v_rcp_f32_e32 v151, v151
	s_nop 0
	v_mul_f32_e32 v151, v158, v151
	v_mul_f32_e32 v151, v162, v151
	v_cvt_pk_bf16_f32 v151, v151, v152
	v_mad_i64_i32 v[152:153], s[4:5], v147, s33, v[136:137]
	v_lshl_add_u64 v[152:153], v[152:153], 0, v[138:139]
	global_store_dwordx4 v[152:153], v[148:151], off
	ds_read_b32 v148, v145 offset:192
	v_or_b32_e32 v147, 48, v146
	s_waitcnt lgkmcnt(0)
	v_pk_mul_f32 v[152:153], v[102:103], v[148:149] op_sel_hi:[1,0]
	v_pk_mul_f32 v[150:151], v[104:105], v[148:149] op_sel_hi:[1,0]
	v_pk_mul_f32 v[154:155], v[72:73], v[148:149] op_sel_hi:[1,0]
	v_pk_mul_f32 v[156:157], v[70:71], v[148:149] op_sel_hi:[1,0]
	v_pk_mul_f32 v[158:159], v[100:101], v[148:149] op_sel_hi:[1,0]
	v_pk_mul_f32 v[160:161], v[98:99], v[148:149] op_sel_hi:[1,0]
	v_pk_mul_f32 v[162:163], v[68:69], v[148:149] op_sel_hi:[1,0]
	v_pk_mul_f32 v[164:165], v[66:67], v[148:149] op_sel_hi:[1,0]
	v_mul_f32_e32 v148, 0xbfb8aa3b, v152
	v_mul_f32_e32 v149, 0xbfb8aa3b, v153
	v_exp_f32_e32 v148, v148
	v_exp_f32_e32 v149, v149
	v_add_f32_e32 v148, 1.0, v148
	v_add_f32_e32 v149, 1.0, v149
	v_rcp_f32_e32 v148, v148
	v_rcp_f32_e32 v149, v149
	v_mul_f32_e32 v148, v152, v148
	v_mul_f32_e32 v149, v153, v149
	v_mul_f32_e32 v148, v156, v148
	v_mul_f32_e32 v149, v157, v149
	v_cvt_pk_bf16_f32 v148, v148, v149
	v_mul_f32_e32 v149, 0xbfb8aa3b, v150
	v_exp_f32_e32 v149, v149
	v_mul_f32_e32 v152, 0xbfb8aa3b, v159
	v_exp_f32_e32 v152, v152
	v_add_f32_e32 v149, 1.0, v149
	v_rcp_f32_e32 v149, v149
	v_add_f32_e32 v152, 1.0, v152
	v_rcp_f32_e32 v152, v152
	v_mul_f32_e32 v149, v150, v149
	v_mul_f32_e32 v150, 0xbfb8aa3b, v151
	v_exp_f32_e32 v150, v150
	v_mul_f32_e32 v149, v154, v149
	v_mul_f32_e32 v152, v159, v152
	v_mul_f32_e32 v152, v163, v152
	v_add_f32_e32 v150, 1.0, v150
	v_rcp_f32_e32 v150, v150
	s_nop 0
	v_mul_f32_e32 v150, v151, v150
	v_mul_f32_e32 v150, v155, v150
	v_cvt_pk_bf16_f32 v149, v149, v150
	v_mul_f32_e32 v150, 0xbfb8aa3b, v160
	v_mul_f32_e32 v151, 0xbfb8aa3b, v161
	v_exp_f32_e32 v150, v150
	v_exp_f32_e32 v151, v151
	v_add_f32_e32 v150, 1.0, v150
	v_add_f32_e32 v151, 1.0, v151
	v_rcp_f32_e32 v150, v150
	v_rcp_f32_e32 v151, v151
	v_mul_f32_e32 v150, v160, v150
	v_mul_f32_e32 v151, v161, v151
	v_mul_f32_e32 v150, v164, v150
	v_mul_f32_e32 v151, v165, v151
	v_cvt_pk_bf16_f32 v150, v150, v151
	v_mul_f32_e32 v151, 0xbfb8aa3b, v158
	v_exp_f32_e32 v151, v151
	s_nop 0
	v_add_f32_e32 v151, 1.0, v151
	v_rcp_f32_e32 v151, v151
	s_nop 0
	v_mul_f32_e32 v151, v158, v151
	v_mul_f32_e32 v151, v162, v151
	v_cvt_pk_bf16_f32 v151, v151, v152
	v_mad_i64_i32 v[152:153], s[4:5], v147, s33, v[136:137]
	v_lshl_add_u64 v[152:153], v[152:153], 0, v[138:139]
	global_store_dwordx4 v[152:153], v[148:151], off
	ds_read_b32 v148, v145 offset:512
	v_add_u32_e32 v147, 0x80, v146
	s_waitcnt lgkmcnt(0)
; __device__ __forceinline__ unsigned pk2(float lo, float hi) { unsigned r; asm volatile("v_cvt_pk_bf16_f32 %0, %1, %2" : "=v"(r) : "v"(lo), "v"(hi)); return r; }
; __device__ __forceinline__ float siluf_(float x) { return x * __builtin_amdgcn_rcpf(1.0f + __expf(-x)); }
;     template <int mode> __device__ __forceinline__ void run(const f32x4 (&acc)[2][2][4][2], const Unit& u, int wr, int wc, int fr, int fq, const LAS float* sc) const {
;     ...
; #pragma unroll
;             for (int ai = 0; ai < 2; ++ai)
; #pragma unroll
;                 for (int m = 0; m < 4; ++m) {
;                     const int row = row0 + ai * HALF + m * 16;
;                     const float s = sc[ai * HALF + wr * 64 + m * 16 + fr];
;                     const f32x4 g0 = acc[ai][0][m][0] * s, u0 = acc[ai][1][m][0] * s, g1 = acc[ai][0][m][1] * s, u1 = acc[ai][1][m][1] * s;
;                     u32x4 w;
;                     w.x = pk2(siluf_(g0[0]) * u0[0], siluf_(g0[1]) * u0[1]); w.y = pk2(siluf_(g0[2]) * u0[2], siluf_(g0[3]) * u0[3]);
;                     w.z = pk2(siluf_(g1[0]) * u1[0], siluf_(g1[1]) * u1[1]); w.w = pk2(siluf_(g1[2]) * u1[2], siluf_(g1[3]) * u1[3]);
;                     *(u32x4*)(ob + (size_t)row * FF + col0) = w;
	v_pk_mul_f32 v[152:153], v[62:63], v[148:149] op_sel_hi:[1,0]
	v_pk_mul_f32 v[150:151], v[64:65], v[148:149] op_sel_hi:[1,0]
	v_pk_mul_f32 v[154:155], v[32:33], v[148:149] op_sel_hi:[1,0]
	v_pk_mul_f32 v[156:157], v[30:31], v[148:149] op_sel_hi:[1,0]
	v_pk_mul_f32 v[158:159], v[60:61], v[148:149] op_sel_hi:[1,0]
	v_pk_mul_f32 v[160:161], v[58:59], v[148:149] op_sel_hi:[1,0]
	v_pk_mul_f32 v[162:163], v[28:29], v[148:149] op_sel_hi:[1,0]
	v_pk_mul_f32 v[164:165], v[26:27], v[148:149] op_sel_hi:[1,0]
	v_mul_f32_e32 v148, 0xbfb8aa3b, v152
	v_mul_f32_e32 v149, 0xbfb8aa3b, v153
	v_exp_f32_e32 v148, v148
	v_exp_f32_e32 v149, v149
	v_add_f32_e32 v148, 1.0, v148
	v_add_f32_e32 v149, 1.0, v149
	v_rcp_f32_e32 v148, v148
	v_rcp_f32_e32 v149, v149
	v_mul_f32_e32 v148, v152, v148
	v_mul_f32_e32 v149, v153, v149
	v_mul_f32_e32 v148, v156, v148
	v_mul_f32_e32 v149, v157, v149
	v_cvt_pk_bf16_f32 v148, v148, v149
	v_mul_f32_e32 v149, 0xbfb8aa3b, v150
	v_exp_f32_e32 v149, v149
	v_mul_f32_e32 v152, 0xbfb8aa3b, v159
	v_exp_f32_e32 v152, v152
	v_add_f32_e32 v149, 1.0, v149
	v_rcp_f32_e32 v149, v149
	v_add_f32_e32 v152, 1.0, v152
	v_rcp_f32_e32 v152, v152
	v_mul_f32_e32 v149, v150, v149
	v_mul_f32_e32 v150, 0xbfb8aa3b, v151
	v_exp_f32_e32 v150, v150
	v_mul_f32_e32 v149, v154, v149
	v_mul_f32_e32 v152, v159, v152
	v_mul_f32_e32 v152, v163, v152
	v_add_f32_e32 v150, 1.0, v150
	v_rcp_f32_e32 v150, v150
	s_nop 0
	v_mul_f32_e32 v150, v151, v150
	v_mul_f32_e32 v150, v155, v150
	v_cvt_pk_bf16_f32 v149, v149, v150
	v_mul_f32_e32 v150, 0xbfb8aa3b, v160
	v_mul_f32_e32 v151, 0xbfb8aa3b, v161
	v_exp_f32_e32 v150, v150
	v_exp_f32_e32 v151, v151
	v_add_f32_e32 v150, 1.0, v150
	v_add_f32_e32 v151, 1.0, v151
	v_rcp_f32_e32 v150, v150
	v_rcp_f32_e32 v151, v151
	v_mul_f32_e32 v150, v160, v150
	v_mul_f32_e32 v151, v161, v151
	v_mul_f32_e32 v150, v164, v150
	v_mul_f32_e32 v151, v165, v151
	v_cvt_pk_bf16_f32 v150, v150, v151
	v_mul_f32_e32 v151, 0xbfb8aa3b, v158
	v_exp_f32_e32 v151, v151
	s_nop 0
	v_add_f32_e32 v151, 1.0, v151
	v_rcp_f32_e32 v151, v151
	s_nop 0
	v_mul_f32_e32 v151, v158, v151
	v_mul_f32_e32 v151, v162, v151
	v_cvt_pk_bf16_f32 v151, v151, v152
	v_mad_i64_i32 v[152:153], s[4:5], v147, s33, v[136:137]
	v_lshl_add_u64 v[152:153], v[152:153], 0, v[138:139]
	global_store_dwordx4 v[152:153], v[148:151], off
	ds_read_b32 v148, v145 offset:576
	v_add_u32_e32 v147, 0x90, v146
	s_waitcnt lgkmcnt(0)
	v_pk_mul_f32 v[152:153], v[54:55], v[148:149] op_sel_hi:[1,0]
	v_pk_mul_f32 v[150:151], v[56:57], v[148:149] op_sel_hi:[1,0]
	v_pk_mul_f32 v[154:155], v[24:25], v[148:149] op_sel_hi:[1,0]
	v_pk_mul_f32 v[156:157], v[22:23], v[148:149] op_sel_hi:[1,0]
	v_pk_mul_f32 v[158:159], v[52:53], v[148:149] op_sel_hi:[1,0]
	v_pk_mul_f32 v[160:161], v[50:51], v[148:149] op_sel_hi:[1,0]
	v_pk_mul_f32 v[162:163], v[20:21], v[148:149] op_sel_hi:[1,0]
	v_pk_mul_f32 v[164:165], v[18:19], v[148:149] op_sel_hi:[1,0]
	v_mul_f32_e32 v148, 0xbfb8aa3b, v152
	v_mul_f32_e32 v149, 0xbfb8aa3b, v153
	v_exp_f32_e32 v148, v148
	v_exp_f32_e32 v149, v149
	v_add_f32_e32 v148, 1.0, v148
	v_add_f32_e32 v149, 1.0, v149
	v_rcp_f32_e32 v148, v148
	v_rcp_f32_e32 v149, v149
	v_mul_f32_e32 v148, v152, v148
	v_mul_f32_e32 v149, v153, v149
	v_mul_f32_e32 v148, v156, v148
	v_mul_f32_e32 v149, v157, v149
	v_cvt_pk_bf16_f32 v148, v148, v149
	v_mul_f32_e32 v149, 0xbfb8aa3b, v150
	v_exp_f32_e32 v149, v149
	v_mul_f32_e32 v152, 0xbfb8aa3b, v159
	v_exp_f32_e32 v152, v152
	v_add_f32_e32 v149, 1.0, v149
	v_rcp_f32_e32 v149, v149
	v_add_f32_e32 v152, 1.0, v152
	v_rcp_f32_e32 v152, v152
	v_mul_f32_e32 v149, v150, v149
	v_mul_f32_e32 v150, 0xbfb8aa3b, v151
	v_exp_f32_e32 v150, v150
	v_mul_f32_e32 v149, v154, v149
	v_mul_f32_e32 v152, v159, v152
	v_mul_f32_e32 v152, v163, v152
	v_add_f32_e32 v150, 1.0, v150
	v_rcp_f32_e32 v150, v150
	s_nop 0
	v_mul_f32_e32 v150, v151, v150
	v_mul_f32_e32 v150, v155, v150
	v_cvt_pk_bf16_f32 v149, v149, v150
	v_mul_f32_e32 v150, 0xbfb8aa3b, v160
	v_mul_f32_e32 v151, 0xbfb8aa3b, v161
	v_exp_f32_e32 v150, v150
	v_exp_f32_e32 v151, v151
	v_add_f32_e32 v150, 1.0, v150
	v_add_f32_e32 v151, 1.0, v151
	v_rcp_f32_e32 v150, v150
	v_rcp_f32_e32 v151, v151
	v_mul_f32_e32 v150, v160, v150
	v_mul_f32_e32 v151, v161, v151
	v_mul_f32_e32 v150, v164, v150
	v_mul_f32_e32 v151, v165, v151
	v_cvt_pk_bf16_f32 v150, v150, v151
	v_mul_f32_e32 v151, 0xbfb8aa3b, v158
	v_exp_f32_e32 v151, v151
	s_nop 0
	v_add_f32_e32 v151, 1.0, v151
	v_rcp_f32_e32 v151, v151
	s_nop 0
	v_mul_f32_e32 v151, v158, v151
	v_mul_f32_e32 v151, v162, v151
	v_cvt_pk_bf16_f32 v151, v151, v152
	v_mad_i64_i32 v[152:153], s[4:5], v147, s33, v[136:137]
	v_lshl_add_u64 v[152:153], v[152:153], 0, v[138:139]
	global_store_dwordx4 v[152:153], v[148:151], off
	ds_read_b32 v148, v145 offset:640
	v_add_u32_e32 v147, 0xa0, v146
	s_waitcnt lgkmcnt(0)
; __device__ __forceinline__ unsigned pk2(float lo, float hi) { unsigned r; asm volatile("v_cvt_pk_bf16_f32 %0, %1, %2" : "=v"(r) : "v"(lo), "v"(hi)); return r; }
; __device__ __forceinline__ float siluf_(float x) { return x * __builtin_amdgcn_rcpf(1.0f + __expf(-x)); }
;     template <int mode> __device__ __forceinline__ void run(const f32x4 (&acc)[2][2][4][2], const Unit& u, int wr, int wc, int fr, int fq, const LAS float* sc) const {
;     ...
; #pragma unroll
;             for (int ai = 0; ai < 2; ++ai)
; #pragma unroll
;                 for (int m = 0; m < 4; ++m) {
;                     const int row = row0 + ai * HALF + m * 16;
;                     const float s = sc[ai * HALF + wr * 64 + m * 16 + fr];
;                     const f32x4 g0 = acc[ai][0][m][0] * s, u0 = acc[ai][1][m][0] * s, g1 = acc[ai][0][m][1] * s, u1 = acc[ai][1][m][1] * s;
;                     u32x4 w;
;                     w.x = pk2(siluf_(g0[0]) * u0[0], siluf_(g0[1]) * u0[1]); w.y = pk2(siluf_(g0[2]) * u0[2], siluf_(g0[3]) * u0[3]);
;                     w.z = pk2(siluf_(g1[0]) * u1[0], siluf_(g1[1]) * u1[1]); w.w = pk2(siluf_(g1[2]) * u1[2], siluf_(g1[3]) * u1[3]);
;                     *(u32x4*)(ob + (size_t)row * FF + col0) = w;
	v_pk_mul_f32 v[152:153], v[46:47], v[148:149] op_sel_hi:[1,0]
	v_pk_mul_f32 v[150:151], v[48:49], v[148:149] op_sel_hi:[1,0]
	v_pk_mul_f32 v[154:155], v[16:17], v[148:149] op_sel_hi:[1,0]
	v_pk_mul_f32 v[156:157], v[14:15], v[148:149] op_sel_hi:[1,0]
	v_pk_mul_f32 v[158:159], v[44:45], v[148:149] op_sel_hi:[1,0]
	v_pk_mul_f32 v[160:161], v[42:43], v[148:149] op_sel_hi:[1,0]
	v_pk_mul_f32 v[162:163], v[12:13], v[148:149] op_sel_hi:[1,0]
	v_pk_mul_f32 v[164:165], v[10:11], v[148:149] op_sel_hi:[1,0]
	v_mul_f32_e32 v148, 0xbfb8aa3b, v152
	v_mul_f32_e32 v149, 0xbfb8aa3b, v153
	v_exp_f32_e32 v148, v148
	v_exp_f32_e32 v149, v149
	v_add_f32_e32 v148, 1.0, v148
	v_add_f32_e32 v149, 1.0, v149
	v_rcp_f32_e32 v148, v148
	v_rcp_f32_e32 v149, v149
	v_mul_f32_e32 v148, v152, v148
	v_mul_f32_e32 v149, v153, v149
	v_mul_f32_e32 v148, v156, v148
	v_mul_f32_e32 v149, v157, v149
	v_cvt_pk_bf16_f32 v148, v148, v149
	v_mul_f32_e32 v149, 0xbfb8aa3b, v150
	v_exp_f32_e32 v149, v149
	v_mul_f32_e32 v152, 0xbfb8aa3b, v159
	v_exp_f32_e32 v152, v152
	v_add_f32_e32 v149, 1.0, v149
	v_rcp_f32_e32 v149, v149
	v_add_f32_e32 v152, 1.0, v152
	v_rcp_f32_e32 v152, v152
	v_mul_f32_e32 v149, v150, v149
	v_mul_f32_e32 v150, 0xbfb8aa3b, v151
	v_exp_f32_e32 v150, v150
	v_mul_f32_e32 v149, v154, v149
	v_mul_f32_e32 v152, v159, v152
	v_mul_f32_e32 v152, v163, v152
	v_add_f32_e32 v150, 1.0, v150
	v_rcp_f32_e32 v150, v150
	s_nop 0
	v_mul_f32_e32 v150, v151, v150
	v_mul_f32_e32 v150, v155, v150
	v_cvt_pk_bf16_f32 v149, v149, v150
	v_mul_f32_e32 v150, 0xbfb8aa3b, v160
	v_mul_f32_e32 v151, 0xbfb8aa3b, v161
	v_exp_f32_e32 v150, v150
	v_exp_f32_e32 v151, v151
	v_add_f32_e32 v150, 1.0, v150
	v_add_f32_e32 v151, 1.0, v151
	v_rcp_f32_e32 v150, v150
	v_rcp_f32_e32 v151, v151
	v_mul_f32_e32 v150, v160, v150
	v_mul_f32_e32 v151, v161, v151
	v_mul_f32_e32 v150, v164, v150
	v_mul_f32_e32 v151, v165, v151
	v_cvt_pk_bf16_f32 v150, v150, v151
	v_mul_f32_e32 v151, 0xbfb8aa3b, v158
	v_exp_f32_e32 v151, v151
	v_add_u32_e32 v164, 0xb0, v146
	v_add_f32_e32 v151, 1.0, v151
	v_rcp_f32_e32 v151, v151
	s_nop 0
	v_mul_f32_e32 v151, v158, v151
	v_mul_f32_e32 v151, v162, v151
	v_cvt_pk_bf16_f32 v151, v151, v152
	ds_read_b32 v146, v145 offset:704
	v_mad_i64_i32 v[152:153], s[4:5], v147, s33, v[136:137]
	v_lshl_add_u64 v[152:153], v[152:153], 0, v[138:139]
	global_store_dwordx4 v[152:153], v[148:151], off
	s_waitcnt lgkmcnt(0)
	v_pk_mul_f32 v[152:153], v[8:9], v[146:147] op_sel_hi:[1,0]
	v_pk_mul_f32 v[154:155], v[6:7], v[146:147] op_sel_hi:[1,0]
	v_pk_mul_f32 v[150:151], v[38:39], v[146:147] op_sel_hi:[1,0]
	v_pk_mul_f32 v[148:149], v[40:41], v[146:147] op_sel_hi:[1,0]
	v_pk_mul_f32 v[156:157], v[36:37], v[146:147] op_sel_hi:[1,0]
	v_pk_mul_f32 v[158:159], v[34:35], v[146:147] op_sel_hi:[1,0]
	v_pk_mul_f32 v[160:161], v[4:5], v[146:147] op_sel_hi:[1,0]
	v_pk_mul_f32 v[162:163], v[2:3], v[146:147] op_sel_hi:[1,0]
	v_mul_f32_e32 v145, 0xbfb8aa3b, v150
	v_mul_f32_e32 v146, 0xbfb8aa3b, v151
	v_exp_f32_e32 v145, v145
	v_exp_f32_e32 v146, v146
	v_mul_f32_e32 v147, 0xbfb8aa3b, v149
	v_exp_f32_e32 v147, v147
	v_add_f32_e32 v145, 1.0, v145
	v_add_f32_e32 v146, 1.0, v146
	v_rcp_f32_e32 v145, v145
	v_rcp_f32_e32 v146, v146
	v_add_f32_e32 v147, 1.0, v147
	v_rcp_f32_e32 v147, v147
	v_mul_f32_e32 v145, v150, v145
	v_mul_f32_e32 v146, v151, v146
	v_mul_f32_e32 v145, v154, v145
	v_mul_f32_e32 v146, v155, v146
	v_cvt_pk_bf16_f32 v146, v145, v146
	v_mul_f32_e32 v145, 0xbfb8aa3b, v148
	v_exp_f32_e32 v145, v145
	v_mul_f32_e32 v147, v149, v147
	v_mul_f32_e32 v147, v153, v147
	v_mul_f32_e32 v149, 0xbfb8aa3b, v157
	v_add_f32_e32 v145, 1.0, v145
	v_rcp_f32_e32 v145, v145
	v_exp_f32_e32 v149, v149
	v_mad_i64_i32 v[136:137], s[4:5], v164, s33, v[136:137]
	v_mul_f32_e32 v145, v148, v145
	v_mul_f32_e32 v145, v152, v145
	v_cvt_pk_bf16_f32 v147, v145, v147
	v_mul_f32_e32 v145, 0xbfb8aa3b, v158
	v_mul_f32_e32 v148, 0xbfb8aa3b, v159
	v_exp_f32_e32 v145, v145
	v_exp_f32_e32 v148, v148
	v_add_f32_e32 v149, 1.0, v149
	v_rcp_f32_e32 v149, v149
	v_add_f32_e32 v145, 1.0, v145
	v_add_f32_e32 v148, 1.0, v148
	v_rcp_f32_e32 v145, v145
	v_rcp_f32_e32 v148, v148
	v_mul_f32_e32 v149, v157, v149
	v_mul_f32_e32 v149, v161, v149
	v_mul_f32_e32 v145, v158, v145
	v_mul_f32_e32 v148, v159, v148
	v_mul_f32_e32 v145, v162, v145
	v_mul_f32_e32 v148, v163, v148
	v_cvt_pk_bf16_f32 v148, v145, v148
	v_mul_f32_e32 v145, 0xbfb8aa3b, v156
	v_exp_f32_e32 v145, v145
	v_lshl_add_u64 v[136:137], v[136:137], 0, v[138:139]
	v_add_f32_e32 v145, 1.0, v145
	v_rcp_f32_e32 v145, v145
	s_nop 0
	v_mul_f32_e32 v145, v156, v145
	v_mul_f32_e32 v145, v160, v145
	v_cvt_pk_bf16_f32 v149, v145, v149
	global_store_dwordx4 v[136:137], v[146:149], off
	s_cbranch_vccnz .LBB0_324
; template <int MODE, class EpiT, class Sched>
; __device__ __forceinline__ void gemm_phase(LAS unsigned char* lds, const Gemm g, const Sched& S, const EpiT& E) {
;     ...
; #pragma unroll
;         for (int a = 0; a < 2; ++a)
; #pragma unroll
;             for (int b = 0; b < 2; ++b)
; #pragma unroll
;                 for (int m = 0; m < 4; ++m)
; #pragma unroll
;                     for (int n = 0; n < 2; ++n) acc[a][b][m][n] = (f32x4){0.f, 0.f, 0.f, 0.f};
;         cur = nxt; cA = nA; cB = nB; ++ui;
	v_mov_b32_e32 v2, 0
	s_mov_b32 s9, s61
	s_mov_b32 s8, s60
	s_mov_b64 s[12:13], s[28:29]
	s_mov_b64 s[10:11], s[34:35]
	s_mov_b32 s57, s2
	v_mov_b32_e32 v3, v2
	v_mov_b32_e32 v4, v2
	v_mov_b32_e32 v5, v2
	v_mov_b32_e32 v6, v2
	v_mov_b32_e32 v7, v2
	v_mov_b32_e32 v8, v2
	v_mov_b32_e32 v9, v2
	v_mov_b32_e32 v10, v2
	v_mov_b32_e32 v11, v2
	v_mov_b32_e32 v12, v2
	v_mov_b32_e32 v13, v2
	v_mov_b32_e32 v14, v2
	v_mov_b32_e32 v15, v2
	v_mov_b32_e32 v16, v2
	v_mov_b32_e32 v17, v2
	v_mov_b32_e32 v18, v2
	v_mov_b32_e32 v19, v2
	v_mov_b32_e32 v20, v2
	v_mov_b32_e32 v21, v2
	v_mov_b32_e32 v22, v2
	v_mov_b32_e32 v23, v2
	v_mov_b32_e32 v24, v2
	v_mov_b32_e32 v25, v2
	v_mov_b32_e32 v26, v2
	v_mov_b32_e32 v27, v2
	v_mov_b32_e32 v28, v2
	v_mov_b32_e32 v29, v2
	v_mov_b32_e32 v30, v2
	v_mov_b32_e32 v31, v2
	v_mov_b32_e32 v32, v2
	v_mov_b32_e32 v33, v2
	v_mov_b32_e32 v34, v2
	v_mov_b32_e32 v35, v2
	v_mov_b32_e32 v36, v2
	v_mov_b32_e32 v37, v2
	v_mov_b32_e32 v38, v2
	v_mov_b32_e32 v39, v2
	v_mov_b32_e32 v40, v2
	v_mov_b32_e32 v41, v2
	v_mov_b32_e32 v42, v2
	v_mov_b32_e32 v43, v2
	v_mov_b32_e32 v44, v2
	v_mov_b32_e32 v45, v2
	v_mov_b32_e32 v46, v2
	v_mov_b32_e32 v47, v2
	v_mov_b32_e32 v48, v2
	v_mov_b32_e32 v49, v2
	v_mov_b32_e32 v50, v2
	v_mov_b32_e32 v51, v2
	v_mov_b32_e32 v52, v2
	v_mov_b32_e32 v53, v2
	v_mov_b32_e32 v54, v2
	v_mov_b32_e32 v55, v2
	v_mov_b32_e32 v56, v2
	v_mov_b32_e32 v57, v2
	v_mov_b32_e32 v58, v2
	v_mov_b32_e32 v59, v2
	v_mov_b32_e32 v60, v2
	v_mov_b32_e32 v61, v2
	v_mov_b32_e32 v62, v2
	v_mov_b32_e32 v63, v2
	v_mov_b32_e32 v64, v2
	v_mov_b32_e32 v65, v2
	v_mov_b32_e32 v66, v2
	v_mov_b32_e32 v67, v2
	v_mov_b32_e32 v68, v2
	v_mov_b32_e32 v69, v2
	v_mov_b32_e32 v70, v2
	v_mov_b32_e32 v71, v2
	v_mov_b32_e32 v72, v2
	v_mov_b32_e32 v73, v2
	v_mov_b32_e32 v74, v2
	v_mov_b32_e32 v75, v2
	v_mov_b32_e32 v76, v2
	v_mov_b32_e32 v77, v2
	v_mov_b32_e32 v78, v2
	v_mov_b32_e32 v79, v2
	v_mov_b32_e32 v80, v2
	v_mov_b32_e32 v81, v2
	v_mov_b32_e32 v82, v2
	v_mov_b32_e32 v83, v2
	v_mov_b32_e32 v84, v2
	v_mov_b32_e32 v85, v2
	v_mov_b32_e32 v86, v2
	v_mov_b32_e32 v87, v2
	v_mov_b32_e32 v88, v2
	v_mov_b32_e32 v89, v2
	v_mov_b32_e32 v90, v2
	v_mov_b32_e32 v91, v2
	v_mov_b32_e32 v92, v2
	v_mov_b32_e32 v93, v2
	v_mov_b32_e32 v94, v2
	v_mov_b32_e32 v95, v2
	v_mov_b32_e32 v96, v2
	v_mov_b32_e32 v97, v2
	v_mov_b32_e32 v98, v2
	v_mov_b32_e32 v99, v2
	v_mov_b32_e32 v100, v2
	v_mov_b32_e32 v101, v2
	v_mov_b32_e32 v102, v2
	v_mov_b32_e32 v103, v2
	v_mov_b32_e32 v104, v2
	v_mov_b32_e32 v105, v2
	v_mov_b32_e32 v106, v2
	v_mov_b32_e32 v107, v2
	v_mov_b32_e32 v108, v2
	v_mov_b32_e32 v109, v2
	v_mov_b32_e32 v110, v2
	v_mov_b32_e32 v111, v2
	v_mov_b32_e32 v112, v2
	v_mov_b32_e32 v113, v2
	v_mov_b32_e32 v114, v2
	v_mov_b32_e32 v115, v2
	v_mov_b32_e32 v116, v2
	v_mov_b32_e32 v117, v2
	v_mov_b32_e32 v118, v2
	v_mov_b32_e32 v119, v2
	v_mov_b32_e32 v120, v2
	v_mov_b32_e32 v121, v2
	v_mov_b32_e32 v122, v2
	v_mov_b32_e32 v123, v2
	v_mov_b32_e32 v124, v2
	v_mov_b32_e32 v125, v2
	v_mov_b32_e32 v126, v2
	v_mov_b32_e32 v127, v2
	v_mov_b32_e32 v128, v2
	v_mov_b32_e32 v129, v2
	s_branch .LBB0_324
